# on top of the static-priority version: 42 compiler lgkmcnt(0) waits that directly repeat an identical inline-asm wait removed from the GEMM loops
# speedup vs baseline: 1.0057x; 1.0057x over previous
.LBB0_191:
	s_add_u32 s36, s44, 0xfffc0080
	s_addc_u32 s37, s45, -1
	s_add_i32 s38, 0, 0x10000
	v_add_u32_e32 v152, s38, v142
	ds_read_b128 v[138:141], v152
	ds_read_b128 v[144:147], v152 offset:1024
	ds_read_b128 v[148:151], v152 offset:2048
	ds_read_b128 v[152:155], v152 offset:3072
	s_cmp_eq_u32 s61, 12
	s_cselect_b32 s49, s13, s37
	s_cselect_b32 s48, s34, s36
	s_cselect_b32 s47, s9, s60
	s_cselect_b32 s46, s35, s59
	v_lshl_add_u64 v[172:173], s[44:45], 0, v[134:135]
	s_add_i32 m0, s30, 0xc000
	ds_read_b128 v[156:159], v143
	ds_read_b128 v[160:163], v143 offset:1024
	ds_read_b128 v[164:167], v143 offset:2048
	ds_read_b128 v[180:183], v143 offset:3072
	ds_read_b128 v[184:187], v143 offset:4096
	ds_read_b128 v[188:191], v143 offset:5120
	ds_read_b128 v[192:195], v143 offset:6144
	ds_read_b128 v[196:199], v143 offset:7168
	global_load_lds_dwordx4 v[172:173], off
	v_lshl_add_u64 v[172:173], s[44:45], 0, v[136:137]
	s_add_i32 m0, s30, 0xe000
	s_nop 0
	global_load_lds_dwordx4 v[172:173], off
	s_waitcnt lgkmcnt(8)
	s_barrier
	s_waitcnt lgkmcnt(0)
	v_mfma_f32_16x16x32_bf16 v[124:127], v[138:141], v[156:159], v[124:127]
	v_mfma_f32_16x16x32_bf16 v[116:119], v[148:151], v[156:159], v[116:119]
	v_mfma_f32_16x16x32_bf16 v[108:111], v[138:141], v[164:167], v[108:111]
	v_mfma_f32_16x16x32_bf16 v[100:103], v[148:151], v[164:167], v[100:103]
	v_mfma_f32_16x16x32_bf16 v[92:95], v[138:141], v[184:187], v[92:95]
	v_mfma_f32_16x16x32_bf16 v[84:87], v[148:151], v[184:187], v[84:87]
	v_mfma_f32_16x16x32_bf16 v[76:79], v[138:141], v[192:195], v[76:79]
	v_mfma_f32_16x16x32_bf16 v[68:71], v[148:151], v[192:195], v[68:71]
	v_mfma_f32_16x16x32_bf16 v[124:127], v[144:147], v[160:163], v[124:127]
	v_mfma_f32_16x16x32_bf16 v[116:119], v[152:155], v[160:163], v[116:119]
	v_mfma_f32_16x16x32_bf16 v[108:111], v[144:147], v[180:183], v[108:111]
	v_mfma_f32_16x16x32_bf16 v[100:103], v[152:155], v[180:183], v[100:103]
	v_mfma_f32_16x16x32_bf16 v[92:95], v[144:147], v[188:191], v[92:95]
	v_mfma_f32_16x16x32_bf16 v[84:87], v[152:155], v[188:191], v[84:87]
	v_mfma_f32_16x16x32_bf16 v[76:79], v[144:147], v[196:199], v[76:79]
	v_mfma_f32_16x16x32_bf16 v[68:71], v[152:155], v[196:199], v[68:71]
	s_barrier
	s_add_i32 s39, 0, 0x14000
	v_add_u32_e32 v172, s39, v142
	s_add_i32 s36, s38, s29
	ds_read_b128 v[200:203], v172
	ds_read_b128 v[204:207], v172 offset:1024
	ds_read_b128 v[208:211], v172 offset:2048
	ds_read_b128 v[212:215], v172 offset:3072
	v_lshl_add_u64 v[172:173], s[46:47], 0, v[168:169]
	s_mov_b32 m0, s36
	v_lshl_add_u64 v[174:175], s[46:47], 0, v[128:129]
	global_load_lds_dwordx4 v[172:173], off
	s_add_i32 m0, s36, 0x2000
	s_nop 0
	global_load_lds_dwordx4 v[174:175], off
	s_barrier
	s_waitcnt lgkmcnt(0)
	v_mfma_f32_16x16x32_bf16 v[120:123], v[200:203], v[156:159], v[120:123]
	v_mfma_f32_16x16x32_bf16 v[112:115], v[208:211], v[156:159], v[112:115]
	v_mfma_f32_16x16x32_bf16 v[104:107], v[200:203], v[164:167], v[104:107]
	v_mfma_f32_16x16x32_bf16 v[96:99], v[208:211], v[164:167], v[96:99]
	v_mfma_f32_16x16x32_bf16 v[88:91], v[200:203], v[184:187], v[88:91]
	v_mfma_f32_16x16x32_bf16 v[80:83], v[208:211], v[184:187], v[80:83]
	v_mfma_f32_16x16x32_bf16 v[72:75], v[200:203], v[192:195], v[72:75]
	v_mfma_f32_16x16x32_bf16 v[64:67], v[208:211], v[192:195], v[64:67]
	v_mfma_f32_16x16x32_bf16 v[120:123], v[204:207], v[160:163], v[120:123]
	v_mfma_f32_16x16x32_bf16 v[112:115], v[212:215], v[160:163], v[112:115]
	v_mfma_f32_16x16x32_bf16 v[104:107], v[204:207], v[180:183], v[104:107]
	v_mfma_f32_16x16x32_bf16 v[96:99], v[212:215], v[180:183], v[96:99]
	v_mfma_f32_16x16x32_bf16 v[88:91], v[204:207], v[188:191], v[88:91]
	v_mfma_f32_16x16x32_bf16 v[80:83], v[212:215], v[188:191], v[80:83]
	v_mfma_f32_16x16x32_bf16 v[72:75], v[204:207], v[196:199], v[72:75]
	v_mfma_f32_16x16x32_bf16 v[64:67], v[212:215], v[196:199], v[64:67]
	s_mov_b32 m0, s30
	v_lshl_add_u64 v[176:177], s[48:49], 0, v[132:133]
	s_barrier
	ds_read_b128 v[156:159], v143 offset:16384
	ds_read_b128 v[160:163], v143 offset:17408
	ds_read_b128 v[164:167], v143 offset:18432
	ds_read_b128 v[180:183], v143 offset:19456
	ds_read_b128 v[184:187], v143 offset:20480
	ds_read_b128 v[188:191], v143 offset:21504
	ds_read_b128 v[192:195], v143 offset:22528
	ds_read_b128 v[196:199], v143 offset:23552
	global_load_lds_dwordx4 v[176:177], off
	v_lshl_add_u64 v[178:179], s[48:49], 0, v[130:131]
	s_mov_b32 m0, s31
	s_nop 0
	global_load_lds_dwordx4 v[178:179], off
	s_barrier
	s_waitcnt lgkmcnt(0)
	v_mfma_f32_16x16x32_bf16 v[60:63], v[138:141], v[156:159], v[60:63]
	v_mfma_f32_16x16x32_bf16 v[52:55], v[148:151], v[156:159], v[52:55]
	v_mfma_f32_16x16x32_bf16 v[44:47], v[138:141], v[164:167], v[44:47]
	v_mfma_f32_16x16x32_bf16 v[36:39], v[148:151], v[164:167], v[36:39]
	v_mfma_f32_16x16x32_bf16 v[28:31], v[138:141], v[184:187], v[28:31]
	v_mfma_f32_16x16x32_bf16 v[20:23], v[148:151], v[184:187], v[20:23]
	v_mfma_f32_16x16x32_bf16 v[12:15], v[138:141], v[192:195], v[12:15]
	v_mfma_f32_16x16x32_bf16 v[4:7], v[148:151], v[192:195], v[4:7]
	v_mfma_f32_16x16x32_bf16 v[60:63], v[144:147], v[160:163], v[60:63]
	v_mfma_f32_16x16x32_bf16 v[52:55], v[152:155], v[160:163], v[52:55]
	v_mfma_f32_16x16x32_bf16 v[44:47], v[144:147], v[180:183], v[44:47]
	v_mfma_f32_16x16x32_bf16 v[36:39], v[152:155], v[180:183], v[36:39]
	v_mfma_f32_16x16x32_bf16 v[28:31], v[144:147], v[188:191], v[28:31]
	v_mfma_f32_16x16x32_bf16 v[20:23], v[152:155], v[188:191], v[20:23]
	v_mfma_f32_16x16x32_bf16 v[12:15], v[144:147], v[196:199], v[12:15]
	v_mfma_f32_16x16x32_bf16 v[4:7], v[152:155], v[196:199], v[4:7]
	s_barrier
	s_add_u32 s36, s46, 0x40000
	s_addc_u32 s37, s47, 0
	s_add_i32 s38, s39, s29
	v_lshl_add_u64 v[138:139], s[36:37], 0, v[168:169]
	s_mov_b32 m0, s38
	s_nop 0
	global_load_lds_dwordx4 v[138:139], off
	v_lshl_add_u64 v[138:139], s[36:37], 0, v[128:129]
	s_add_i32 m0, s38, 0x2000
	s_nop 0
	global_load_lds_dwordx4 v[138:139], off
	s_waitcnt vmcnt(6)
	s_barrier
	v_mfma_f32_16x16x32_bf16 v[56:59], v[200:203], v[156:159], v[56:59]
	v_mfma_f32_16x16x32_bf16 v[48:51], v[208:211], v[156:159], v[48:51]
	v_mfma_f32_16x16x32_bf16 v[40:43], v[200:203], v[164:167], v[40:43]
	v_mfma_f32_16x16x32_bf16 v[32:35], v[208:211], v[164:167], v[32:35]
	v_mfma_f32_16x16x32_bf16 v[24:27], v[200:203], v[184:187], v[24:27]
	v_mfma_f32_16x16x32_bf16 v[16:19], v[208:211], v[184:187], v[16:19]
	v_mfma_f32_16x16x32_bf16 v[8:11], v[200:203], v[192:195], v[8:11]
	v_mfma_f32_16x16x32_bf16 v[0:3], v[208:211], v[192:195], v[0:3]
	v_mfma_f32_16x16x32_bf16 v[56:59], v[204:207], v[160:163], v[56:59]
	v_mfma_f32_16x16x32_bf16 v[48:51], v[212:215], v[160:163], v[48:51]
	v_mfma_f32_16x16x32_bf16 v[40:43], v[204:207], v[180:183], v[40:43]
	v_mfma_f32_16x16x32_bf16 v[32:35], v[212:215], v[180:183], v[32:35]
	v_mfma_f32_16x16x32_bf16 v[24:27], v[204:207], v[188:191], v[24:27]
	v_mfma_f32_16x16x32_bf16 v[16:19], v[212:215], v[188:191], v[16:19]
	v_mfma_f32_16x16x32_bf16 v[8:11], v[204:207], v[196:199], v[8:11]
	v_mfma_f32_16x16x32_bf16 v[0:3], v[212:215], v[196:199], v[0:3]
	s_add_i32 s38, 0, 0x18000
	v_add_u32_e32 v152, s38, v142
	s_barrier
	ds_read_b128 v[138:141], v152
	ds_read_b128 v[144:147], v152 offset:1024
	ds_read_b128 v[148:151], v152 offset:2048
	ds_read_b128 v[152:155], v152 offset:3072
	s_add_u32 s36, s48, 0x40000
	s_addc_u32 s37, s49, 0
	s_mov_b32 m0, s50
	v_lshl_add_u64 v[200:201], s[36:37], 0, v[132:133]
	ds_read_b128 v[156:159], v143 offset:32768
	ds_read_b128 v[160:163], v143 offset:33792
	ds_read_b128 v[164:167], v143 offset:34816
	ds_read_b128 v[180:183], v143 offset:35840
	ds_read_b128 v[184:187], v143 offset:36864
	ds_read_b128 v[188:191], v143 offset:37888
	ds_read_b128 v[192:195], v143 offset:38912
	ds_read_b128 v[196:199], v143 offset:39936
	global_load_lds_dwordx4 v[200:201], off
	v_lshl_add_u64 v[200:201], s[36:37], 0, v[130:131]
	s_mov_b32 m0, s51
	s_nop 0
	global_load_lds_dwordx4 v[200:201], off
	s_waitcnt lgkmcnt(8)
	s_barrier
	s_waitcnt lgkmcnt(0)
	v_mfma_f32_16x16x32_bf16 v[124:127], v[138:141], v[156:159], v[124:127]
	v_mfma_f32_16x16x32_bf16 v[116:119], v[148:151], v[156:159], v[116:119]
	v_mfma_f32_16x16x32_bf16 v[108:111], v[138:141], v[164:167], v[108:111]
	v_mfma_f32_16x16x32_bf16 v[100:103], v[148:151], v[164:167], v[100:103]
	v_mfma_f32_16x16x32_bf16 v[92:95], v[138:141], v[184:187], v[92:95]
	v_mfma_f32_16x16x32_bf16 v[84:87], v[148:151], v[184:187], v[84:87]
	v_mfma_f32_16x16x32_bf16 v[76:79], v[138:141], v[192:195], v[76:79]
	v_mfma_f32_16x16x32_bf16 v[68:71], v[148:151], v[192:195], v[68:71]
	v_mfma_f32_16x16x32_bf16 v[124:127], v[144:147], v[160:163], v[124:127]
	v_mfma_f32_16x16x32_bf16 v[116:119], v[152:155], v[160:163], v[116:119]
	v_mfma_f32_16x16x32_bf16 v[108:111], v[144:147], v[180:183], v[108:111]
	v_mfma_f32_16x16x32_bf16 v[100:103], v[152:155], v[180:183], v[100:103]
	v_mfma_f32_16x16x32_bf16 v[92:95], v[144:147], v[188:191], v[92:95]
	v_mfma_f32_16x16x32_bf16 v[84:87], v[152:155], v[188:191], v[84:87]
	v_mfma_f32_16x16x32_bf16 v[76:79], v[144:147], v[196:199], v[76:79]
	v_mfma_f32_16x16x32_bf16 v[68:71], v[152:155], v[196:199], v[68:71]
	s_barrier
	s_add_i32 s39, 0, 0x1c000
	s_add_i32 s36, s38, s29
	v_add_u32_e32 v212, s39, v142
	v_lshl_add_u64 v[172:173], v[172:173], 0, s[88:89]
	s_mov_b32 m0, s36
	ds_read_b128 v[200:203], v212
	ds_read_b128 v[204:207], v212 offset:1024
	ds_read_b128 v[208:211], v212 offset:2048
	ds_read_b128 v[212:215], v212 offset:3072
	global_load_lds_dwordx4 v[172:173], off
	v_lshl_add_u64 v[172:173], v[174:175], 0, s[88:89]
	s_add_i32 m0, s36, 0x2000
	s_nop 0
	global_load_lds_dwordx4 v[172:173], off
	s_barrier
	s_waitcnt lgkmcnt(0)
	v_mfma_f32_16x16x32_bf16 v[120:123], v[200:203], v[156:159], v[120:123]
	v_mfma_f32_16x16x32_bf16 v[112:115], v[208:211], v[156:159], v[112:115]
	v_mfma_f32_16x16x32_bf16 v[104:107], v[200:203], v[164:167], v[104:107]
	v_mfma_f32_16x16x32_bf16 v[96:99], v[208:211], v[164:167], v[96:99]
	v_mfma_f32_16x16x32_bf16 v[88:91], v[200:203], v[184:187], v[88:91]
	v_mfma_f32_16x16x32_bf16 v[80:83], v[208:211], v[184:187], v[80:83]
	v_mfma_f32_16x16x32_bf16 v[72:75], v[200:203], v[192:195], v[72:75]
	v_mfma_f32_16x16x32_bf16 v[64:67], v[208:211], v[192:195], v[64:67]
	v_mfma_f32_16x16x32_bf16 v[120:123], v[204:207], v[160:163], v[120:123]
	v_mfma_f32_16x16x32_bf16 v[112:115], v[212:215], v[160:163], v[112:115]
	v_mfma_f32_16x16x32_bf16 v[104:107], v[204:207], v[180:183], v[104:107]
	v_mfma_f32_16x16x32_bf16 v[96:99], v[212:215], v[180:183], v[96:99]
	v_mfma_f32_16x16x32_bf16 v[88:91], v[204:207], v[188:191], v[88:91]
	v_mfma_f32_16x16x32_bf16 v[80:83], v[212:215], v[188:191], v[80:83]
	v_mfma_f32_16x16x32_bf16 v[72:75], v[204:207], v[196:199], v[72:75]
	v_mfma_f32_16x16x32_bf16 v[64:67], v[212:215], v[196:199], v[64:67]
	s_mov_b32 m0, s54
	v_lshl_add_u64 v[172:173], v[176:177], 0, s[88:89]
	s_barrier
	ds_read_b128 v[156:159], v143 offset:49152
	ds_read_b128 v[160:163], v143 offset:50176
	ds_read_b128 v[164:167], v143 offset:51200
	ds_read_b128 v[180:183], v143 offset:52224
	ds_read_b128 v[184:187], v143 offset:53248
	ds_read_b128 v[188:191], v143 offset:54272
	ds_read_b128 v[192:195], v143 offset:55296
	ds_read_b128 v[196:199], v143 offset:56320
	global_load_lds_dwordx4 v[172:173], off
	v_lshl_add_u64 v[172:173], v[178:179], 0, s[88:89]
	s_mov_b32 m0, s55
	s_nop 0
	global_load_lds_dwordx4 v[172:173], off
	s_barrier
	s_waitcnt lgkmcnt(0)
	v_mfma_f32_16x16x32_bf16 v[60:63], v[138:141], v[156:159], v[60:63]
	v_mfma_f32_16x16x32_bf16 v[52:55], v[148:151], v[156:159], v[52:55]
	v_mfma_f32_16x16x32_bf16 v[44:47], v[138:141], v[164:167], v[44:47]
	v_mfma_f32_16x16x32_bf16 v[36:39], v[148:151], v[164:167], v[36:39]
	v_mfma_f32_16x16x32_bf16 v[28:31], v[138:141], v[184:187], v[28:31]
	v_mfma_f32_16x16x32_bf16 v[20:23], v[148:151], v[184:187], v[20:23]
	v_mfma_f32_16x16x32_bf16 v[12:15], v[138:141], v[192:195], v[12:15]
	v_mfma_f32_16x16x32_bf16 v[4:7], v[148:151], v[192:195], v[4:7]
	v_mfma_f32_16x16x32_bf16 v[60:63], v[144:147], v[160:163], v[60:63]
	v_mfma_f32_16x16x32_bf16 v[52:55], v[152:155], v[160:163], v[52:55]
	v_mfma_f32_16x16x32_bf16 v[44:47], v[144:147], v[180:183], v[44:47]
	v_mfma_f32_16x16x32_bf16 v[36:39], v[152:155], v[180:183], v[36:39]
	v_mfma_f32_16x16x32_bf16 v[28:31], v[144:147], v[188:191], v[28:31]
	v_mfma_f32_16x16x32_bf16 v[20:23], v[152:155], v[188:191], v[20:23]
	v_mfma_f32_16x16x32_bf16 v[12:15], v[144:147], v[196:199], v[12:15]
	v_mfma_f32_16x16x32_bf16 v[4:7], v[152:155], v[196:199], v[4:7]
	s_barrier
	s_add_u32 s36, s46, 0x40080
	s_addc_u32 s37, s47, 0
	s_add_i32 s38, s39, s29
	v_lshl_add_u64 v[138:139], s[36:37], 0, v[168:169]
	s_mov_b32 m0, s38
	s_nop 0
	global_load_lds_dwordx4 v[138:139], off
	v_lshl_add_u64 v[138:139], s[36:37], 0, v[128:129]
	s_add_i32 m0, s38, 0x2000
	s_nop 0
	global_load_lds_dwordx4 v[138:139], off
	s_waitcnt vmcnt(6)
	s_barrier
	v_mfma_f32_16x16x32_bf16 v[56:59], v[200:203], v[156:159], v[56:59]
	v_mfma_f32_16x16x32_bf16 v[48:51], v[208:211], v[156:159], v[48:51]
	v_mfma_f32_16x16x32_bf16 v[40:43], v[200:203], v[164:167], v[40:43]
	v_mfma_f32_16x16x32_bf16 v[32:35], v[208:211], v[164:167], v[32:35]
	v_mfma_f32_16x16x32_bf16 v[24:27], v[200:203], v[184:187], v[24:27]
	v_mfma_f32_16x16x32_bf16 v[16:19], v[208:211], v[184:187], v[16:19]
	v_mfma_f32_16x16x32_bf16 v[8:11], v[200:203], v[192:195], v[8:11]
	v_mfma_f32_16x16x32_bf16 v[0:3], v[208:211], v[192:195], v[0:3]
	v_mfma_f32_16x16x32_bf16 v[56:59], v[204:207], v[160:163], v[56:59]
	v_mfma_f32_16x16x32_bf16 v[48:51], v[212:215], v[160:163], v[48:51]
	v_mfma_f32_16x16x32_bf16 v[40:43], v[204:207], v[180:183], v[40:43]
	v_mfma_f32_16x16x32_bf16 v[32:35], v[212:215], v[180:183], v[32:35]
	v_mfma_f32_16x16x32_bf16 v[24:27], v[204:207], v[188:191], v[24:27]
	v_mfma_f32_16x16x32_bf16 v[16:19], v[212:215], v[188:191], v[16:19]
	v_mfma_f32_16x16x32_bf16 v[8:11], v[204:207], v[196:199], v[8:11]
	v_mfma_f32_16x16x32_bf16 v[0:3], v[212:215], v[196:199], v[0:3]
	s_add_i32 s61, s61, 2
	s_add_u32 s44, s44, 0x100
	s_addc_u32 s45, s45, 0
	s_add_u32 s59, s59, 0x100
	s_addc_u32 s60, s60, 0
	s_cmp_gt_u32 s61, 13
	s_barrier
	s_cbranch_scc0 .LBB0_191
	v_mul_f32_e32 v145, 0xbfb8aa3b, v124
	v_exp_f32_e32 v145, v145
	v_mov_b32_e32 v138, v171
	s_lshl_b32 s9, s58, 8
	v_add_f32_e32 v145, 1.0, v145
	v_rcp_f32_e32 v148, v145
	v_mul_f32_e32 v145, 0xbfb8aa3b, v125
	v_exp_f32_e32 v145, v145
	s_add_i32 s9, s9, s52
	v_and_or_b32 v144, v138, 15, s9
	s_lshl_b32 s9, s57, 7
	v_add_f32_e32 v145, 1.0, v145
	v_rcp_f32_e32 v149, v145
	v_lshrrev_b32_e32 v138, 1, v138
	v_and_or_b32 v138, v138, 24, s9
	v_or_b32_e32 v140, s53, v138
	v_pk_mul_f32 v[124:125], v[124:125], v[148:149]
	v_ashrrev_i32_e32 v141, 31, v140
	v_pk_mul_f32 v[120:121], v[124:125], v[120:121]
	v_mov_b64_e32 v[138:139], s[6:7]
	v_cvt_pk_bf16_f32 v120, v120, v121
	v_mul_f32_e32 v121, 0xbfb8aa3b, v126
	v_exp_f32_e32 v121, v121
	v_mad_i64_i32 v[146:147], s[34:35], v144, s18, v[138:139]
	v_lshlrev_b64 v[140:141], 1, v[140:141]
	v_add_f32_e32 v121, 1.0, v121
	v_rcp_f32_e32 v124, v121
	v_mul_f32_e32 v121, 0xbfb8aa3b, v127
	v_exp_f32_e32 v121, v121
	v_lshl_add_u64 v[146:147], v[146:147], 0, v[140:141]
	s_and_b64 vcc, exec, s[40:41]
	s_mov_b32 s57, s8
	v_add_f32_e32 v121, 1.0, v121
	v_rcp_f32_e32 v125, v121
	s_mov_b32 s58, s12
	s_mov_b64 s[46:47], s[42:43]
	s_mov_b64 s[44:45], s[14:15]
	v_pk_mul_f32 v[124:125], v[126:127], v[124:125]
	s_nop 0
	v_pk_mul_f32 v[122:123], v[124:125], v[122:123]
	s_nop 0
	v_cvt_pk_bf16_f32 v121, v122, v123
	v_mul_f32_e32 v122, 0xbfb8aa3b, v116
	v_mul_f32_e32 v123, 0xbfb8aa3b, v117
	v_exp_f32_e32 v122, v122
	v_exp_f32_e32 v123, v123
	v_add_f32_e32 v122, 1.0, v122
	v_add_f32_e32 v123, 1.0, v123
	v_rcp_f32_e32 v122, v122
	v_rcp_f32_e32 v123, v123
	s_nop 0
	v_pk_mul_f32 v[116:117], v[116:117], v[122:123]
	s_nop 0
	v_pk_mul_f32 v[112:113], v[116:117], v[112:113]
	s_nop 0
	v_cvt_pk_bf16_f32 v122, v112, v113
	v_mul_f32_e32 v112, 0xbfb8aa3b, v118
	v_mul_f32_e32 v113, 0xbfb8aa3b, v119
	v_exp_f32_e32 v112, v112
	v_exp_f32_e32 v113, v113
	v_add_f32_e32 v112, 1.0, v112
	v_add_f32_e32 v113, 1.0, v113
	v_rcp_f32_e32 v112, v112
	v_rcp_f32_e32 v113, v113
	s_nop 0
	v_pk_mul_f32 v[112:113], v[118:119], v[112:113]
	s_nop 0
	v_pk_mul_f32 v[112:113], v[112:113], v[114:115]
	v_mul_f32_e32 v114, 0xbfb8aa3b, v108
	v_mul_f32_e32 v115, 0xbfb8aa3b, v109
	v_exp_f32_e32 v114, v114
	v_exp_f32_e32 v115, v115
	v_cvt_pk_bf16_f32 v123, v112, v113
	v_or_b32_e32 v112, 16, v144
	v_add_f32_e32 v114, 1.0, v114
	v_add_f32_e32 v115, 1.0, v115
	v_rcp_f32_e32 v114, v114
	v_rcp_f32_e32 v115, v115
	v_mad_i64_i32 v[112:113], s[34:35], v112, s18, v[138:139]
	global_store_dwordx4 v[146:147], v[120:123], off
	v_pk_mul_f32 v[108:109], v[108:109], v[114:115]
	v_lshl_add_u64 v[112:113], v[112:113], 0, v[140:141]
	v_pk_mul_f32 v[104:105], v[108:109], v[104:105]
	s_nop 0
	v_cvt_pk_bf16_f32 v104, v104, v105
	v_mul_f32_e32 v105, 0xbfb8aa3b, v110
	v_exp_f32_e32 v105, v105
	s_nop 0
	v_add_f32_e32 v105, 1.0, v105
	v_rcp_f32_e32 v108, v105
	v_mul_f32_e32 v105, 0xbfb8aa3b, v111
	v_exp_f32_e32 v105, v105
	s_nop 0
	v_add_f32_e32 v105, 1.0, v105
	v_rcp_f32_e32 v109, v105
	s_nop 0
	v_pk_mul_f32 v[108:109], v[110:111], v[108:109]
	s_nop 0
	v_pk_mul_f32 v[106:107], v[108:109], v[106:107]
	s_nop 0
	v_cvt_pk_bf16_f32 v105, v106, v107
	v_mul_f32_e32 v106, 0xbfb8aa3b, v100
	v_mul_f32_e32 v107, 0xbfb8aa3b, v101
	v_exp_f32_e32 v106, v106
	v_exp_f32_e32 v107, v107
	v_add_f32_e32 v106, 1.0, v106
	v_add_f32_e32 v107, 1.0, v107
	v_rcp_f32_e32 v106, v106
	v_rcp_f32_e32 v107, v107
	s_nop 0
	v_pk_mul_f32 v[100:101], v[100:101], v[106:107]
	s_nop 0
	v_pk_mul_f32 v[96:97], v[100:101], v[96:97]
	s_nop 0
	v_cvt_pk_bf16_f32 v106, v96, v97
	v_mul_f32_e32 v96, 0xbfb8aa3b, v102
	v_mul_f32_e32 v97, 0xbfb8aa3b, v103
	v_exp_f32_e32 v96, v96
	v_exp_f32_e32 v97, v97
	v_add_f32_e32 v96, 1.0, v96
	v_add_f32_e32 v97, 1.0, v97
	v_rcp_f32_e32 v96, v96
	v_rcp_f32_e32 v97, v97
	s_nop 0
	v_pk_mul_f32 v[96:97], v[102:103], v[96:97]
	s_nop 0
	v_pk_mul_f32 v[96:97], v[96:97], v[98:99]
	v_mul_f32_e32 v98, 0xbfb8aa3b, v92
	v_mul_f32_e32 v99, 0xbfb8aa3b, v93
	v_exp_f32_e32 v98, v98
	v_exp_f32_e32 v99, v99
	v_cvt_pk_bf16_f32 v107, v96, v97
	v_or_b32_e32 v96, 32, v144
	v_add_f32_e32 v98, 1.0, v98
	v_add_f32_e32 v99, 1.0, v99
	v_rcp_f32_e32 v98, v98
	v_rcp_f32_e32 v99, v99
	v_mad_i64_i32 v[96:97], s[34:35], v96, s18, v[138:139]
	global_store_dwordx4 v[112:113], v[104:107], off
	v_pk_mul_f32 v[92:93], v[92:93], v[98:99]
	v_lshl_add_u64 v[96:97], v[96:97], 0, v[140:141]
	v_pk_mul_f32 v[88:89], v[92:93], v[88:89]
	s_nop 0
	v_cvt_pk_bf16_f32 v88, v88, v89
	v_mul_f32_e32 v89, 0xbfb8aa3b, v94
	v_exp_f32_e32 v89, v89
	s_nop 0
	v_add_f32_e32 v89, 1.0, v89
	v_rcp_f32_e32 v92, v89
	v_mul_f32_e32 v89, 0xbfb8aa3b, v95
	v_exp_f32_e32 v89, v89
	s_nop 0
	v_add_f32_e32 v89, 1.0, v89
	v_rcp_f32_e32 v93, v89
	s_nop 0
	v_pk_mul_f32 v[92:93], v[94:95], v[92:93]
	s_nop 0
	v_pk_mul_f32 v[90:91], v[92:93], v[90:91]
	s_nop 0
	v_cvt_pk_bf16_f32 v89, v90, v91
	v_mul_f32_e32 v90, 0xbfb8aa3b, v84
	v_mul_f32_e32 v91, 0xbfb8aa3b, v85
	v_exp_f32_e32 v90, v90
	v_exp_f32_e32 v91, v91
	v_add_f32_e32 v90, 1.0, v90
	v_add_f32_e32 v91, 1.0, v91
	v_rcp_f32_e32 v90, v90
	v_rcp_f32_e32 v91, v91
	s_nop 0
	v_pk_mul_f32 v[84:85], v[84:85], v[90:91]
	s_nop 0
	v_pk_mul_f32 v[80:81], v[84:85], v[80:81]
	s_nop 0
	v_cvt_pk_bf16_f32 v90, v80, v81
	v_mul_f32_e32 v80, 0xbfb8aa3b, v86
	v_mul_f32_e32 v81, 0xbfb8aa3b, v87
	v_exp_f32_e32 v80, v80
	v_exp_f32_e32 v81, v81
	v_add_f32_e32 v80, 1.0, v80
	v_add_f32_e32 v81, 1.0, v81
	v_rcp_f32_e32 v80, v80
	v_rcp_f32_e32 v81, v81
	s_nop 0
	v_pk_mul_f32 v[80:81], v[86:87], v[80:81]
	s_nop 0
	v_pk_mul_f32 v[80:81], v[80:81], v[82:83]
	v_mul_f32_e32 v82, 0xbfb8aa3b, v76
	v_mul_f32_e32 v83, 0xbfb8aa3b, v77
	v_exp_f32_e32 v82, v82
	v_exp_f32_e32 v83, v83
	v_cvt_pk_bf16_f32 v91, v80, v81
	v_or_b32_e32 v80, 48, v144
	v_add_f32_e32 v82, 1.0, v82
	v_add_f32_e32 v83, 1.0, v83
	v_rcp_f32_e32 v82, v82
	v_rcp_f32_e32 v83, v83
	v_mad_i64_i32 v[80:81], s[34:35], v80, s18, v[138:139]
	global_store_dwordx4 v[96:97], v[88:91], off
	v_pk_mul_f32 v[76:77], v[76:77], v[82:83]
	v_lshl_add_u64 v[80:81], v[80:81], 0, v[140:141]
	v_pk_mul_f32 v[72:73], v[76:77], v[72:73]
	s_nop 0
	v_cvt_pk_bf16_f32 v72, v72, v73
	v_mul_f32_e32 v73, 0xbfb8aa3b, v78
	v_exp_f32_e32 v73, v73
	s_nop 0
	v_add_f32_e32 v73, 1.0, v73
	v_rcp_f32_e32 v76, v73
	v_mul_f32_e32 v73, 0xbfb8aa3b, v79
	v_exp_f32_e32 v73, v73
	s_nop 0
	v_add_f32_e32 v73, 1.0, v73
	v_rcp_f32_e32 v77, v73
	s_nop 0
	v_pk_mul_f32 v[76:77], v[78:79], v[76:77]
	s_nop 0
	v_pk_mul_f32 v[74:75], v[76:77], v[74:75]
	s_nop 0
	v_cvt_pk_bf16_f32 v73, v74, v75
	v_mul_f32_e32 v74, 0xbfb8aa3b, v68
	v_mul_f32_e32 v75, 0xbfb8aa3b, v69
	v_exp_f32_e32 v74, v74
	v_exp_f32_e32 v75, v75
	v_add_f32_e32 v74, 1.0, v74
	v_add_f32_e32 v75, 1.0, v75
	v_rcp_f32_e32 v74, v74
	v_rcp_f32_e32 v75, v75
	s_nop 0
	v_pk_mul_f32 v[68:69], v[68:69], v[74:75]
	s_nop 0
	v_pk_mul_f32 v[64:65], v[68:69], v[64:65]
	s_nop 0
	v_cvt_pk_bf16_f32 v74, v64, v65
	v_mul_f32_e32 v64, 0xbfb8aa3b, v70
	v_mul_f32_e32 v65, 0xbfb8aa3b, v71
	v_exp_f32_e32 v64, v64
	v_exp_f32_e32 v65, v65
	v_add_f32_e32 v64, 1.0, v64
	v_add_f32_e32 v65, 1.0, v65
	v_rcp_f32_e32 v64, v64
	v_rcp_f32_e32 v65, v65
	s_nop 0
	v_pk_mul_f32 v[64:65], v[70:71], v[64:65]
	s_nop 0
	v_pk_mul_f32 v[64:65], v[64:65], v[66:67]
	v_mul_f32_e32 v66, 0xbfb8aa3b, v60
	v_mul_f32_e32 v67, 0xbfb8aa3b, v61
	v_exp_f32_e32 v66, v66
	v_exp_f32_e32 v67, v67
	v_cvt_pk_bf16_f32 v75, v64, v65
	v_add_u32_e32 v64, 0x80, v144
	v_add_f32_e32 v66, 1.0, v66
	v_add_f32_e32 v67, 1.0, v67
	v_rcp_f32_e32 v66, v66
	v_rcp_f32_e32 v67, v67
	v_mad_i64_i32 v[64:65], s[34:35], v64, s18, v[138:139]
	global_store_dwordx4 v[80:81], v[72:75], off
	v_pk_mul_f32 v[60:61], v[60:61], v[66:67]
	v_lshl_add_u64 v[64:65], v[64:65], 0, v[140:141]
	v_pk_mul_f32 v[56:57], v[60:61], v[56:57]
	s_nop 0
	v_cvt_pk_bf16_f32 v56, v56, v57
	v_mul_f32_e32 v57, 0xbfb8aa3b, v62
	v_exp_f32_e32 v57, v57
	s_nop 0
	v_add_f32_e32 v57, 1.0, v57
	v_rcp_f32_e32 v60, v57
	v_mul_f32_e32 v57, 0xbfb8aa3b, v63
	v_exp_f32_e32 v57, v57
	s_nop 0
	v_add_f32_e32 v57, 1.0, v57
	v_rcp_f32_e32 v61, v57
	s_nop 0
	v_pk_mul_f32 v[60:61], v[62:63], v[60:61]
	s_nop 0
	v_pk_mul_f32 v[58:59], v[60:61], v[58:59]
	s_nop 0
	v_cvt_pk_bf16_f32 v57, v58, v59
	v_mul_f32_e32 v58, 0xbfb8aa3b, v52
	v_mul_f32_e32 v59, 0xbfb8aa3b, v53
	v_exp_f32_e32 v58, v58
	v_exp_f32_e32 v59, v59
	v_add_f32_e32 v58, 1.0, v58
	v_add_f32_e32 v59, 1.0, v59
	v_rcp_f32_e32 v58, v58
	v_rcp_f32_e32 v59, v59
	s_nop 0
	v_pk_mul_f32 v[52:53], v[52:53], v[58:59]
	s_nop 0
	v_pk_mul_f32 v[48:49], v[52:53], v[48:49]
	s_nop 0
	v_cvt_pk_bf16_f32 v58, v48, v49
	v_mul_f32_e32 v48, 0xbfb8aa3b, v54
	v_mul_f32_e32 v49, 0xbfb8aa3b, v55
	v_exp_f32_e32 v48, v48
	v_exp_f32_e32 v49, v49
	v_add_f32_e32 v48, 1.0, v48
	v_add_f32_e32 v49, 1.0, v49
	v_rcp_f32_e32 v48, v48
	v_rcp_f32_e32 v49, v49
	s_nop 0
	v_pk_mul_f32 v[48:49], v[54:55], v[48:49]
	s_nop 0
	v_pk_mul_f32 v[48:49], v[48:49], v[50:51]
	v_mul_f32_e32 v50, 0xbfb8aa3b, v44
	v_mul_f32_e32 v51, 0xbfb8aa3b, v45
	v_exp_f32_e32 v50, v50
	v_exp_f32_e32 v51, v51
	v_cvt_pk_bf16_f32 v59, v48, v49
	v_add_u32_e32 v48, 0x90, v144
	v_add_f32_e32 v50, 1.0, v50
	v_add_f32_e32 v51, 1.0, v51
	v_rcp_f32_e32 v50, v50
	v_rcp_f32_e32 v51, v51
	v_mad_i64_i32 v[48:49], s[34:35], v48, s18, v[138:139]
	global_store_dwordx4 v[64:65], v[56:59], off
	v_pk_mul_f32 v[44:45], v[44:45], v[50:51]
	v_lshl_add_u64 v[48:49], v[48:49], 0, v[140:141]
	v_pk_mul_f32 v[40:41], v[44:45], v[40:41]
	s_nop 0
	v_cvt_pk_bf16_f32 v40, v40, v41
	v_mul_f32_e32 v41, 0xbfb8aa3b, v46
	v_exp_f32_e32 v41, v41
	s_nop 0
	v_add_f32_e32 v41, 1.0, v41
	v_rcp_f32_e32 v44, v41
	v_mul_f32_e32 v41, 0xbfb8aa3b, v47
	v_exp_f32_e32 v41, v41
	s_nop 0
	v_add_f32_e32 v41, 1.0, v41
	v_rcp_f32_e32 v45, v41
	s_nop 0
	v_pk_mul_f32 v[44:45], v[46:47], v[44:45]
	s_nop 0
	v_pk_mul_f32 v[42:43], v[44:45], v[42:43]
	s_nop 0
	v_cvt_pk_bf16_f32 v41, v42, v43
	v_mul_f32_e32 v42, 0xbfb8aa3b, v36
	v_mul_f32_e32 v43, 0xbfb8aa3b, v37
	v_exp_f32_e32 v42, v42
	v_exp_f32_e32 v43, v43
	v_add_f32_e32 v42, 1.0, v42
	v_add_f32_e32 v43, 1.0, v43
	v_rcp_f32_e32 v42, v42
	v_rcp_f32_e32 v43, v43
	s_nop 0
	v_pk_mul_f32 v[36:37], v[36:37], v[42:43]
	s_nop 0
	v_pk_mul_f32 v[32:33], v[36:37], v[32:33]
	s_nop 0
	v_cvt_pk_bf16_f32 v42, v32, v33
	v_mul_f32_e32 v32, 0xbfb8aa3b, v38
	v_mul_f32_e32 v33, 0xbfb8aa3b, v39
	v_exp_f32_e32 v32, v32
	v_exp_f32_e32 v33, v33
	v_add_f32_e32 v32, 1.0, v32
	v_add_f32_e32 v33, 1.0, v33
	v_rcp_f32_e32 v32, v32
	v_rcp_f32_e32 v33, v33
	s_nop 0
	v_pk_mul_f32 v[32:33], v[38:39], v[32:33]
	s_nop 0
	v_pk_mul_f32 v[32:33], v[32:33], v[34:35]
	v_mul_f32_e32 v34, 0xbfb8aa3b, v28
	v_mul_f32_e32 v35, 0xbfb8aa3b, v29
	v_exp_f32_e32 v34, v34
	v_exp_f32_e32 v35, v35
	v_cvt_pk_bf16_f32 v43, v32, v33
	v_add_u32_e32 v32, 0xa0, v144
	v_add_f32_e32 v34, 1.0, v34
	v_add_f32_e32 v35, 1.0, v35
	v_rcp_f32_e32 v34, v34
	v_rcp_f32_e32 v35, v35
	v_mad_i64_i32 v[32:33], s[34:35], v32, s18, v[138:139]
	global_store_dwordx4 v[48:49], v[40:43], off
	v_pk_mul_f32 v[28:29], v[28:29], v[34:35]
	v_lshl_add_u64 v[32:33], v[32:33], 0, v[140:141]
	v_pk_mul_f32 v[24:25], v[28:29], v[24:25]
	s_nop 0
	v_cvt_pk_bf16_f32 v24, v24, v25
	v_mul_f32_e32 v25, 0xbfb8aa3b, v30
	v_exp_f32_e32 v25, v25
	s_nop 0
	v_add_f32_e32 v25, 1.0, v25
	v_rcp_f32_e32 v28, v25
	v_mul_f32_e32 v25, 0xbfb8aa3b, v31
	v_exp_f32_e32 v25, v25
	s_nop 0
	v_add_f32_e32 v25, 1.0, v25
	v_rcp_f32_e32 v29, v25
	s_nop 0
	v_pk_mul_f32 v[28:29], v[30:31], v[28:29]
	s_nop 0
	v_pk_mul_f32 v[26:27], v[28:29], v[26:27]
	s_nop 0
	v_cvt_pk_bf16_f32 v25, v26, v27
	v_mul_f32_e32 v26, 0xbfb8aa3b, v20
	v_mul_f32_e32 v27, 0xbfb8aa3b, v21
	v_exp_f32_e32 v26, v26
	v_exp_f32_e32 v27, v27
	v_add_f32_e32 v26, 1.0, v26
	v_add_f32_e32 v27, 1.0, v27
	v_rcp_f32_e32 v26, v26
	v_rcp_f32_e32 v27, v27
	s_nop 0
	v_pk_mul_f32 v[20:21], v[20:21], v[26:27]
	s_nop 0
	v_pk_mul_f32 v[16:17], v[20:21], v[16:17]
	s_nop 0
	v_cvt_pk_bf16_f32 v26, v16, v17
	v_mul_f32_e32 v16, 0xbfb8aa3b, v22
	v_mul_f32_e32 v17, 0xbfb8aa3b, v23
	v_exp_f32_e32 v16, v16
	v_exp_f32_e32 v17, v17
	v_add_f32_e32 v16, 1.0, v16
	v_add_f32_e32 v17, 1.0, v17
	v_rcp_f32_e32 v16, v16
	v_rcp_f32_e32 v17, v17
	s_nop 0
	v_pk_mul_f32 v[16:17], v[22:23], v[16:17]
	s_nop 0
	v_pk_mul_f32 v[16:17], v[16:17], v[18:19]
	v_mul_f32_e32 v18, 0xbfb8aa3b, v12
	v_mul_f32_e32 v19, 0xbfb8aa3b, v13
	v_exp_f32_e32 v18, v18
	v_exp_f32_e32 v19, v19
	v_cvt_pk_bf16_f32 v27, v16, v17
	v_add_u32_e32 v16, 0xb0, v144
	v_add_f32_e32 v18, 1.0, v18
	v_add_f32_e32 v19, 1.0, v19
	v_rcp_f32_e32 v18, v18
	v_rcp_f32_e32 v19, v19
	v_mad_i64_i32 v[16:17], s[34:35], v16, s18, v[138:139]
	global_store_dwordx4 v[32:33], v[24:27], off
	v_pk_mul_f32 v[12:13], v[12:13], v[18:19]
	v_lshl_add_u64 v[16:17], v[16:17], 0, v[140:141]
	v_pk_mul_f32 v[8:9], v[12:13], v[8:9]
	s_nop 0
	v_cvt_pk_bf16_f32 v8, v8, v9
	v_mul_f32_e32 v9, 0xbfb8aa3b, v14
	v_exp_f32_e32 v9, v9
	s_nop 0
	v_add_f32_e32 v9, 1.0, v9
	v_rcp_f32_e32 v12, v9
	v_mul_f32_e32 v9, 0xbfb8aa3b, v15
	v_exp_f32_e32 v9, v9
	s_nop 0
	v_add_f32_e32 v9, 1.0, v9
	v_rcp_f32_e32 v13, v9
	s_nop 0
	v_pk_mul_f32 v[12:13], v[14:15], v[12:13]
	s_nop 0
	v_pk_mul_f32 v[10:11], v[12:13], v[10:11]
	s_nop 0
	v_cvt_pk_bf16_f32 v9, v10, v11
	v_mul_f32_e32 v10, 0xbfb8aa3b, v4
	v_mul_f32_e32 v11, 0xbfb8aa3b, v5
	v_exp_f32_e32 v10, v10
	v_exp_f32_e32 v11, v11
	v_add_f32_e32 v10, 1.0, v10
	v_add_f32_e32 v11, 1.0, v11
	v_rcp_f32_e32 v10, v10
	v_rcp_f32_e32 v11, v11
	s_nop 0
	v_pk_mul_f32 v[4:5], v[4:5], v[10:11]
	s_nop 0
	v_pk_mul_f32 v[0:1], v[4:5], v[0:1]
	s_nop 0
	v_cvt_pk_bf16_f32 v10, v0, v1
	v_mul_f32_e32 v0, 0xbfb8aa3b, v6
	v_mul_f32_e32 v1, 0xbfb8aa3b, v7
	v_exp_f32_e32 v0, v0
	v_exp_f32_e32 v1, v1
	v_add_f32_e32 v0, 1.0, v0
	v_add_f32_e32 v1, 1.0, v1
	v_rcp_f32_e32 v0, v0
	v_rcp_f32_e32 v1, v1
	s_nop 0
	v_pk_mul_f32 v[0:1], v[6:7], v[0:1]
	s_nop 0
	v_pk_mul_f32 v[0:1], v[0:1], v[2:3]
	s_nop 0
	v_cvt_pk_bf16_f32 v11, v0, v1
	global_store_dwordx4 v[16:17], v[8:11], off
	s_cbranch_vccz .LBB0_188
	s_waitcnt vmcnt(0)
	s_cmpk_gt_u32 s16, 0xff
	s_cbranch_scc1 .LBB0_195
	s_barrier

.LBB0_264:
	s_add_u32 s36, s50, 0xfffc0080
	s_addc_u32 s37, s51, -1
	s_add_i32 s38, 0, 0x10000
	v_add_u32_e32 v154, s38, v144
	ds_read_b128 v[140:143], v154
	ds_read_b128 v[146:149], v154 offset:1024
	ds_read_b128 v[150:153], v154 offset:2048
	ds_read_b128 v[154:157], v154 offset:3072
	s_cmp_eq_u32 s49, 12
	s_cselect_b32 s55, s15, s37
	s_cselect_b32 s54, s16, s36
	s_cselect_b32 s53, s13, s35
	s_cselect_b32 s52, s17, s34
	v_lshl_add_u64 v[166:167], s[50:51], 0, v[136:137]
	s_add_i32 m0, s31, 0xc000
	ds_read_b128 v[158:161], v145
	ds_read_b128 v[162:165], v145 offset:1024
	ds_read_b128 v[180:183], v145 offset:2048
	ds_read_b128 v[184:187], v145 offset:3072
	ds_read_b128 v[188:191], v145 offset:4096
	ds_read_b128 v[192:195], v145 offset:5120
	ds_read_b128 v[196:199], v145 offset:6144
	ds_read_b128 v[200:203], v145 offset:7168
	global_load_lds_dwordx4 v[166:167], off
	v_lshl_add_u64 v[166:167], s[50:51], 0, v[138:139]
	s_add_i32 m0, s31, 0xe000
	s_nop 0
	global_load_lds_dwordx4 v[166:167], off
	s_waitcnt lgkmcnt(8)
	s_barrier
	s_waitcnt lgkmcnt(0)
	v_mfma_f32_16x16x32_bf16 v[124:127], v[140:143], v[158:161], v[124:127]
	v_mfma_f32_16x16x32_bf16 v[120:123], v[150:153], v[158:161], v[120:123]
	v_mfma_f32_16x16x32_bf16 v[116:119], v[140:143], v[180:183], v[116:119]
	v_mfma_f32_16x16x32_bf16 v[112:115], v[150:153], v[180:183], v[112:115]
	v_mfma_f32_16x16x32_bf16 v[108:111], v[140:143], v[188:191], v[108:111]
	v_mfma_f32_16x16x32_bf16 v[104:107], v[150:153], v[188:191], v[104:107]
	v_mfma_f32_16x16x32_bf16 v[100:103], v[140:143], v[196:199], v[100:103]
	v_mfma_f32_16x16x32_bf16 v[96:99], v[150:153], v[196:199], v[96:99]
	v_mfma_f32_16x16x32_bf16 v[124:127], v[146:149], v[162:165], v[124:127]
	v_mfma_f32_16x16x32_bf16 v[120:123], v[154:157], v[162:165], v[120:123]
	v_mfma_f32_16x16x32_bf16 v[116:119], v[146:149], v[184:187], v[116:119]
	v_mfma_f32_16x16x32_bf16 v[112:115], v[154:157], v[184:187], v[112:115]
	v_mfma_f32_16x16x32_bf16 v[108:111], v[146:149], v[192:195], v[108:111]
	v_mfma_f32_16x16x32_bf16 v[104:107], v[154:157], v[192:195], v[104:107]
	v_mfma_f32_16x16x32_bf16 v[100:103], v[146:149], v[200:203], v[100:103]
	v_mfma_f32_16x16x32_bf16 v[96:99], v[154:157], v[200:203], v[96:99]
	s_barrier
	s_add_i32 s39, 0, 0x14000
	v_add_u32_e32 v166, s39, v144
	s_add_i32 s36, s38, s30
	ds_read_b128 v[204:207], v166
	ds_read_b128 v[208:211], v166 offset:1024
	ds_read_b128 v[212:215], v166 offset:2048
	ds_read_b128 v[216:219], v166 offset:3072
	v_lshl_add_u64 v[166:167], s[52:53], 0, v[130:131]
	s_mov_b32 m0, s36
	v_lshl_add_u64 v[172:173], s[52:53], 0, v[134:135]
	global_load_lds_dwordx4 v[166:167], off
	s_add_i32 m0, s36, 0x2000
	s_nop 0
	global_load_lds_dwordx4 v[172:173], off
	s_barrier
	s_waitcnt lgkmcnt(0)
	v_mfma_f32_16x16x32_bf16 v[68:71], v[204:207], v[158:161], v[68:71]
	v_mfma_f32_16x16x32_bf16 v[64:67], v[212:215], v[158:161], v[64:67]
	v_mfma_f32_16x16x32_bf16 v[52:55], v[204:207], v[180:183], v[52:55]
	v_mfma_f32_16x16x32_bf16 v[48:51], v[212:215], v[180:183], v[48:51]
	v_mfma_f32_16x16x32_bf16 v[44:47], v[204:207], v[188:191], v[44:47]
	v_mfma_f32_16x16x32_bf16 v[40:43], v[212:215], v[188:191], v[40:43]
	v_mfma_f32_16x16x32_bf16 v[36:39], v[204:207], v[196:199], v[36:39]
	v_mfma_f32_16x16x32_bf16 v[32:35], v[212:215], v[196:199], v[32:35]
	v_mfma_f32_16x16x32_bf16 v[68:71], v[208:211], v[162:165], v[68:71]
	v_mfma_f32_16x16x32_bf16 v[64:67], v[216:219], v[162:165], v[64:67]
	v_mfma_f32_16x16x32_bf16 v[52:55], v[208:211], v[184:187], v[52:55]
	v_mfma_f32_16x16x32_bf16 v[48:51], v[216:219], v[184:187], v[48:51]
	v_mfma_f32_16x16x32_bf16 v[44:47], v[208:211], v[192:195], v[44:47]
	v_mfma_f32_16x16x32_bf16 v[40:43], v[216:219], v[192:195], v[40:43]
	v_mfma_f32_16x16x32_bf16 v[36:39], v[208:211], v[200:203], v[36:39]
	v_mfma_f32_16x16x32_bf16 v[32:35], v[216:219], v[200:203], v[32:35]
	s_mov_b32 m0, s31
	v_lshl_add_u64 v[174:175], s[54:55], 0, v[128:129]
	s_barrier
	ds_read_b128 v[158:161], v145 offset:16384
	ds_read_b128 v[162:165], v145 offset:17408
	ds_read_b128 v[180:183], v145 offset:18432
	ds_read_b128 v[184:187], v145 offset:19456
	ds_read_b128 v[188:191], v145 offset:20480
	ds_read_b128 v[192:195], v145 offset:21504
	ds_read_b128 v[196:199], v145 offset:22528
	ds_read_b128 v[200:203], v145 offset:23552
	global_load_lds_dwordx4 v[174:175], off
	v_lshl_add_u64 v[176:177], s[54:55], 0, v[132:133]
	s_mov_b32 m0, s45
	s_nop 0
	global_load_lds_dwordx4 v[176:177], off
	s_barrier
	s_waitcnt lgkmcnt(0)
	v_mfma_f32_16x16x32_bf16 v[92:95], v[140:143], v[158:161], v[92:95]
	v_mfma_f32_16x16x32_bf16 v[88:91], v[150:153], v[158:161], v[88:91]
	v_mfma_f32_16x16x32_bf16 v[84:87], v[140:143], v[180:183], v[84:87]
	v_mfma_f32_16x16x32_bf16 v[80:83], v[150:153], v[180:183], v[80:83]
	v_mfma_f32_16x16x32_bf16 v[76:79], v[140:143], v[188:191], v[76:79]
	v_mfma_f32_16x16x32_bf16 v[72:75], v[150:153], v[188:191], v[72:75]
	v_mfma_f32_16x16x32_bf16 v[60:63], v[140:143], v[196:199], v[60:63]
	v_mfma_f32_16x16x32_bf16 v[56:59], v[150:153], v[196:199], v[56:59]
	v_mfma_f32_16x16x32_bf16 v[92:95], v[146:149], v[162:165], v[92:95]
	v_mfma_f32_16x16x32_bf16 v[88:91], v[154:157], v[162:165], v[88:91]
	v_mfma_f32_16x16x32_bf16 v[84:87], v[146:149], v[184:187], v[84:87]
	v_mfma_f32_16x16x32_bf16 v[80:83], v[154:157], v[184:187], v[80:83]
	v_mfma_f32_16x16x32_bf16 v[76:79], v[146:149], v[192:195], v[76:79]
	v_mfma_f32_16x16x32_bf16 v[72:75], v[154:157], v[192:195], v[72:75]
	v_mfma_f32_16x16x32_bf16 v[60:63], v[146:149], v[200:203], v[60:63]
	v_mfma_f32_16x16x32_bf16 v[56:59], v[154:157], v[200:203], v[56:59]
	s_barrier
	s_add_u32 s36, s52, 0x40000
	s_addc_u32 s37, s53, 0
	s_add_i32 s38, s39, s30
	v_lshl_add_u64 v[140:141], s[36:37], 0, v[130:131]
	s_mov_b32 m0, s38
	s_nop 0
	global_load_lds_dwordx4 v[140:141], off
	v_lshl_add_u64 v[140:141], s[36:37], 0, v[134:135]
	s_add_i32 m0, s38, 0x2000
	s_nop 0
	global_load_lds_dwordx4 v[140:141], off
	s_waitcnt vmcnt(6)
	s_barrier
	v_mfma_f32_16x16x32_bf16 v[28:31], v[204:207], v[158:161], v[28:31]
	v_mfma_f32_16x16x32_bf16 v[24:27], v[212:215], v[158:161], v[24:27]
	v_mfma_f32_16x16x32_bf16 v[20:23], v[204:207], v[180:183], v[20:23]
	v_mfma_f32_16x16x32_bf16 v[16:19], v[212:215], v[180:183], v[16:19]
	v_mfma_f32_16x16x32_bf16 v[12:15], v[204:207], v[188:191], v[12:15]
	v_mfma_f32_16x16x32_bf16 v[8:11], v[212:215], v[188:191], v[8:11]
	v_mfma_f32_16x16x32_bf16 v[4:7], v[204:207], v[196:199], v[4:7]
	v_mfma_f32_16x16x32_bf16 v[0:3], v[212:215], v[196:199], v[0:3]
	v_mfma_f32_16x16x32_bf16 v[28:31], v[208:211], v[162:165], v[28:31]
	v_mfma_f32_16x16x32_bf16 v[24:27], v[216:219], v[162:165], v[24:27]
	v_mfma_f32_16x16x32_bf16 v[20:23], v[208:211], v[184:187], v[20:23]
	v_mfma_f32_16x16x32_bf16 v[16:19], v[216:219], v[184:187], v[16:19]
	v_mfma_f32_16x16x32_bf16 v[12:15], v[208:211], v[192:195], v[12:15]
	v_mfma_f32_16x16x32_bf16 v[8:11], v[216:219], v[192:195], v[8:11]
	v_mfma_f32_16x16x32_bf16 v[4:7], v[208:211], v[200:203], v[4:7]
	v_mfma_f32_16x16x32_bf16 v[0:3], v[216:219], v[200:203], v[0:3]
	s_add_i32 s38, 0, 0x18000
	v_add_u32_e32 v154, s38, v144
	s_barrier
	ds_read_b128 v[140:143], v154
	ds_read_b128 v[146:149], v154 offset:1024
	ds_read_b128 v[150:153], v154 offset:2048
	ds_read_b128 v[154:157], v154 offset:3072
	s_add_u32 s36, s54, 0x40000
	s_addc_u32 s37, s55, 0
	s_mov_b32 m0, s56
	v_lshl_add_u64 v[178:179], s[36:37], 0, v[128:129]
	ds_read_b128 v[158:161], v145 offset:32768
	ds_read_b128 v[162:165], v145 offset:33792
	ds_read_b128 v[180:183], v145 offset:34816
	ds_read_b128 v[184:187], v145 offset:35840
	ds_read_b128 v[188:191], v145 offset:36864
	ds_read_b128 v[192:195], v145 offset:37888
	ds_read_b128 v[196:199], v145 offset:38912
	ds_read_b128 v[200:203], v145 offset:39936
	global_load_lds_dwordx4 v[178:179], off
	v_lshl_add_u64 v[178:179], s[36:37], 0, v[132:133]
	s_mov_b32 m0, s57
	s_nop 0
	global_load_lds_dwordx4 v[178:179], off
	s_waitcnt lgkmcnt(8)
	s_barrier
	s_waitcnt lgkmcnt(0)
	v_mfma_f32_16x16x32_bf16 v[124:127], v[140:143], v[158:161], v[124:127]
	v_mfma_f32_16x16x32_bf16 v[120:123], v[150:153], v[158:161], v[120:123]
	v_mfma_f32_16x16x32_bf16 v[116:119], v[140:143], v[180:183], v[116:119]
	v_mfma_f32_16x16x32_bf16 v[112:115], v[150:153], v[180:183], v[112:115]
	v_mfma_f32_16x16x32_bf16 v[108:111], v[140:143], v[188:191], v[108:111]
	v_mfma_f32_16x16x32_bf16 v[104:107], v[150:153], v[188:191], v[104:107]
	v_mfma_f32_16x16x32_bf16 v[100:103], v[140:143], v[196:199], v[100:103]
	v_mfma_f32_16x16x32_bf16 v[96:99], v[150:153], v[196:199], v[96:99]
	v_mfma_f32_16x16x32_bf16 v[124:127], v[146:149], v[162:165], v[124:127]
	v_mfma_f32_16x16x32_bf16 v[120:123], v[154:157], v[162:165], v[120:123]
	v_mfma_f32_16x16x32_bf16 v[116:119], v[146:149], v[184:187], v[116:119]
	v_mfma_f32_16x16x32_bf16 v[112:115], v[154:157], v[184:187], v[112:115]
	v_mfma_f32_16x16x32_bf16 v[108:111], v[146:149], v[192:195], v[108:111]
	v_mfma_f32_16x16x32_bf16 v[104:107], v[154:157], v[192:195], v[104:107]
	v_mfma_f32_16x16x32_bf16 v[100:103], v[146:149], v[200:203], v[100:103]
	v_mfma_f32_16x16x32_bf16 v[96:99], v[154:157], v[200:203], v[96:99]
	s_barrier
	s_add_i32 s39, 0, 0x1c000
	s_add_i32 s36, s38, s30
	v_add_u32_e32 v168, s39, v144
	v_lshl_add_u64 v[166:167], v[166:167], 0, s[88:89]
	s_mov_b32 m0, s36
	ds_read_b128 v[204:207], v168
	ds_read_b128 v[208:211], v168 offset:1024
	ds_read_b128 v[212:215], v168 offset:2048
	ds_read_b128 v[216:219], v168 offset:3072
	global_load_lds_dwordx4 v[166:167], off
	v_lshl_add_u64 v[166:167], v[172:173], 0, s[88:89]
	s_add_i32 m0, s36, 0x2000
	s_nop 0
	global_load_lds_dwordx4 v[166:167], off
	s_barrier
	s_waitcnt lgkmcnt(0)
	v_mfma_f32_16x16x32_bf16 v[68:71], v[204:207], v[158:161], v[68:71]
	v_mfma_f32_16x16x32_bf16 v[64:67], v[212:215], v[158:161], v[64:67]
	v_mfma_f32_16x16x32_bf16 v[52:55], v[204:207], v[180:183], v[52:55]
	v_mfma_f32_16x16x32_bf16 v[48:51], v[212:215], v[180:183], v[48:51]
	v_mfma_f32_16x16x32_bf16 v[44:47], v[204:207], v[188:191], v[44:47]
	v_mfma_f32_16x16x32_bf16 v[40:43], v[212:215], v[188:191], v[40:43]
	v_mfma_f32_16x16x32_bf16 v[36:39], v[204:207], v[196:199], v[36:39]
	v_mfma_f32_16x16x32_bf16 v[32:35], v[212:215], v[196:199], v[32:35]
	v_mfma_f32_16x16x32_bf16 v[68:71], v[208:211], v[162:165], v[68:71]
	v_mfma_f32_16x16x32_bf16 v[64:67], v[216:219], v[162:165], v[64:67]
	v_mfma_f32_16x16x32_bf16 v[52:55], v[208:211], v[184:187], v[52:55]
	v_mfma_f32_16x16x32_bf16 v[48:51], v[216:219], v[184:187], v[48:51]
	v_mfma_f32_16x16x32_bf16 v[44:47], v[208:211], v[192:195], v[44:47]
	v_mfma_f32_16x16x32_bf16 v[40:43], v[216:219], v[192:195], v[40:43]
	v_mfma_f32_16x16x32_bf16 v[36:39], v[208:211], v[200:203], v[36:39]
	v_mfma_f32_16x16x32_bf16 v[32:35], v[216:219], v[200:203], v[32:35]
	s_mov_b32 m0, s60
	v_lshl_add_u64 v[166:167], v[174:175], 0, s[88:89]
	s_barrier
	ds_read_b128 v[158:161], v145 offset:49152
	ds_read_b128 v[162:165], v145 offset:50176
	ds_read_b128 v[180:183], v145 offset:51200
	ds_read_b128 v[184:187], v145 offset:52224
	ds_read_b128 v[188:191], v145 offset:53248
	ds_read_b128 v[192:195], v145 offset:54272
	ds_read_b128 v[196:199], v145 offset:55296
	ds_read_b128 v[200:203], v145 offset:56320
	global_load_lds_dwordx4 v[166:167], off
	v_lshl_add_u64 v[166:167], v[176:177], 0, s[88:89]
	s_mov_b32 m0, s61
	s_nop 0
	global_load_lds_dwordx4 v[166:167], off
	s_barrier
	s_waitcnt lgkmcnt(0)
	v_mfma_f32_16x16x32_bf16 v[92:95], v[140:143], v[158:161], v[92:95]
	v_mfma_f32_16x16x32_bf16 v[88:91], v[150:153], v[158:161], v[88:91]
	v_mfma_f32_16x16x32_bf16 v[84:87], v[140:143], v[180:183], v[84:87]
	v_mfma_f32_16x16x32_bf16 v[80:83], v[150:153], v[180:183], v[80:83]
	v_mfma_f32_16x16x32_bf16 v[76:79], v[140:143], v[188:191], v[76:79]
	v_mfma_f32_16x16x32_bf16 v[72:75], v[150:153], v[188:191], v[72:75]
	v_mfma_f32_16x16x32_bf16 v[60:63], v[140:143], v[196:199], v[60:63]
	v_mfma_f32_16x16x32_bf16 v[56:59], v[150:153], v[196:199], v[56:59]
	v_mfma_f32_16x16x32_bf16 v[92:95], v[146:149], v[162:165], v[92:95]
	v_mfma_f32_16x16x32_bf16 v[88:91], v[154:157], v[162:165], v[88:91]
	v_mfma_f32_16x16x32_bf16 v[84:87], v[146:149], v[184:187], v[84:87]
	v_mfma_f32_16x16x32_bf16 v[80:83], v[154:157], v[184:187], v[80:83]
	v_mfma_f32_16x16x32_bf16 v[76:79], v[146:149], v[192:195], v[76:79]
	v_mfma_f32_16x16x32_bf16 v[72:75], v[154:157], v[192:195], v[72:75]
	v_mfma_f32_16x16x32_bf16 v[60:63], v[146:149], v[200:203], v[60:63]
	v_mfma_f32_16x16x32_bf16 v[56:59], v[154:157], v[200:203], v[56:59]
	s_barrier
	s_add_u32 s36, s52, 0x40080
	s_addc_u32 s37, s53, 0
	s_add_i32 s38, s39, s30
	v_lshl_add_u64 v[140:141], s[36:37], 0, v[130:131]
	s_mov_b32 m0, s38
	s_nop 0
	global_load_lds_dwordx4 v[140:141], off
	v_lshl_add_u64 v[140:141], s[36:37], 0, v[134:135]
	s_add_i32 m0, s38, 0x2000
	s_nop 0
	global_load_lds_dwordx4 v[140:141], off
	s_waitcnt vmcnt(6)
	s_barrier
	v_mfma_f32_16x16x32_bf16 v[28:31], v[204:207], v[158:161], v[28:31]
	v_mfma_f32_16x16x32_bf16 v[24:27], v[212:215], v[158:161], v[24:27]
	v_mfma_f32_16x16x32_bf16 v[20:23], v[204:207], v[180:183], v[20:23]
	v_mfma_f32_16x16x32_bf16 v[16:19], v[212:215], v[180:183], v[16:19]
	v_mfma_f32_16x16x32_bf16 v[12:15], v[204:207], v[188:191], v[12:15]
	v_mfma_f32_16x16x32_bf16 v[8:11], v[212:215], v[188:191], v[8:11]
	v_mfma_f32_16x16x32_bf16 v[4:7], v[204:207], v[196:199], v[4:7]
	v_mfma_f32_16x16x32_bf16 v[0:3], v[212:215], v[196:199], v[0:3]
	v_mfma_f32_16x16x32_bf16 v[28:31], v[208:211], v[162:165], v[28:31]
	v_mfma_f32_16x16x32_bf16 v[24:27], v[216:219], v[162:165], v[24:27]
	v_mfma_f32_16x16x32_bf16 v[20:23], v[208:211], v[184:187], v[20:23]
	v_mfma_f32_16x16x32_bf16 v[16:19], v[216:219], v[184:187], v[16:19]
	v_mfma_f32_16x16x32_bf16 v[12:15], v[208:211], v[192:195], v[12:15]
	v_mfma_f32_16x16x32_bf16 v[8:11], v[216:219], v[192:195], v[8:11]
	v_mfma_f32_16x16x32_bf16 v[4:7], v[208:211], v[200:203], v[4:7]
	v_mfma_f32_16x16x32_bf16 v[0:3], v[216:219], v[200:203], v[0:3]
	s_add_i32 s49, s49, 2
	s_add_u32 s50, s50, 0x100
	s_addc_u32 s51, s51, 0
	s_add_u32 s34, s34, 0x100
	s_addc_u32 s35, s35, 0
	s_cmp_gt_u32 s49, 13
	s_barrier
	s_cbranch_scc0 .LBB0_264
	v_mov_b32_e32 v141, v171
	s_lshl_b32 s13, s48, 8
	s_or_b32 s13, s13, s59
	v_lshrrev_b32_e32 v140, 1, v141
	s_cmpk_lg_i32 s13, 0x400
	v_and_or_b32 v140, v140, 24, s13
	s_mov_b64 s[48:49], -1
	s_cbranch_scc0 .LBB0_267
	v_add_u32_e32 v142, 0xfffff4d8, v140
	v_add_u32_e32 v143, 0xfffff518, v140
	v_cmp_gt_u32_e32 vcc, 16, v142
	s_movk_i32 s13, 0x720
	s_mov_b64 s[48:49], 0
	v_cndmask_b32_e32 v142, -1, v143, vcc
	v_cmp_ne_u32_e32 vcc, s13, v140
	s_nop 1
	v_cndmask_b32_e32 v168, 32, v142, vcc

.LBB0_631:
	s_ashr_i32 s43, s42, 31
	s_lshl_b64 s[34:35], s[42:43], 17
	v_mov_b64_e32 v[0:1], 0x84
	s_add_u32 s44, s6, s34
	v_cmp_lt_i64_e32 vcc, s[12:13], v[0:1]
	s_addc_u32 s45, s7, s35
	s_and_b64 s[34:35], vcc, exec
	s_cselect_b32 s55, s45, s49
	s_cselect_b32 s54, s44, s48
	s_ashr_i32 s15, s14, 31
	s_lshl_b64 s[34:35], s[14:15], 17
	s_add_u32 s46, s17, s34
	s_addc_u32 s47, s27, s35
	s_and_b64 s[34:35], vcc, exec
	s_cselect_b32 s53, s47, s51
	s_cselect_b32 s52, s46, s50
	s_add_i32 s31, 0, 0x10000
	v_add_u32_e32 v168, s31, v236
	ds_read_b128 v[0:3], v168
	ds_read_b128 v[4:7], v168 offset:1024
	ds_read_b128 v[8:11], v168 offset:2048
	ds_read_b128 v[12:15], v168 offset:3072
	v_mov_b32_e32 v170, 0x3f803f80
	v_mov_b64_e32 v[226:227], 0x200
	s_add_u32 s34, s48, 0x10080
	s_addc_u32 s35, s49, 0
	s_add_i32 s36, s29, 0xc000
	v_lshl_add_u64 v[48:49], s[34:35], 0, v[186:187]
	s_mov_b32 m0, s36
	s_add_i32 s15, s29, 0xe000
	ds_read_b128 v[16:19], v237
	ds_read_b128 v[20:23], v237 offset:1024
	ds_read_b128 v[24:27], v237 offset:2048
	ds_read_b128 v[28:31], v237 offset:3072
	ds_read_b128 v[32:35], v237 offset:4096
	ds_read_b128 v[36:39], v237 offset:5120
	ds_read_b128 v[40:43], v237 offset:6144
	ds_read_b128 v[44:47], v237 offset:7168
	global_load_lds_dwordx4 v[48:49], off
	v_lshl_add_u64 v[48:49], s[34:35], 0, v[182:183]
	s_mov_b32 m0, s15
	s_nop 0
	global_load_lds_dwordx4 v[48:49], off
	s_waitcnt lgkmcnt(8)
	s_barrier
	s_waitcnt lgkmcnt(0)
	v_mfma_f32_16x16x32_bf16 v[48:51], v[0:3], v[16:19], 0
	v_mfma_f32_16x16x32_bf16 v[52:55], v[8:11], v[16:19], 0
	v_mfma_f32_16x16x32_bf16 v[56:59], v[0:3], v[24:27], 0
	v_mfma_f32_16x16x32_bf16 v[60:63], v[8:11], v[24:27], 0
	v_mfma_f32_16x16x32_bf16 v[64:67], v[0:3], v[32:35], 0
	v_mfma_f32_16x16x32_bf16 v[68:71], v[8:11], v[32:35], 0
	v_mfma_f32_16x16x32_bf16 v[72:75], v[0:3], v[40:43], 0
	v_mfma_f32_16x16x32_bf16 v[76:79], v[8:11], v[40:43], 0
	v_mfma_f32_16x16x32_bf16 v[48:51], v[4:7], v[20:23], v[48:51]
	v_mfma_f32_16x16x32_bf16 v[52:55], v[12:15], v[20:23], v[52:55]
	v_mfma_f32_16x16x32_bf16 v[56:59], v[4:7], v[28:31], v[56:59]
	v_mfma_f32_16x16x32_bf16 v[60:63], v[12:15], v[28:31], v[60:63]
	v_mfma_f32_16x16x32_bf16 v[64:67], v[4:7], v[36:39], v[64:67]
	v_mfma_f32_16x16x32_bf16 v[68:71], v[12:15], v[36:39], v[68:71]
	v_mfma_f32_16x16x32_bf16 v[72:75], v[4:7], v[44:47], v[72:75]
	v_mfma_f32_16x16x32_bf16 v[76:79], v[12:15], v[44:47], v[76:79]
	s_barrier
	s_add_i32 s37, 0, 0x14000
	v_lshl_add_u64 v[172:173], s[50:51], 0, v[184:185]
	s_add_i32 s35, s31, s28
	v_add_u32_e32 v212, s37, v236
	v_lshl_add_u64 v[96:97], v[172:173], 0, s[90:91]
	s_mov_b32 m0, s35
	v_lshl_add_u64 v[174:175], s[50:51], 0, v[180:181]
	s_add_i32 s31, s35, 0x2000
	ds_read_b128 v[80:83], v212
	ds_read_b128 v[84:87], v212 offset:1024
	ds_read_b128 v[88:91], v212 offset:2048
	ds_read_b128 v[92:95], v212 offset:3072
	global_load_lds_dwordx4 v[96:97], off
	v_lshl_add_u64 v[96:97], v[174:175], 0, s[90:91]
	s_mov_b32 m0, s31
	s_nop 0
	global_load_lds_dwordx4 v[96:97], off
	s_barrier
	s_waitcnt lgkmcnt(0)
	v_mfma_f32_16x16x32_bf16 v[96:99], v[80:83], v[16:19], 0
	v_mfma_f32_16x16x32_bf16 v[16:19], v[88:91], v[16:19], 0
	v_mfma_f32_16x16x32_bf16 v[96:99], v[84:87], v[20:23], v[96:99]
	v_mfma_f32_16x16x32_bf16 v[16:19], v[92:95], v[20:23], v[16:19]
	v_mfma_f32_16x16x32_bf16 v[20:23], v[80:83], v[24:27], 0
	v_mfma_f32_16x16x32_bf16 v[24:27], v[88:91], v[24:27], 0
	v_mfma_f32_16x16x32_bf16 v[20:23], v[84:87], v[28:31], v[20:23]
	v_mfma_f32_16x16x32_bf16 v[24:27], v[92:95], v[28:31], v[24:27]
	v_mfma_f32_16x16x32_bf16 v[28:31], v[80:83], v[32:35], 0
	v_mfma_f32_16x16x32_bf16 v[32:35], v[88:91], v[32:35], 0
	v_mfma_f32_16x16x32_bf16 v[28:31], v[84:87], v[36:39], v[28:31]
	v_mfma_f32_16x16x32_bf16 v[32:35], v[92:95], v[36:39], v[32:35]
	v_mfma_f32_16x16x32_bf16 v[36:39], v[80:83], v[40:43], 0
	v_mfma_f32_16x16x32_bf16 v[40:43], v[88:91], v[40:43], 0
	v_mfma_f32_16x16x32_bf16 v[36:39], v[84:87], v[44:47], v[36:39]
	v_mfma_f32_16x16x32_bf16 v[40:43], v[92:95], v[44:47], v[40:43]
	v_lshl_add_u64 v[176:177], s[48:49], 0, v[186:187]
	s_mov_b32 m0, s29
	v_lshl_add_u64 v[128:129], v[176:177], 0, s[90:91]
	v_lshl_add_u64 v[178:179], s[48:49], 0, v[182:183]
	s_barrier
	ds_read_b128 v[44:47], v237 offset:16384
	ds_read_b128 v[100:103], v237 offset:17408
	ds_read_b128 v[104:107], v237 offset:18432
	ds_read_b128 v[108:111], v237 offset:19456
	ds_read_b128 v[112:115], v237 offset:20480
	ds_read_b128 v[116:119], v237 offset:21504
	ds_read_b128 v[120:123], v237 offset:22528
	ds_read_b128 v[124:127], v237 offset:23552
	global_load_lds_dwordx4 v[128:129], off
	v_lshl_add_u64 v[128:129], v[178:179], 0, s[90:91]
	s_mov_b32 m0, s56
	s_nop 0
	global_load_lds_dwordx4 v[128:129], off
	s_barrier
	s_waitcnt lgkmcnt(0)
	v_mfma_f32_16x16x32_bf16 v[128:131], v[0:3], v[44:47], 0
	v_mfma_f32_16x16x32_bf16 v[136:139], v[0:3], v[104:107], 0
	v_mfma_f32_16x16x32_bf16 v[144:147], v[0:3], v[112:115], 0
	v_mfma_f32_16x16x32_bf16 v[0:3], v[0:3], v[120:123], 0
	v_mfma_f32_16x16x32_bf16 v[128:131], v[4:7], v[100:103], v[128:131]
	v_mfma_f32_16x16x32_bf16 v[132:135], v[8:11], v[44:47], 0
	v_mfma_f32_16x16x32_bf16 v[136:139], v[4:7], v[108:111], v[136:139]
	v_mfma_f32_16x16x32_bf16 v[140:143], v[8:11], v[104:107], 0
	v_mfma_f32_16x16x32_bf16 v[144:147], v[4:7], v[116:119], v[144:147]
	v_mfma_f32_16x16x32_bf16 v[148:151], v[8:11], v[112:115], 0
	v_mfma_f32_16x16x32_bf16 v[0:3], v[4:7], v[124:127], v[0:3]
	v_mfma_f32_16x16x32_bf16 v[4:7], v[8:11], v[120:123], 0
	v_mfma_f32_16x16x32_bf16 v[132:135], v[12:15], v[100:103], v[132:135]
	v_mfma_f32_16x16x32_bf16 v[140:143], v[12:15], v[108:111], v[140:143]
	v_mfma_f32_16x16x32_bf16 v[148:151], v[12:15], v[116:119], v[148:151]
	v_mfma_f32_16x16x32_bf16 v[4:7], v[12:15], v[124:127], v[4:7]
	s_barrier
	s_add_u32 s38, s50, 0x10100
	s_addc_u32 s39, s51, 0
	s_add_i32 s37, s37, s28
	v_lshl_add_u64 v[8:9], s[38:39], 0, v[184:185]
	s_mov_b32 m0, s37
	s_add_i32 s34, s37, 0x2000
	global_load_lds_dwordx4 v[8:9], off
	v_lshl_add_u64 v[8:9], s[38:39], 0, v[180:181]
	s_mov_b32 m0, s34
	s_nop 0
	global_load_lds_dwordx4 v[8:9], off
	s_waitcnt vmcnt(6)
	s_barrier
	v_mfma_f32_16x16x32_bf16 v[8:11], v[80:83], v[44:47], 0
	v_mfma_f32_16x16x32_bf16 v[12:15], v[88:91], v[44:47], 0
	v_mfma_f32_16x16x32_bf16 v[8:11], v[84:87], v[100:103], v[8:11]
	v_mfma_f32_16x16x32_bf16 v[12:15], v[92:95], v[100:103], v[12:15]
	v_mfma_f32_16x16x32_bf16 v[44:47], v[80:83], v[104:107], 0
	v_mfma_f32_16x16x32_bf16 v[100:103], v[88:91], v[104:107], 0
	v_mfma_f32_16x16x32_bf16 v[104:107], v[80:83], v[112:115], 0
	v_mfma_f32_16x16x32_bf16 v[80:83], v[80:83], v[120:123], 0
	v_mfma_f32_16x16x32_bf16 v[44:47], v[84:87], v[108:111], v[44:47]
	v_mfma_f32_16x16x32_bf16 v[100:103], v[92:95], v[108:111], v[100:103]
	v_mfma_f32_16x16x32_bf16 v[104:107], v[84:87], v[116:119], v[104:107]
	v_mfma_f32_16x16x32_bf16 v[108:111], v[88:91], v[112:115], 0
	v_mfma_f32_16x16x32_bf16 v[80:83], v[84:87], v[124:127], v[80:83]
	v_mfma_f32_16x16x32_bf16 v[84:87], v[88:91], v[120:123], 0
	v_mfma_f32_16x16x32_bf16 v[108:111], v[92:95], v[116:119], v[108:111]
	v_mfma_f32_16x16x32_bf16 v[84:87], v[92:95], v[124:127], v[84:87]
	s_add_i32 s64, 0, 0x18000
	v_add_u32_e32 v222, s64, v236
	s_barrier
	ds_read_b128 v[88:91], v222
	ds_read_b128 v[92:95], v222 offset:1024
	ds_read_b128 v[112:115], v222 offset:2048
	ds_read_b128 v[116:119], v222 offset:3072
	s_add_u32 s38, s48, 0x10100
	s_addc_u32 s39, s49, 0
	s_mov_b32 m0, s57
	v_lshl_add_u64 v[196:197], s[38:39], 0, v[186:187]
	ds_read_b128 v[120:123], v237 offset:32768
	ds_read_b128 v[124:127], v237 offset:33792
	ds_read_b128 v[152:155], v237 offset:34816
	ds_read_b128 v[156:159], v237 offset:35840
	ds_read_b128 v[160:163], v237 offset:36864
	ds_read_b128 v[164:167], v237 offset:37888
	ds_read_b128 v[188:191], v237 offset:38912
	ds_read_b128 v[192:195], v237 offset:39936
	global_load_lds_dwordx4 v[196:197], off
	v_lshl_add_u64 v[196:197], s[38:39], 0, v[182:183]
	s_mov_b32 m0, s58
	s_nop 0
	global_load_lds_dwordx4 v[196:197], off
	s_waitcnt lgkmcnt(8)
	s_barrier
	s_waitcnt lgkmcnt(0)
	v_mfma_f32_16x16x32_bf16 v[48:51], v[88:91], v[120:123], v[48:51]
	v_mfma_f32_16x16x32_bf16 v[52:55], v[112:115], v[120:123], v[52:55]
	v_mfma_f32_16x16x32_bf16 v[56:59], v[88:91], v[152:155], v[56:59]
	v_mfma_f32_16x16x32_bf16 v[60:63], v[112:115], v[152:155], v[60:63]
	v_mfma_f32_16x16x32_bf16 v[64:67], v[88:91], v[160:163], v[64:67]
	v_mfma_f32_16x16x32_bf16 v[68:71], v[112:115], v[160:163], v[68:71]
	v_mfma_f32_16x16x32_bf16 v[72:75], v[88:91], v[188:191], v[72:75]
	v_mfma_f32_16x16x32_bf16 v[76:79], v[112:115], v[188:191], v[76:79]
	v_mfma_f32_16x16x32_bf16 v[48:51], v[92:95], v[124:127], v[48:51]
	v_mfma_f32_16x16x32_bf16 v[52:55], v[116:119], v[124:127], v[52:55]
	v_mfma_f32_16x16x32_bf16 v[56:59], v[92:95], v[156:159], v[56:59]
	v_mfma_f32_16x16x32_bf16 v[60:63], v[116:119], v[156:159], v[60:63]
	v_mfma_f32_16x16x32_bf16 v[64:67], v[92:95], v[164:167], v[64:67]
	v_mfma_f32_16x16x32_bf16 v[68:71], v[116:119], v[164:167], v[68:71]
	v_mfma_f32_16x16x32_bf16 v[72:75], v[92:95], v[192:195], v[72:75]
	v_mfma_f32_16x16x32_bf16 v[76:79], v[116:119], v[192:195], v[76:79]
	s_barrier
	s_add_i32 s65, 0, 0x1c000
	s_add_i32 s64, s64, s28
	v_add_u32_e32 v223, s65, v236
	v_lshl_add_u64 v[172:173], v[172:173], 0, s[94:95]
	s_mov_b32 m0, s64
	s_add_i32 s43, s64, 0x2000
	ds_read_b128 v[196:199], v223
	ds_read_b128 v[200:203], v223 offset:1024
	ds_read_b128 v[204:207], v223 offset:2048
	ds_read_b128 v[208:211], v223 offset:3072
	global_load_lds_dwordx4 v[172:173], off
	v_lshl_add_u64 v[172:173], v[174:175], 0, s[94:95]
	s_mov_b32 m0, s43
	s_nop 0
	global_load_lds_dwordx4 v[172:173], off
	s_barrier
	s_waitcnt lgkmcnt(0)
	v_mfma_f32_16x16x32_bf16 v[96:99], v[196:199], v[120:123], v[96:99]
	v_mfma_f32_16x16x32_bf16 v[16:19], v[204:207], v[120:123], v[16:19]
	v_mfma_f32_16x16x32_bf16 v[20:23], v[196:199], v[152:155], v[20:23]
	v_mfma_f32_16x16x32_bf16 v[24:27], v[204:207], v[152:155], v[24:27]
	v_mfma_f32_16x16x32_bf16 v[28:31], v[196:199], v[160:163], v[28:31]
	v_mfma_f32_16x16x32_bf16 v[32:35], v[204:207], v[160:163], v[32:35]
	v_mfma_f32_16x16x32_bf16 v[36:39], v[196:199], v[188:191], v[36:39]
	v_mfma_f32_16x16x32_bf16 v[40:43], v[204:207], v[188:191], v[40:43]
	v_mfma_f32_16x16x32_bf16 v[96:99], v[200:203], v[124:127], v[96:99]
	v_mfma_f32_16x16x32_bf16 v[16:19], v[208:211], v[124:127], v[16:19]
	v_mfma_f32_16x16x32_bf16 v[20:23], v[200:203], v[156:159], v[20:23]
	v_mfma_f32_16x16x32_bf16 v[24:27], v[208:211], v[156:159], v[24:27]
	v_mfma_f32_16x16x32_bf16 v[28:31], v[200:203], v[164:167], v[28:31]
	v_mfma_f32_16x16x32_bf16 v[32:35], v[208:211], v[164:167], v[32:35]
	v_mfma_f32_16x16x32_bf16 v[36:39], v[200:203], v[192:195], v[36:39]
	v_mfma_f32_16x16x32_bf16 v[40:43], v[208:211], v[192:195], v[40:43]
	s_mov_b32 m0, s61
	v_lshl_add_u64 v[172:173], v[176:177], 0, s[94:95]
	s_barrier
	ds_read_b128 v[120:123], v237 offset:49152
	ds_read_b128 v[124:127], v237 offset:50176
	ds_read_b128 v[152:155], v237 offset:51200
	ds_read_b128 v[156:159], v237 offset:52224
	ds_read_b128 v[160:163], v237 offset:53248
	ds_read_b128 v[164:167], v237 offset:54272
	ds_read_b128 v[188:191], v237 offset:55296
	ds_read_b128 v[192:195], v237 offset:56320
	global_load_lds_dwordx4 v[172:173], off
	v_lshl_add_u64 v[172:173], v[178:179], 0, s[94:95]
	s_mov_b32 m0, s62
	s_nop 0
	global_load_lds_dwordx4 v[172:173], off
	s_barrier
	s_waitcnt lgkmcnt(0)
	v_mfma_f32_16x16x32_bf16 v[128:131], v[88:91], v[120:123], v[128:131]
	v_mfma_f32_16x16x32_bf16 v[132:135], v[112:115], v[120:123], v[132:135]
	v_mfma_f32_16x16x32_bf16 v[136:139], v[88:91], v[152:155], v[136:139]
	v_mfma_f32_16x16x32_bf16 v[140:143], v[112:115], v[152:155], v[140:143]
	v_mfma_f32_16x16x32_bf16 v[144:147], v[88:91], v[160:163], v[144:147]
	v_mfma_f32_16x16x32_bf16 v[148:151], v[112:115], v[160:163], v[148:151]
	v_mfma_f32_16x16x32_bf16 v[0:3], v[88:91], v[188:191], v[0:3]
	v_mfma_f32_16x16x32_bf16 v[4:7], v[112:115], v[188:191], v[4:7]
	v_mfma_f32_16x16x32_bf16 v[128:131], v[92:95], v[124:127], v[128:131]
	v_mfma_f32_16x16x32_bf16 v[132:135], v[116:119], v[124:127], v[132:135]
	v_mfma_f32_16x16x32_bf16 v[136:139], v[92:95], v[156:159], v[136:139]
	v_mfma_f32_16x16x32_bf16 v[140:143], v[116:119], v[156:159], v[140:143]
	v_mfma_f32_16x16x32_bf16 v[144:147], v[92:95], v[164:167], v[144:147]
	v_mfma_f32_16x16x32_bf16 v[148:151], v[116:119], v[164:167], v[148:151]
	v_mfma_f32_16x16x32_bf16 v[0:3], v[92:95], v[192:195], v[0:3]
	v_mfma_f32_16x16x32_bf16 v[4:7], v[116:119], v[192:195], v[4:7]
	s_barrier
	s_add_u32 s38, s50, 0x10180
	s_addc_u32 s39, s51, 0
	s_add_i32 s51, s65, s28
	v_lshl_add_u64 v[88:89], s[38:39], 0, v[184:185]
	s_mov_b32 m0, s51
	s_add_i32 s50, s51, 0x2000
	global_load_lds_dwordx4 v[88:89], off
	v_lshl_add_u64 v[88:89], s[38:39], 0, v[180:181]
	s_mov_b32 m0, s50
	s_nop 0
	global_load_lds_dwordx4 v[88:89], off
	s_waitcnt vmcnt(6)
	s_barrier
	v_mfma_f32_16x16x32_bf16 v[8:11], v[196:199], v[120:123], v[8:11]
	v_mfma_f32_16x16x32_bf16 v[12:15], v[204:207], v[120:123], v[12:15]
	v_mfma_f32_16x16x32_bf16 v[44:47], v[196:199], v[152:155], v[44:47]
	v_mfma_f32_16x16x32_bf16 v[88:91], v[204:207], v[152:155], v[100:103]
	v_mfma_f32_16x16x32_bf16 v[92:95], v[196:199], v[160:163], v[104:107]
	v_mfma_f32_16x16x32_bf16 v[100:103], v[204:207], v[160:163], v[108:111]
	v_mfma_f32_16x16x32_bf16 v[80:83], v[196:199], v[188:191], v[80:83]
	v_mfma_f32_16x16x32_bf16 v[84:87], v[204:207], v[188:191], v[84:87]
	v_mfma_f32_16x16x32_bf16 v[8:11], v[200:203], v[124:127], v[8:11]
	v_mfma_f32_16x16x32_bf16 v[12:15], v[208:211], v[124:127], v[12:15]
	v_mfma_f32_16x16x32_bf16 v[44:47], v[200:203], v[156:159], v[44:47]
	v_mfma_f32_16x16x32_bf16 v[88:91], v[208:211], v[156:159], v[88:91]
	v_mfma_f32_16x16x32_bf16 v[92:95], v[200:203], v[164:167], v[92:95]
	v_mfma_f32_16x16x32_bf16 v[100:103], v[208:211], v[164:167], v[100:103]
	v_mfma_f32_16x16x32_bf16 v[80:83], v[200:203], v[192:195], v[80:83]
	v_mfma_f32_16x16x32_bf16 v[84:87], v[208:211], v[192:195], v[84:87]
	s_barrier
	ds_read_b128 v[104:107], v168
	ds_read_b128 v[108:111], v168 offset:1024
	ds_read_b128 v[112:115], v168 offset:2048
	ds_read_b128 v[116:119], v168 offset:3072
	s_add_u32 s38, s48, 0x10180
	s_addc_u32 s39, s49, 0
	s_mov_b32 m0, s36
	v_lshl_add_u64 v[172:173], s[38:39], 0, v[186:187]
	ds_read_b128 v[120:123], v237
	ds_read_b128 v[124:127], v237 offset:1024
	ds_read_b128 v[152:155], v237 offset:2048
	ds_read_b128 v[156:159], v237 offset:3072
	ds_read_b128 v[160:163], v237 offset:4096
	ds_read_b128 v[164:167], v237 offset:5120
	ds_read_b128 v[188:191], v237 offset:6144
	ds_read_b128 v[192:195], v237 offset:7168
	global_load_lds_dwordx4 v[172:173], off
	v_lshl_add_u64 v[172:173], s[38:39], 0, v[182:183]
	s_mov_b32 m0, s15
	s_nop 0
	global_load_lds_dwordx4 v[172:173], off
	s_waitcnt lgkmcnt(8)
	s_barrier
	s_waitcnt lgkmcnt(0)
	v_mfma_f32_16x16x32_bf16 v[48:51], v[104:107], v[120:123], v[48:51]
	v_mfma_f32_16x16x32_bf16 v[52:55], v[112:115], v[120:123], v[52:55]
	v_mfma_f32_16x16x32_bf16 v[56:59], v[104:107], v[152:155], v[56:59]
	v_mfma_f32_16x16x32_bf16 v[60:63], v[112:115], v[152:155], v[60:63]
	v_mfma_f32_16x16x32_bf16 v[64:67], v[104:107], v[160:163], v[64:67]
	v_mfma_f32_16x16x32_bf16 v[68:71], v[112:115], v[160:163], v[68:71]
	v_mfma_f32_16x16x32_bf16 v[72:75], v[104:107], v[188:191], v[72:75]
	v_mfma_f32_16x16x32_bf16 v[76:79], v[112:115], v[188:191], v[76:79]
	v_mfma_f32_16x16x32_bf16 v[48:51], v[108:111], v[124:127], v[48:51]
	v_mfma_f32_16x16x32_bf16 v[52:55], v[116:119], v[124:127], v[52:55]
	v_mfma_f32_16x16x32_bf16 v[56:59], v[108:111], v[156:159], v[56:59]
	v_mfma_f32_16x16x32_bf16 v[60:63], v[116:119], v[156:159], v[60:63]
	v_mfma_f32_16x16x32_bf16 v[64:67], v[108:111], v[164:167], v[64:67]
	v_mfma_f32_16x16x32_bf16 v[68:71], v[116:119], v[164:167], v[68:71]
	v_mfma_f32_16x16x32_bf16 v[72:75], v[108:111], v[192:195], v[72:75]
	v_mfma_f32_16x16x32_bf16 v[76:79], v[116:119], v[192:195], v[76:79]
	s_barrier
	s_mov_b32 m0, s35
	v_lshl_add_u64 v[172:173], s[52:53], 0, v[184:185]
	ds_read_b128 v[196:199], v212
	ds_read_b128 v[200:203], v212 offset:1024
	ds_read_b128 v[204:207], v212 offset:2048
	ds_read_b128 v[208:211], v212 offset:3072
	global_load_lds_dwordx4 v[172:173], off
	v_lshl_add_u64 v[174:175], s[52:53], 0, v[180:181]
	s_mov_b32 m0, s31
	s_nop 0
	global_load_lds_dwordx4 v[174:175], off
	s_barrier
	s_waitcnt lgkmcnt(0)
	v_mfma_f32_16x16x32_bf16 v[96:99], v[196:199], v[120:123], v[96:99]
	v_mfma_f32_16x16x32_bf16 v[16:19], v[204:207], v[120:123], v[16:19]
	v_mfma_f32_16x16x32_bf16 v[20:23], v[196:199], v[152:155], v[20:23]
	v_mfma_f32_16x16x32_bf16 v[24:27], v[204:207], v[152:155], v[24:27]
	v_mfma_f32_16x16x32_bf16 v[28:31], v[196:199], v[160:163], v[28:31]
	v_mfma_f32_16x16x32_bf16 v[32:35], v[204:207], v[160:163], v[32:35]
	v_mfma_f32_16x16x32_bf16 v[36:39], v[196:199], v[188:191], v[36:39]
	v_mfma_f32_16x16x32_bf16 v[40:43], v[204:207], v[188:191], v[40:43]
	v_mfma_f32_16x16x32_bf16 v[96:99], v[200:203], v[124:127], v[96:99]
	v_mfma_f32_16x16x32_bf16 v[16:19], v[208:211], v[124:127], v[16:19]
	v_mfma_f32_16x16x32_bf16 v[20:23], v[200:203], v[156:159], v[20:23]
	v_mfma_f32_16x16x32_bf16 v[24:27], v[208:211], v[156:159], v[24:27]
	v_mfma_f32_16x16x32_bf16 v[28:31], v[200:203], v[164:167], v[28:31]
	v_mfma_f32_16x16x32_bf16 v[32:35], v[208:211], v[164:167], v[32:35]
	v_mfma_f32_16x16x32_bf16 v[36:39], v[200:203], v[192:195], v[36:39]
	v_mfma_f32_16x16x32_bf16 v[152:155], v[208:211], v[192:195], v[40:43]
	s_mov_b32 m0, s29
	v_lshl_add_u64 v[220:221], s[54:55], 0, v[186:187]
	s_barrier
	ds_read_b128 v[40:43], v237 offset:16384
	ds_read_b128 v[120:123], v237 offset:17408
	ds_read_b128 v[124:127], v237 offset:18432
	ds_read_b128 v[156:159], v237 offset:19456
	ds_read_b128 v[160:163], v237 offset:20480
	ds_read_b128 v[164:167], v237 offset:21504
	ds_read_b128 v[188:191], v237 offset:22528
	ds_read_b128 v[192:195], v237 offset:23552
	global_load_lds_dwordx4 v[220:221], off
	v_lshl_add_u64 v[250:251], s[54:55], 0, v[182:183]
	s_mov_b32 m0, s56
	s_nop 0
	global_load_lds_dwordx4 v[250:251], off
	s_barrier
	s_waitcnt lgkmcnt(0)
	v_mfma_f32_16x16x32_bf16 v[132:135], v[112:115], v[40:43], v[132:135]
	v_mfma_f32_16x16x32_bf16 v[212:215], v[116:119], v[120:123], v[132:135]
	v_mfma_f32_16x16x32_bf16 v[132:135], v[104:107], v[124:127], v[136:139]
	v_mfma_f32_16x16x32_bf16 v[216:219], v[108:111], v[156:159], v[132:135]
	v_mfma_f32_16x16x32_bf16 v[132:135], v[112:115], v[124:127], v[140:143]
	v_mfma_f32_16x16x32_bf16 v[140:143], v[116:119], v[156:159], v[132:135]
	v_mfma_f32_16x16x32_bf16 v[132:135], v[104:107], v[160:163], v[144:147]
	v_mfma_f32_16x16x32_bf16 v[128:131], v[104:107], v[40:43], v[128:131]
	v_mfma_f32_16x16x32_bf16 v[238:241], v[108:111], v[164:167], v[132:135]
	v_mfma_f32_16x16x32_bf16 v[132:135], v[112:115], v[160:163], v[148:151]
	v_mfma_f32_16x16x32_bf16 v[0:3], v[104:107], v[188:191], v[0:3]
	v_mfma_f32_16x16x32_bf16 v[4:7], v[112:115], v[188:191], v[4:7]
	v_mfma_f32_16x16x32_bf16 v[128:131], v[108:111], v[120:123], v[128:131]
	v_mfma_f32_16x16x32_bf16 v[242:245], v[116:119], v[164:167], v[132:135]
	v_mfma_f32_16x16x32_bf16 v[0:3], v[108:111], v[192:195], v[0:3]
	v_mfma_f32_16x16x32_bf16 v[4:7], v[116:119], v[192:195], v[4:7]
	s_barrier
	s_add_u32 s36, s52, 0x10000
	s_mov_b32 m0, s37
	s_addc_u32 s37, s53, 0
	v_lshl_add_u64 v[104:105], s[36:37], 0, v[184:185]
	global_load_lds_dwordx4 v[104:105], off
	v_lshl_add_u64 v[104:105], s[36:37], 0, v[180:181]
	s_mov_b32 m0, s34
	s_nop 0
	global_load_lds_dwordx4 v[104:105], off
	s_waitcnt vmcnt(6)
	s_barrier
	v_mfma_f32_16x16x32_bf16 v[8:11], v[196:199], v[40:43], v[8:11]
	v_mfma_f32_16x16x32_bf16 v[12:15], v[204:207], v[40:43], v[12:15]
	v_mfma_f32_16x16x32_bf16 v[40:43], v[196:199], v[124:127], v[44:47]
	v_mfma_f32_16x16x32_bf16 v[104:107], v[200:203], v[156:159], v[40:43]
	v_mfma_f32_16x16x32_bf16 v[40:43], v[204:207], v[124:127], v[88:91]
	v_mfma_f32_16x16x32_bf16 v[116:119], v[208:211], v[156:159], v[40:43]
	v_mfma_f32_16x16x32_bf16 v[40:43], v[196:199], v[160:163], v[92:95]
	v_mfma_f32_16x16x32_bf16 v[92:95], v[200:203], v[164:167], v[40:43]
	v_mfma_f32_16x16x32_bf16 v[40:43], v[204:207], v[160:163], v[100:103]
	v_mfma_f32_16x16x32_bf16 v[156:159], v[208:211], v[164:167], v[40:43]
	v_mfma_f32_16x16x32_bf16 v[40:43], v[196:199], v[188:191], v[80:83]
	v_mfma_f32_16x16x32_bf16 v[80:83], v[200:203], v[192:195], v[40:43]
	v_mfma_f32_16x16x32_bf16 v[40:43], v[204:207], v[188:191], v[84:87]
	v_mfma_f32_16x16x32_bf16 v[8:11], v[200:203], v[120:123], v[8:11]
	v_mfma_f32_16x16x32_bf16 v[12:15], v[208:211], v[120:123], v[12:15]
	v_mfma_f32_16x16x32_bf16 v[188:191], v[208:211], v[192:195], v[40:43]
	s_barrier
	ds_read_b128 v[192:195], v222
	ds_read_b128 v[196:199], v222 offset:1024
	ds_read_b128 v[200:203], v222 offset:2048
	ds_read_b128 v[204:207], v222 offset:3072
	s_add_u32 s34, s54, 0x10000
	s_addc_u32 s35, s55, 0
	s_mov_b32 m0, s57
	v_lshl_add_u64 v[120:121], s[34:35], 0, v[186:187]
	ds_read_b128 v[40:43], v237 offset:32768
	ds_read_b128 v[44:47], v237 offset:33792
	ds_read_b128 v[84:87], v237 offset:34816
	ds_read_b128 v[88:91], v237 offset:35840
	ds_read_b128 v[100:103], v237 offset:36864
	ds_read_b128 v[108:111], v237 offset:37888
	ds_read_b128 v[112:115], v237 offset:38912
	ds_read_b128 v[208:211], v237 offset:39936
	global_load_lds_dwordx4 v[120:121], off
	v_lshl_add_u64 v[120:121], s[34:35], 0, v[182:183]
	s_mov_b32 m0, s58
	s_nop 0
	global_load_lds_dwordx4 v[120:121], off
	s_waitcnt lgkmcnt(8)
	s_barrier
	s_waitcnt lgkmcnt(0)
	v_mfma_f32_16x16x32_bf16 v[48:51], v[192:195], v[40:43], v[48:51]
	v_mfma_f32_16x16x32_bf16 v[164:167], v[196:199], v[44:47], v[48:51]
	v_mfma_f32_16x16x32_bf16 v[48:51], v[200:203], v[40:43], v[52:55]
	v_mfma_f32_16x16x32_bf16 v[160:163], v[204:207], v[44:47], v[48:51]
	v_mfma_f32_16x16x32_bf16 v[48:51], v[192:195], v[84:87], v[56:59]
	v_mfma_f32_16x16x32_bf16 v[148:151], v[196:199], v[88:91], v[48:51]
	v_mfma_f32_16x16x32_bf16 v[48:51], v[200:203], v[84:87], v[60:63]
	v_mfma_f32_16x16x32_bf16 v[144:147], v[204:207], v[88:91], v[48:51]
	v_mfma_f32_16x16x32_bf16 v[48:51], v[192:195], v[100:103], v[64:67]
	v_mfma_f32_16x16x32_bf16 v[136:139], v[196:199], v[108:111], v[48:51]
	v_mfma_f32_16x16x32_bf16 v[48:51], v[200:203], v[100:103], v[68:71]
	v_mfma_f32_16x16x32_bf16 v[132:135], v[204:207], v[108:111], v[48:51]
	v_mfma_f32_16x16x32_bf16 v[48:51], v[192:195], v[112:115], v[72:75]
	v_mfma_f32_16x16x32_bf16 v[124:127], v[196:199], v[208:211], v[48:51]
	v_mfma_f32_16x16x32_bf16 v[48:51], v[200:203], v[112:115], v[76:79]
	v_mfma_f32_16x16x32_bf16 v[120:123], v[204:207], v[208:211], v[48:51]
	s_barrier
	s_mov_b32 m0, s64
	s_nop 3
	v_lshl_add_u64 v[48:49], v[172:173], 0, s[88:89]
	ds_read_b128 v[72:75], v223
	ds_read_b128 v[76:79], v223 offset:1024
	ds_read_b128 v[246:249], v223 offset:2048
	ds_read_b128 v[222:225], v223 offset:3072
	global_load_lds_dwordx4 v[48:49], off
	v_lshl_add_u64 v[48:49], v[174:175], 0, s[88:89]
	s_mov_b32 m0, s43
	s_nop 0
	global_load_lds_dwordx4 v[48:49], off
	s_barrier
	s_waitcnt lgkmcnt(0)
	v_mfma_f32_16x16x32_bf16 v[16:19], v[246:249], v[40:43], v[16:19]
	v_mfma_f32_16x16x32_bf16 v[56:59], v[222:225], v[44:47], v[16:19]
	v_mfma_f32_16x16x32_bf16 v[16:19], v[72:75], v[84:87], v[20:23]
	v_mfma_f32_16x16x32_bf16 v[48:51], v[72:75], v[40:43], v[96:99]
	v_mfma_f32_16x16x32_bf16 v[52:55], v[76:79], v[88:91], v[16:19]
	v_mfma_f32_16x16x32_bf16 v[16:19], v[246:249], v[84:87], v[24:27]
	v_mfma_f32_16x16x32_bf16 v[60:63], v[76:79], v[44:47], v[48:51]
	v_mfma_f32_16x16x32_bf16 v[48:51], v[222:225], v[88:91], v[16:19]
	v_mfma_f32_16x16x32_bf16 v[16:19], v[72:75], v[100:103], v[28:31]
	v_mfma_f32_16x16x32_bf16 v[44:47], v[76:79], v[108:111], v[16:19]
	v_mfma_f32_16x16x32_bf16 v[16:19], v[246:249], v[100:103], v[32:35]
	v_mfma_f32_16x16x32_bf16 v[40:43], v[222:225], v[108:111], v[16:19]
	v_mfma_f32_16x16x32_bf16 v[16:19], v[72:75], v[112:115], v[36:39]
	v_mfma_f32_16x16x32_bf16 v[36:39], v[76:79], v[208:211], v[16:19]
	v_mfma_f32_16x16x32_bf16 v[16:19], v[246:249], v[112:115], v[152:155]
	v_mfma_f32_16x16x32_bf16 v[32:35], v[222:225], v[208:211], v[16:19]
	s_mov_b32 m0, s61
	v_lshl_add_u64 v[24:25], v[220:221], 0, s[88:89]
	s_barrier
	s_nop 2
	ds_read_b128 v[16:19], v237 offset:49152
	ds_read_b128 v[20:23], v237 offset:50176
	ds_read_b128 v[152:155], v237 offset:51200
	ds_read_b128 v[208:211], v237 offset:52224
	ds_read_b128 v[232:235], v237 offset:53248
	ds_read_b128 v[228:231], v237 offset:54272
	ds_read_b128 v[172:175], v237 offset:55296
	ds_read_b128 v[176:179], v237 offset:56320
	global_load_lds_dwordx4 v[24:25], off
	v_lshl_add_u64 v[24:25], v[250:251], 0, s[88:89]
	s_mov_b32 m0, s62
	s_nop 0
	global_load_lds_dwordx4 v[24:25], off
	s_barrier
	s_waitcnt lgkmcnt(0)
	v_mfma_f32_16x16x32_bf16 v[24:27], v[192:195], v[16:19], v[128:131]
	v_mfma_f32_16x16x32_bf16 v[112:115], v[196:199], v[20:23], v[24:27]
	v_mfma_f32_16x16x32_bf16 v[24:27], v[200:203], v[16:19], v[212:215]
	v_mfma_f32_16x16x32_bf16 v[108:111], v[204:207], v[20:23], v[24:27]
	v_mfma_f32_16x16x32_bf16 v[24:27], v[192:195], v[152:155], v[216:219]
	v_mfma_f32_16x16x32_bf16 v[100:103], v[196:199], v[208:211], v[24:27]
	v_mfma_f32_16x16x32_bf16 v[24:27], v[200:203], v[152:155], v[140:143]
	v_mfma_f32_16x16x32_bf16 v[96:99], v[204:207], v[208:211], v[24:27]
	v_mfma_f32_16x16x32_bf16 v[24:27], v[192:195], v[232:235], v[238:241]
	v_mfma_f32_16x16x32_bf16 v[0:3], v[192:195], v[172:175], v[0:3]
	v_mfma_f32_16x16x32_bf16 v[88:91], v[196:199], v[228:231], v[24:27]
	v_mfma_f32_16x16x32_bf16 v[24:27], v[200:203], v[232:235], v[242:245]
	v_mfma_f32_16x16x32_bf16 v[68:71], v[196:199], v[176:179], v[0:3]
	v_mfma_f32_16x16x32_bf16 v[0:3], v[200:203], v[172:175], v[4:7]
	v_mfma_f32_16x16x32_bf16 v[84:87], v[204:207], v[228:231], v[24:27]
	v_mfma_f32_16x16x32_bf16 v[64:67], v[204:207], v[176:179], v[0:3]
	s_barrier
	s_add_u32 s34, s52, 0x10080
	s_addc_u32 s35, s53, 0
	s_mov_b32 m0, s51
	s_nop 0
	v_lshl_add_u64 v[0:1], s[34:35], 0, v[184:185]
	global_load_lds_dwordx4 v[0:1], off
	v_lshl_add_u64 v[0:1], s[34:35], 0, v[180:181]
	s_mov_b32 m0, s50
	s_nop 0
	global_load_lds_dwordx4 v[0:1], off
	s_waitcnt vmcnt(6)
	s_barrier
	v_mfma_f32_16x16x32_bf16 v[0:3], v[72:75], v[16:19], v[8:11]
	v_mfma_f32_16x16x32_bf16 v[28:31], v[76:79], v[20:23], v[0:3]
	v_mfma_f32_16x16x32_bf16 v[0:3], v[246:249], v[16:19], v[12:15]
	v_mfma_f32_16x16x32_bf16 v[24:27], v[222:225], v[20:23], v[0:3]
	v_mfma_f32_16x16x32_bf16 v[0:3], v[72:75], v[152:155], v[104:107]
	v_mfma_f32_16x16x32_bf16 v[20:23], v[76:79], v[208:211], v[0:3]
	v_mfma_f32_16x16x32_bf16 v[0:3], v[246:249], v[152:155], v[116:119]
	v_mfma_f32_16x16x32_bf16 v[16:19], v[222:225], v[208:211], v[0:3]
	v_mfma_f32_16x16x32_bf16 v[0:3], v[72:75], v[232:235], v[92:95]
	v_mfma_f32_16x16x32_bf16 v[12:15], v[76:79], v[228:231], v[0:3]
	v_mfma_f32_16x16x32_bf16 v[0:3], v[246:249], v[232:235], v[156:159]
	v_mfma_f32_16x16x32_bf16 v[8:11], v[222:225], v[228:231], v[0:3]
	v_mfma_f32_16x16x32_bf16 v[0:3], v[72:75], v[172:175], v[80:83]
	v_mfma_f32_16x16x32_bf16 v[4:7], v[76:79], v[176:179], v[0:3]
	v_mfma_f32_16x16x32_bf16 v[0:3], v[246:249], v[172:175], v[188:191]
	v_mfma_f32_16x16x32_bf16 v[0:3], v[222:225], v[176:179], v[0:3]
	v_mov_b32_e32 v72, v171
	s_lshl_b32 s15, s30, 8
	s_barrier
	s_add_i32 s15, s15, s59
	v_and_or_b32 v218, v72, 15, s15
	v_lshrrev_b32_e32 v72, 1, v72
	v_and_or_b32 v80, v72, 24, s60
	v_lshlrev_b32_e32 v238, 2, v80
	global_load_dwordx4 v[72:75], v238, s[8:9] offset:16
	global_load_dwordx4 v[76:79], v238, s[8:9]
	v_lshlrev_b32_e32 v168, 1, v80
	v_ashrrev_i32_e32 v219, 31, v218
	v_lshl_add_u64 v[80:81], s[6:7], 0, v[168:169]
	v_lshlrev_b64 v[188:189], 9, v[218:219]
	v_lshl_add_u64 v[82:83], v[80:81], 0, v[188:189]
	global_load_dwordx4 v[156:159], v[82:83], off
	v_or_b32_e32 v216, 16, v218
	v_ashrrev_i32_e32 v217, 31, v216
	v_lshlrev_b64 v[190:191], 9, v[216:217]
	v_lshl_add_u64 v[82:83], v[80:81], 0, v[190:191]
	global_load_dwordx4 v[152:155], v[82:83], off
	v_or_b32_e32 v214, 32, v218
	v_ashrrev_i32_e32 v215, 31, v214
	v_lshlrev_b64 v[192:193], 9, v[214:215]
	v_lshl_add_u64 v[82:83], v[80:81], 0, v[192:193]
	global_load_dwordx4 v[140:143], v[82:83], off
	v_or_b32_e32 v212, 48, v218
	v_add_u32_e32 v210, 0x80, v218
	v_ashrrev_i32_e32 v213, 31, v212
	v_ashrrev_i32_e32 v211, 31, v210
	v_lshlrev_b64 v[196:197], 9, v[212:213]
	v_add_u32_e32 v208, 0x90, v218
	v_lshl_add_u64 v[82:83], v[80:81], 0, v[196:197]
	v_lshlrev_b64 v[194:195], 9, v[210:211]
	v_ashrrev_i32_e32 v209, 31, v208
	v_add_u32_e32 v206, 0xa0, v218
	v_add_u32_e32 v204, 0xb0, v218
	global_load_dwordx4 v[128:131], v[82:83], off
	v_lshl_add_u64 v[82:83], v[80:81], 0, v[194:195]
	v_lshlrev_b64 v[198:199], 9, v[208:209]
	v_ashrrev_i32_e32 v207, 31, v206
	v_ashrrev_i32_e32 v205, 31, v204
	global_load_dwordx4 v[116:119], v[82:83], off
	v_lshl_add_u64 v[82:83], v[80:81], 0, v[198:199]
	v_lshlrev_b64 v[200:201], 9, v[206:207]
	v_lshlrev_b64 v[202:203], 9, v[204:205]
	global_load_dwordx4 v[104:107], v[82:83], off
	v_lshl_add_u64 v[82:83], v[80:81], 0, v[200:201]
	v_lshl_add_u64 v[80:81], v[80:81], 0, v[202:203]
	global_load_dwordx4 v[92:95], v[82:83], off
	s_add_i32 s63, s63, s96
	global_load_dwordx4 v[80:83], v[80:81], off
	s_andn2_b64 vcc, exec, s[40:41]
	s_mov_b32 s30, s42
	s_mov_b64 s[50:51], s[46:47]
	s_mov_b64 s[48:49], s[44:45]
	s_mov_b32 s39, 0x83ff
	s_movk_i32 s38, 0x1000
	v_mov_b64_e32 v[240:241], 0x1ff
	s_waitcnt vmcnt(0)
	v_pk_add_f32 v[160:161], v[160:161], v[72:73]
	v_pk_add_f32 v[164:165], v[164:165], v[76:77]
	v_pk_add_f32 v[166:167], v[166:167], v[78:79]
	v_mul_f32_e32 v164, 0xbfb8aa3b, v164
	v_mul_f32_e32 v165, 0xbfb8aa3b, v165
	v_exp_f32_e32 v164, v164
	v_exp_f32_e32 v165, v165
	v_lshlrev_b32_e32 v172, 16, v156
	v_and_b32_e32 v173, 0xffff0000, v156
	v_add_f32_e32 v164, 1.0, v164
	v_add_f32_e32 v165, 1.0, v165
	v_rcp_f32_e32 v164, v164
	v_rcp_f32_e32 v165, v165
	v_mul_f32_e32 v160, 0xbfb8aa3b, v160
	v_mul_f32_e32 v161, 0xbfb8aa3b, v161
	v_exp_f32_e32 v160, v160
	v_pk_mul_f32 v[164:165], v[164:165], v[172:173]
	v_exp_f32_e32 v161, v161
	v_cvt_pk_bf16_f32 v156, v164, v165
	v_mul_f32_e32 v164, 0xbfb8aa3b, v166
	v_mul_f32_e32 v165, 0xbfb8aa3b, v167
	v_exp_f32_e32 v164, v164
	v_exp_f32_e32 v165, v165
	v_add_f32_e32 v160, 1.0, v160
	v_add_f32_e32 v161, 1.0, v161
	v_add_f32_e32 v164, 1.0, v164
	v_add_f32_e32 v165, 1.0, v165
	v_rcp_f32_e32 v164, v164
	v_rcp_f32_e32 v165, v165
	v_rcp_f32_e32 v160, v160
	v_rcp_f32_e32 v161, v161
	v_lshlrev_b32_e32 v166, 16, v157
	v_and_b32_e32 v167, 0xffff0000, v157
	v_pk_mul_f32 v[164:165], v[164:165], v[166:167]
	v_pk_add_f32 v[162:163], v[162:163], v[74:75]
	v_cvt_pk_bf16_f32 v157, v164, v165
	v_lshlrev_b32_e32 v164, 16, v158
	v_and_b32_e32 v165, 0xffff0000, v158
	v_pk_mul_f32 v[160:161], v[160:161], v[164:165]
	v_pk_add_f32 v[148:149], v[148:149], v[76:77]
	v_cvt_pk_bf16_f32 v158, v160, v161
	v_mul_f32_e32 v160, 0xbfb8aa3b, v162
	v_mul_f32_e32 v161, 0xbfb8aa3b, v163
	v_exp_f32_e32 v160, v160
	v_exp_f32_e32 v161, v161
	v_lshlrev_b32_e32 v162, 16, v159
	v_and_b32_e32 v163, 0xffff0000, v159
	v_add_f32_e32 v160, 1.0, v160
	v_add_f32_e32 v161, 1.0, v161
	v_rcp_f32_e32 v160, v160
	v_rcp_f32_e32 v161, v161
	v_pk_add_f32 v[150:151], v[150:151], v[78:79]
	v_pk_add_f32 v[144:145], v[144:145], v[72:73]
	v_pk_add_f32 v[136:137], v[136:137], v[76:77]
	v_pk_mul_f32 v[160:161], v[160:161], v[162:163]
	v_mul_f32_e32 v144, 0xbfb8aa3b, v144
	v_cvt_pk_bf16_f32 v159, v160, v161
	v_lshlrev_b64 v[160:161], 11, v[218:219]
	v_lshl_add_u64 v[160:161], s[10:11], 0, v[160:161]
	v_lshl_add_u64 v[160:161], v[160:161], 0, v[168:169]
	global_store_dwordx4 v[160:161], v[156:159], off offset:1536
	v_mul_f32_e32 v145, 0xbfb8aa3b, v145
	v_exp_f32_e32 v144, v144
	v_pk_add_f32 v[156:157], v[146:147], v[74:75]
	v_mul_f32_e32 v146, 0xbfb8aa3b, v148
	v_mul_f32_e32 v147, 0xbfb8aa3b, v149
	v_exp_f32_e32 v146, v146
	v_exp_f32_e32 v147, v147
	v_lshlrev_b32_e32 v148, 16, v152
	v_and_b32_e32 v149, 0xffff0000, v152
	v_add_f32_e32 v146, 1.0, v146
	v_add_f32_e32 v147, 1.0, v147
	v_rcp_f32_e32 v146, v146
	v_rcp_f32_e32 v147, v147
	v_exp_f32_e32 v145, v145
	v_add_f32_e32 v144, 1.0, v144
	v_rcp_f32_e32 v144, v144
	v_pk_mul_f32 v[146:147], v[146:147], v[148:149]
	v_add_f32_e32 v145, 1.0, v145
	v_cvt_pk_bf16_f32 v146, v146, v147
	v_mul_f32_e32 v147, 0xbfb8aa3b, v150
	v_exp_f32_e32 v147, v147
	v_rcp_f32_e32 v145, v145
	v_lshlrev_b32_e32 v150, 16, v153
	v_pk_add_f32 v[138:139], v[138:139], v[78:79]
	v_add_f32_e32 v147, 1.0, v147
	v_rcp_f32_e32 v148, v147
	v_mul_f32_e32 v147, 0xbfb8aa3b, v151
	v_exp_f32_e32 v147, v147
	v_and_b32_e32 v151, 0xffff0000, v153
	v_pk_add_f32 v[132:133], v[132:133], v[72:73]
	v_pk_add_f32 v[124:125], v[124:125], v[76:77]
	v_add_f32_e32 v147, 1.0, v147
	v_rcp_f32_e32 v149, v147
	v_mul_f32_e32 v132, 0xbfb8aa3b, v132
	v_mul_f32_e32 v133, 0xbfb8aa3b, v133
	v_exp_f32_e32 v132, v132
	v_pk_mul_f32 v[148:149], v[148:149], v[150:151]
	v_lshlrev_b32_e32 v150, 16, v155
	v_cvt_pk_bf16_f32 v147, v148, v149
	v_lshlrev_b32_e32 v148, 16, v154
	v_and_b32_e32 v149, 0xffff0000, v154
	v_pk_mul_f32 v[144:145], v[144:145], v[148:149]
	v_and_b32_e32 v151, 0xffff0000, v155
	v_cvt_pk_bf16_f32 v148, v144, v145
	v_mul_f32_e32 v144, 0xbfb8aa3b, v156
	v_mul_f32_e32 v145, 0xbfb8aa3b, v157
	v_exp_f32_e32 v144, v144
	v_exp_f32_e32 v145, v145
	v_exp_f32_e32 v133, v133
	v_add_f32_e32 v132, 1.0, v132
	v_add_f32_e32 v144, 1.0, v144
	v_add_f32_e32 v145, 1.0, v145
	v_rcp_f32_e32 v144, v144
	v_rcp_f32_e32 v145, v145
	v_add_f32_e32 v133, 1.0, v133
	v_rcp_f32_e32 v132, v132
	v_rcp_f32_e32 v133, v133
	v_pk_mul_f32 v[144:145], v[144:145], v[150:151]
	v_pk_add_f32 v[126:127], v[126:127], v[78:79]
	v_cvt_pk_bf16_f32 v149, v144, v145
	v_lshlrev_b64 v[144:145], 11, v[216:217]
	v_lshl_add_u64 v[144:145], s[10:11], 0, v[144:145]
	v_lshl_add_u64 v[144:145], v[144:145], 0, v[168:169]
	global_store_dwordx4 v[144:145], v[146:149], off offset:1536
	v_pk_add_f32 v[120:121], v[120:121], v[72:73]
	v_pk_add_f32 v[112:113], v[112:113], v[76:77]
	v_pk_add_f32 v[146:147], v[134:135], v[74:75]
	v_mul_f32_e32 v134, 0xbfb8aa3b, v136
	v_mul_f32_e32 v135, 0xbfb8aa3b, v137
	v_exp_f32_e32 v134, v134
	v_exp_f32_e32 v135, v135
	v_lshlrev_b32_e32 v136, 16, v140
	v_and_b32_e32 v137, 0xffff0000, v140
	v_add_f32_e32 v134, 1.0, v134
	v_add_f32_e32 v135, 1.0, v135
	v_rcp_f32_e32 v134, v134
	v_rcp_f32_e32 v135, v135
	v_mul_f32_e32 v120, 0xbfb8aa3b, v120
	v_mul_f32_e32 v121, 0xbfb8aa3b, v121
	v_exp_f32_e32 v120, v120
	v_pk_mul_f32 v[134:135], v[134:135], v[136:137]
	v_exp_f32_e32 v121, v121
	v_cvt_pk_bf16_f32 v134, v134, v135
	v_mul_f32_e32 v135, 0xbfb8aa3b, v138
	v_exp_f32_e32 v135, v135
	v_lshlrev_b32_e32 v138, 16, v141
	v_add_f32_e32 v120, 1.0, v120
	v_add_f32_e32 v121, 1.0, v121
	v_add_f32_e32 v135, 1.0, v135
	v_rcp_f32_e32 v136, v135
	v_mul_f32_e32 v135, 0xbfb8aa3b, v139
	v_exp_f32_e32 v135, v135
	v_and_b32_e32 v139, 0xffff0000, v141
	v_rcp_f32_e32 v120, v120
	v_rcp_f32_e32 v121, v121
	v_add_f32_e32 v135, 1.0, v135
	v_rcp_f32_e32 v137, v135
	v_pk_add_f32 v[114:115], v[114:115], v[78:79]
	v_pk_add_f32 v[108:109], v[108:109], v[72:73]
	v_pk_add_f32 v[100:101], v[100:101], v[76:77]
	v_pk_mul_f32 v[136:137], v[136:137], v[138:139]
	v_lshlrev_b32_e32 v138, 16, v143
	v_cvt_pk_bf16_f32 v135, v136, v137
	v_lshlrev_b32_e32 v136, 16, v142
	v_and_b32_e32 v137, 0xffff0000, v142
	v_pk_mul_f32 v[132:133], v[132:133], v[136:137]
	v_and_b32_e32 v139, 0xffff0000, v143
	v_cvt_pk_bf16_f32 v136, v132, v133
	v_mul_f32_e32 v132, 0xbfb8aa3b, v146
	v_mul_f32_e32 v133, 0xbfb8aa3b, v147
	v_exp_f32_e32 v132, v132
	v_exp_f32_e32 v133, v133
	v_mul_f32_e32 v108, 0xbfb8aa3b, v108
	v_mul_f32_e32 v109, 0xbfb8aa3b, v109
	v_add_f32_e32 v132, 1.0, v132
	v_add_f32_e32 v133, 1.0, v133
	v_rcp_f32_e32 v132, v132
	v_rcp_f32_e32 v133, v133
	v_exp_f32_e32 v108, v108
	v_exp_f32_e32 v109, v109
	v_pk_add_f32 v[102:103], v[102:103], v[78:79]
	v_pk_mul_f32 v[132:133], v[132:133], v[138:139]
	v_add_f32_e32 v108, 1.0, v108
	v_cvt_pk_bf16_f32 v137, v132, v133
	v_lshlrev_b64 v[132:133], 11, v[214:215]
	v_lshl_add_u64 v[132:133], s[10:11], 0, v[132:133]
	v_lshl_add_u64 v[132:133], v[132:133], 0, v[168:169]
	global_store_dwordx4 v[132:133], v[134:137], off offset:1536
	v_add_f32_e32 v109, 1.0, v109
	v_rcp_f32_e32 v108, v108
	v_pk_add_f32 v[134:135], v[122:123], v[74:75]
	v_mul_f32_e32 v122, 0xbfb8aa3b, v124
	v_mul_f32_e32 v123, 0xbfb8aa3b, v125
	v_exp_f32_e32 v122, v122
	v_exp_f32_e32 v123, v123
	v_lshlrev_b32_e32 v124, 16, v128
	v_and_b32_e32 v125, 0xffff0000, v128
	v_add_f32_e32 v122, 1.0, v122
	v_add_f32_e32 v123, 1.0, v123
	v_rcp_f32_e32 v122, v122
	v_rcp_f32_e32 v123, v123
	v_rcp_f32_e32 v109, v109
	v_pk_add_f32 v[88:89], v[88:89], v[76:77]
	v_pk_add_f32 v[68:69], v[68:69], v[76:77]
	v_pk_mul_f32 v[122:123], v[122:123], v[124:125]
	v_pk_add_f32 v[90:91], v[90:91], v[78:79]
	v_cvt_pk_bf16_f32 v122, v122, v123
	v_mul_f32_e32 v123, 0xbfb8aa3b, v126
	v_exp_f32_e32 v123, v123
	v_lshlrev_b32_e32 v126, 16, v129
	v_pk_add_f32 v[70:71], v[70:71], v[78:79]
	v_add_f32_e32 v123, 1.0, v123
	v_rcp_f32_e32 v124, v123
	v_mul_f32_e32 v123, 0xbfb8aa3b, v127
	v_exp_f32_e32 v123, v123
	v_and_b32_e32 v127, 0xffff0000, v129
	v_add_f32_e32 v123, 1.0, v123
	v_rcp_f32_e32 v125, v123
	s_nop 0
	v_pk_mul_f32 v[124:125], v[124:125], v[126:127]
	s_nop 0
	v_cvt_pk_bf16_f32 v123, v124, v125
	v_lshlrev_b32_e32 v124, 16, v130
	v_and_b32_e32 v125, 0xffff0000, v130
	v_pk_mul_f32 v[120:121], v[120:121], v[124:125]
	v_lshlrev_b32_e32 v126, 16, v131
	v_cvt_pk_bf16_f32 v124, v120, v121
	v_mul_f32_e32 v120, 0xbfb8aa3b, v134
	v_mul_f32_e32 v121, 0xbfb8aa3b, v135
	v_exp_f32_e32 v120, v120
	v_exp_f32_e32 v121, v121
	v_and_b32_e32 v127, 0xffff0000, v131
	v_add_f32_e32 v120, 1.0, v120
	v_add_f32_e32 v121, 1.0, v121
	v_rcp_f32_e32 v120, v120
	v_rcp_f32_e32 v121, v121
	s_nop 0
	v_pk_mul_f32 v[120:121], v[120:121], v[126:127]
	s_nop 0
	v_cvt_pk_bf16_f32 v125, v120, v121
	v_lshlrev_b64 v[120:121], 11, v[212:213]
	v_lshl_add_u64 v[120:121], s[10:11], 0, v[120:121]
	v_lshl_add_u64 v[120:121], v[120:121], 0, v[168:169]
	global_store_dwordx4 v[120:121], v[122:125], off offset:1536
	s_nop 1
	v_pk_add_f32 v[122:123], v[110:111], v[74:75]
	v_mul_f32_e32 v110, 0xbfb8aa3b, v112
	v_mul_f32_e32 v111, 0xbfb8aa3b, v113
	v_exp_f32_e32 v110, v110
	v_exp_f32_e32 v111, v111
	v_lshlrev_b32_e32 v112, 16, v116
	v_and_b32_e32 v113, 0xffff0000, v116
	v_add_f32_e32 v110, 1.0, v110
	v_add_f32_e32 v111, 1.0, v111
	v_rcp_f32_e32 v110, v110
	v_rcp_f32_e32 v111, v111
	s_nop 0
	v_pk_mul_f32 v[110:111], v[110:111], v[112:113]
	s_nop 0
	v_cvt_pk_bf16_f32 v110, v110, v111
	v_mul_f32_e32 v111, 0xbfb8aa3b, v114
	v_exp_f32_e32 v111, v111
	v_lshlrev_b32_e32 v114, 16, v117
	v_add_f32_e32 v111, 1.0, v111
	v_rcp_f32_e32 v112, v111
	v_mul_f32_e32 v111, 0xbfb8aa3b, v115
	v_exp_f32_e32 v111, v111
	v_and_b32_e32 v115, 0xffff0000, v117
	v_add_f32_e32 v111, 1.0, v111
	v_rcp_f32_e32 v113, v111
	s_nop 0
	v_pk_mul_f32 v[112:113], v[112:113], v[114:115]
	s_nop 0
	v_cvt_pk_bf16_f32 v111, v112, v113
	v_lshlrev_b32_e32 v112, 16, v118
	v_and_b32_e32 v113, 0xffff0000, v118
	v_pk_mul_f32 v[108:109], v[108:109], v[112:113]
	v_lshlrev_b32_e32 v114, 16, v119
	v_cvt_pk_bf16_f32 v112, v108, v109
	v_mul_f32_e32 v108, 0xbfb8aa3b, v122
	v_mul_f32_e32 v109, 0xbfb8aa3b, v123
	v_exp_f32_e32 v108, v108
	v_exp_f32_e32 v109, v109
	v_and_b32_e32 v115, 0xffff0000, v119
	v_add_f32_e32 v108, 1.0, v108
	v_add_f32_e32 v109, 1.0, v109
	v_rcp_f32_e32 v108, v108
	v_rcp_f32_e32 v109, v109
	s_nop 0
	v_pk_mul_f32 v[108:109], v[108:109], v[114:115]
	s_nop 0
	v_cvt_pk_bf16_f32 v113, v108, v109
	v_lshlrev_b64 v[108:109], 11, v[210:211]
	v_lshl_add_u64 v[108:109], s[10:11], 0, v[108:109]
	v_lshl_add_u64 v[108:109], v[108:109], 0, v[168:169]
	global_store_dwordx4 v[108:109], v[110:113], off offset:1536
	s_nop 1
	v_pk_add_f32 v[110:111], v[98:99], v[74:75]
	v_pk_add_f32 v[98:99], v[96:97], v[72:73]
	v_mul_f32_e32 v96, 0xbfb8aa3b, v100
	v_mul_f32_e32 v97, 0xbfb8aa3b, v101
	v_exp_f32_e32 v96, v96
	v_exp_f32_e32 v97, v97
	v_lshlrev_b32_e32 v100, 16, v104
	v_and_b32_e32 v101, 0xffff0000, v104
	v_add_f32_e32 v96, 1.0, v96
	v_add_f32_e32 v97, 1.0, v97
	v_rcp_f32_e32 v96, v96
	v_rcp_f32_e32 v97, v97
	v_mul_f32_e32 v98, 0xbfb8aa3b, v98
	v_mul_f32_e32 v99, 0xbfb8aa3b, v99
	v_exp_f32_e32 v98, v98
	v_pk_mul_f32 v[96:97], v[96:97], v[100:101]
	v_exp_f32_e32 v99, v99
	v_cvt_pk_bf16_f32 v96, v96, v97
	v_mul_f32_e32 v97, 0xbfb8aa3b, v102
	v_exp_f32_e32 v97, v97
	v_add_f32_e32 v98, 1.0, v98
	v_add_f32_e32 v99, 1.0, v99
	v_rcp_f32_e32 v98, v98
	v_add_f32_e32 v97, 1.0, v97
	v_rcp_f32_e32 v100, v97
	v_mul_f32_e32 v97, 0xbfb8aa3b, v103
	v_exp_f32_e32 v97, v97
	v_rcp_f32_e32 v99, v99
	v_lshlrev_b32_e32 v102, 16, v105
	v_and_b32_e32 v103, 0xffff0000, v105
	v_add_f32_e32 v97, 1.0, v97
	v_rcp_f32_e32 v101, v97
	s_nop 0
	v_pk_mul_f32 v[100:101], v[100:101], v[102:103]
	s_nop 0
	v_cvt_pk_bf16_f32 v97, v100, v101
	v_lshlrev_b32_e32 v100, 16, v106
	v_and_b32_e32 v101, 0xffff0000, v106
	v_pk_mul_f32 v[98:99], v[98:99], v[100:101]
	v_lshlrev_b32_e32 v102, 16, v107
	v_cvt_pk_bf16_f32 v98, v98, v99
	v_mul_f32_e32 v99, 0xbfb8aa3b, v110
	v_exp_f32_e32 v99, v99
	v_and_b32_e32 v103, 0xffff0000, v107
	v_add_f32_e32 v99, 1.0, v99
	v_rcp_f32_e32 v100, v99
	v_mul_f32_e32 v99, 0xbfb8aa3b, v111
	v_exp_f32_e32 v99, v99
	s_nop 0
	v_add_f32_e32 v99, 1.0, v99
	v_rcp_f32_e32 v101, v99
	s_nop 0
	v_pk_mul_f32 v[100:101], v[100:101], v[102:103]
	s_nop 0
	v_cvt_pk_bf16_f32 v99, v100, v101
	v_lshlrev_b64 v[100:101], 11, v[208:209]
	v_lshl_add_u64 v[100:101], s[10:11], 0, v[100:101]
	v_lshl_add_u64 v[100:101], v[100:101], 0, v[168:169]
	global_store_dwordx4 v[100:101], v[96:99], off offset:1536
	s_nop 1
	v_pk_add_f32 v[96:97], v[86:87], v[74:75]
	v_pk_add_f32 v[86:87], v[84:85], v[72:73]
	v_mul_f32_e32 v84, 0xbfb8aa3b, v88
	v_mul_f32_e32 v85, 0xbfb8aa3b, v89
	v_pk_add_f32 v[74:75], v[66:67], v[74:75]
	v_pk_add_f32 v[66:67], v[64:65], v[72:73]
	v_mul_f32_e32 v64, 0xbfb8aa3b, v68
	v_mul_f32_e32 v65, 0xbfb8aa3b, v69
	v_exp_f32_e32 v84, v84
	v_exp_f32_e32 v85, v85
	v_exp_f32_e32 v64, v64
	v_exp_f32_e32 v65, v65
	v_add_f32_e32 v84, 1.0, v84
	v_add_f32_e32 v85, 1.0, v85
	v_add_f32_e32 v64, 1.0, v64
	v_add_f32_e32 v65, 1.0, v65
	v_rcp_f32_e32 v84, v84
	v_rcp_f32_e32 v85, v85
	v_rcp_f32_e32 v64, v64
	v_rcp_f32_e32 v65, v65
	v_lshlrev_b32_e32 v88, 16, v92
	v_and_b32_e32 v89, 0xffff0000, v92
	v_lshlrev_b32_e32 v68, 16, v80
	v_and_b32_e32 v69, 0xffff0000, v80
	v_pk_mul_f32 v[84:85], v[84:85], v[88:89]
	v_pk_mul_f32 v[64:65], v[64:65], v[68:69]
	v_cvt_pk_bf16_f32 v84, v84, v85
	v_mul_f32_e32 v85, 0xbfb8aa3b, v90
	v_cvt_pk_bf16_f32 v64, v64, v65
	v_mul_f32_e32 v65, 0xbfb8aa3b, v70
	v_exp_f32_e32 v85, v85
	v_exp_f32_e32 v65, v65
	v_mul_f32_e32 v86, 0xbfb8aa3b, v86
	v_mul_f32_e32 v87, 0xbfb8aa3b, v87
	v_add_f32_e32 v85, 1.0, v85
	v_add_f32_e32 v65, 1.0, v65
	v_rcp_f32_e32 v88, v85
	v_mul_f32_e32 v85, 0xbfb8aa3b, v91
	v_rcp_f32_e32 v68, v65
	v_mul_f32_e32 v65, 0xbfb8aa3b, v71
	v_exp_f32_e32 v85, v85
	v_exp_f32_e32 v65, v65
	v_mul_f32_e32 v66, 0xbfb8aa3b, v66
	v_mul_f32_e32 v67, 0xbfb8aa3b, v67
	v_exp_f32_e32 v86, v86
	v_exp_f32_e32 v87, v87
	v_exp_f32_e32 v66, v66
	v_exp_f32_e32 v67, v67
	v_add_f32_e32 v85, 1.0, v85
	v_add_f32_e32 v65, 1.0, v65
	v_rcp_f32_e32 v89, v85
	v_rcp_f32_e32 v69, v65
	v_add_f32_e32 v86, 1.0, v86
	v_add_f32_e32 v87, 1.0, v87
	v_add_f32_e32 v66, 1.0, v66
	v_add_f32_e32 v67, 1.0, v67
	v_rcp_f32_e32 v86, v86
	v_rcp_f32_e32 v87, v87
	v_rcp_f32_e32 v66, v66
	v_rcp_f32_e32 v67, v67
	v_lshlrev_b32_e32 v90, 16, v93
	v_and_b32_e32 v91, 0xffff0000, v93
	v_lshlrev_b32_e32 v70, 16, v81
	v_and_b32_e32 v71, 0xffff0000, v81
	v_pk_mul_f32 v[88:89], v[88:89], v[90:91]
	v_pk_mul_f32 v[68:69], v[68:69], v[70:71]
	v_cvt_pk_bf16_f32 v85, v88, v89
	v_lshlrev_b32_e32 v88, 16, v94
	v_and_b32_e32 v89, 0xffff0000, v94
	v_cvt_pk_bf16_f32 v65, v68, v69
	v_lshlrev_b32_e32 v68, 16, v82
	v_and_b32_e32 v69, 0xffff0000, v82
	v_pk_mul_f32 v[86:87], v[86:87], v[88:89]
	v_pk_mul_f32 v[66:67], v[66:67], v[68:69]
	v_cvt_pk_bf16_f32 v86, v86, v87
	v_mul_f32_e32 v87, 0xbfb8aa3b, v96
	v_cvt_pk_bf16_f32 v66, v66, v67
	v_mul_f32_e32 v67, 0xbfb8aa3b, v74
	v_exp_f32_e32 v87, v87
	v_exp_f32_e32 v67, v67
	v_lshlrev_b32_e32 v90, 16, v95
	v_and_b32_e32 v91, 0xffff0000, v95
	v_add_f32_e32 v87, 1.0, v87
	v_add_f32_e32 v67, 1.0, v67
	v_rcp_f32_e32 v88, v87
	v_mul_f32_e32 v87, 0xbfb8aa3b, v97
	v_rcp_f32_e32 v68, v67
	v_mul_f32_e32 v67, 0xbfb8aa3b, v75
	v_exp_f32_e32 v87, v87
	v_exp_f32_e32 v67, v67
	v_lshlrev_b32_e32 v70, 16, v83
	v_and_b32_e32 v71, 0xffff0000, v83
	v_add_f32_e32 v87, 1.0, v87
	v_add_f32_e32 v67, 1.0, v67
	v_rcp_f32_e32 v89, v87
	v_rcp_f32_e32 v69, v67
	v_pk_mul_f32 v[88:89], v[88:89], v[90:91]
	v_pk_mul_f32 v[68:69], v[68:69], v[70:71]
	v_cvt_pk_bf16_f32 v87, v88, v89
	v_lshlrev_b64 v[88:89], 11, v[206:207]
	v_cvt_pk_bf16_f32 v67, v68, v69
	v_lshlrev_b64 v[68:69], 11, v[204:205]
	v_lshl_add_u64 v[88:89], s[10:11], 0, v[88:89]
	v_lshl_add_u64 v[68:69], s[10:11], 0, v[68:69]
	v_lshl_add_u64 v[102:103], v[88:89], 0, v[168:169]
	v_lshl_add_u64 v[104:105], v[68:69], 0, v[168:169]
	global_store_dwordx4 v[102:103], v[84:87], off offset:1536
	global_store_dwordx4 v[104:105], v[64:67], off offset:1536
	global_load_dwordx4 v[68:71], v238, s[8:9] offset:528
	global_load_dwordx4 v[72:75], v238, s[8:9] offset:512
	v_lshl_add_u64 v[64:65], s[6:7], 0, v[188:189]
	v_or_b32_e32 v168, 0x100, v168
	v_lshl_add_u64 v[64:65], v[64:65], 0, v[168:169]
	global_load_dwordx4 v[110:113], v[64:65], off
	v_lshl_add_u64 v[64:65], s[6:7], 0, v[190:191]
	v_lshl_add_u64 v[64:65], v[64:65], 0, v[168:169]
	global_load_dwordx4 v[96:99], v[64:65], off
	v_lshl_add_u64 v[64:65], s[6:7], 0, v[192:193]
	v_lshl_add_u64 v[64:65], v[64:65], 0, v[168:169]
	global_load_dwordx4 v[92:95], v[64:65], off
	v_lshl_add_u64 v[64:65], s[6:7], 0, v[196:197]
	v_lshl_add_u64 v[64:65], v[64:65], 0, v[168:169]
	global_load_dwordx4 v[88:91], v[64:65], off
	v_lshl_add_u64 v[64:65], s[6:7], 0, v[194:195]
	v_lshl_add_u64 v[64:65], v[64:65], 0, v[168:169]
	global_load_dwordx4 v[84:87], v[64:65], off
	v_lshl_add_u64 v[64:65], s[6:7], 0, v[198:199]
	v_lshl_add_u64 v[64:65], v[64:65], 0, v[168:169]
	global_load_dwordx4 v[80:83], v[64:65], off
	v_lshl_add_u64 v[64:65], s[6:7], 0, v[200:201]
	v_lshl_add_u64 v[64:65], v[64:65], 0, v[168:169]
	global_load_dwordx4 v[76:79], v[64:65], off
	v_lshl_add_u64 v[64:65], s[6:7], 0, v[202:203]
	v_lshl_add_u64 v[64:65], v[64:65], 0, v[168:169]
	global_load_dwordx4 v[64:67], v[64:65], off
	v_mov_b64_e32 v[238:239], v[226:227]
	v_mov_b32_e32 v227, v170
	v_mov_b32_e32 v170, 0x358637bd
	s_waitcnt vmcnt(0)
	v_pk_add_f32 v[106:107], v[58:59], v[70:71]
	v_pk_add_f32 v[60:61], v[60:61], v[72:73]
	v_pk_add_f32 v[58:59], v[56:57], v[68:69]
	v_mul_f32_e32 v56, 0xbfb8aa3b, v60
	v_mul_f32_e32 v57, 0xbfb8aa3b, v61
	v_exp_f32_e32 v56, v56
	v_exp_f32_e32 v57, v57
	v_lshlrev_b32_e32 v60, 16, v110
	v_and_b32_e32 v61, 0xffff0000, v110
	v_add_f32_e32 v56, 1.0, v56
	v_add_f32_e32 v57, 1.0, v57
	v_rcp_f32_e32 v56, v56
	v_rcp_f32_e32 v57, v57
	v_pk_add_f32 v[62:63], v[62:63], v[74:75]
	v_mul_f32_e32 v58, 0xbfb8aa3b, v58
	v_mul_f32_e32 v59, 0xbfb8aa3b, v59
	v_pk_mul_f32 v[56:57], v[56:57], v[60:61]
	v_exp_f32_e32 v58, v58
	v_cvt_pk_bf16_f32 v56, v56, v57
	v_mul_f32_e32 v57, 0xbfb8aa3b, v62
	v_exp_f32_e32 v57, v57
	v_exp_f32_e32 v59, v59
	v_add_f32_e32 v58, 1.0, v58
	v_rcp_f32_e32 v58, v58
	v_add_f32_e32 v57, 1.0, v57
	v_rcp_f32_e32 v60, v57
	v_mul_f32_e32 v57, 0xbfb8aa3b, v63
	v_exp_f32_e32 v57, v57
	v_add_f32_e32 v59, 1.0, v59
	v_rcp_f32_e32 v59, v59
	v_lshlrev_b32_e32 v62, 16, v111
	v_add_f32_e32 v57, 1.0, v57
	v_rcp_f32_e32 v61, v57
	v_and_b32_e32 v63, 0xffff0000, v111
	v_pk_add_f32 v[52:53], v[52:53], v[72:73]
	v_pk_add_f32 v[54:55], v[54:55], v[74:75]
	v_pk_mul_f32 v[60:61], v[60:61], v[62:63]
	v_lshlrev_b32_e32 v62, 16, v113
	v_cvt_pk_bf16_f32 v57, v60, v61
	v_lshlrev_b32_e32 v60, 16, v112
	v_and_b32_e32 v61, 0xffff0000, v112
	v_pk_mul_f32 v[58:59], v[58:59], v[60:61]
	v_and_b32_e32 v63, 0xffff0000, v113
	v_cvt_pk_bf16_f32 v58, v58, v59
	v_mul_f32_e32 v59, 0xbfb8aa3b, v106
	v_exp_f32_e32 v59, v59
	v_pk_add_f32 v[44:45], v[44:45], v[72:73]
	v_pk_add_f32 v[46:47], v[46:47], v[74:75]
	v_pk_add_f32 v[36:37], v[36:37], v[72:73]
	v_add_f32_e32 v59, 1.0, v59
	v_rcp_f32_e32 v60, v59
	v_mul_f32_e32 v59, 0xbfb8aa3b, v107
	v_exp_f32_e32 v59, v59
	v_pk_add_f32 v[38:39], v[38:39], v[74:75]
	v_pk_add_f32 v[28:29], v[28:29], v[72:73]
	v_pk_add_f32 v[30:31], v[30:31], v[74:75]
	v_add_f32_e32 v59, 1.0, v59
	v_rcp_f32_e32 v61, v59
	v_pk_add_f32 v[20:21], v[20:21], v[72:73]
	v_pk_add_f32 v[22:23], v[22:23], v[74:75]
	v_pk_add_f32 v[12:13], v[12:13], v[72:73]
	v_pk_mul_f32 v[60:61], v[60:61], v[62:63]
	v_pk_add_f32 v[14:15], v[14:15], v[74:75]
	v_cvt_pk_bf16_f32 v59, v60, v61
	global_store_dwordx4 v[160:161], v[56:59], off offset:1792
	v_pk_add_f32 v[4:5], v[4:5], v[72:73]
	v_pk_add_f32 v[6:7], v[6:7], v[74:75]
	v_pk_add_f32 v[56:57], v[50:51], v[70:71]
	v_pk_add_f32 v[50:51], v[48:49], v[68:69]
	v_mul_f32_e32 v48, 0xbfb8aa3b, v52
	v_mul_f32_e32 v49, 0xbfb8aa3b, v53
	v_exp_f32_e32 v48, v48
	v_exp_f32_e32 v49, v49
	v_lshlrev_b32_e32 v52, 16, v96
	v_and_b32_e32 v53, 0xffff0000, v96
	v_add_f32_e32 v48, 1.0, v48
	v_add_f32_e32 v49, 1.0, v49
	v_rcp_f32_e32 v48, v48
	v_rcp_f32_e32 v49, v49
	v_mul_f32_e32 v50, 0xbfb8aa3b, v50
	v_mul_f32_e32 v51, 0xbfb8aa3b, v51
	v_exp_f32_e32 v50, v50
	v_pk_mul_f32 v[48:49], v[48:49], v[52:53]
	v_exp_f32_e32 v51, v51
	v_cvt_pk_bf16_f32 v48, v48, v49
	v_mul_f32_e32 v49, 0xbfb8aa3b, v54
	v_exp_f32_e32 v49, v49
	v_add_f32_e32 v50, 1.0, v50
	v_add_f32_e32 v51, 1.0, v51
	v_rcp_f32_e32 v50, v50
	v_add_f32_e32 v49, 1.0, v49
	v_rcp_f32_e32 v52, v49
	v_mul_f32_e32 v49, 0xbfb8aa3b, v55
	v_exp_f32_e32 v49, v49
	v_rcp_f32_e32 v51, v51
	v_lshlrev_b32_e32 v54, 16, v97
	v_and_b32_e32 v55, 0xffff0000, v97
	v_add_f32_e32 v49, 1.0, v49
	v_rcp_f32_e32 v53, v49
	s_nop 0
	v_pk_mul_f32 v[52:53], v[52:53], v[54:55]
	s_nop 0
	v_cvt_pk_bf16_f32 v49, v52, v53
	v_lshlrev_b32_e32 v52, 16, v98
	v_and_b32_e32 v53, 0xffff0000, v98
	v_pk_mul_f32 v[50:51], v[50:51], v[52:53]
	v_lshlrev_b32_e32 v54, 16, v99
	v_cvt_pk_bf16_f32 v50, v50, v51
	v_mul_f32_e32 v51, 0xbfb8aa3b, v56
	v_exp_f32_e32 v51, v51
	v_and_b32_e32 v55, 0xffff0000, v99
	v_add_f32_e32 v51, 1.0, v51
	v_rcp_f32_e32 v52, v51
	v_mul_f32_e32 v51, 0xbfb8aa3b, v57
	v_exp_f32_e32 v51, v51
	s_nop 0
	v_add_f32_e32 v51, 1.0, v51
	v_rcp_f32_e32 v53, v51
	s_nop 0
	v_pk_mul_f32 v[52:53], v[52:53], v[54:55]
	s_nop 0
	v_cvt_pk_bf16_f32 v51, v52, v53
	global_store_dwordx4 v[144:145], v[48:51], off offset:1792
	s_nop 1
	v_pk_add_f32 v[48:49], v[42:43], v[70:71]
	v_pk_add_f32 v[42:43], v[40:41], v[68:69]
	v_mul_f32_e32 v40, 0xbfb8aa3b, v44
	v_mul_f32_e32 v41, 0xbfb8aa3b, v45
	v_exp_f32_e32 v40, v40
	v_exp_f32_e32 v41, v41
	v_lshlrev_b32_e32 v44, 16, v92
	v_and_b32_e32 v45, 0xffff0000, v92
	v_add_f32_e32 v40, 1.0, v40
	v_add_f32_e32 v41, 1.0, v41
	v_rcp_f32_e32 v40, v40
	v_rcp_f32_e32 v41, v41
	v_mul_f32_e32 v42, 0xbfb8aa3b, v42
	v_mul_f32_e32 v43, 0xbfb8aa3b, v43
	v_exp_f32_e32 v42, v42
	v_pk_mul_f32 v[40:41], v[40:41], v[44:45]
	v_exp_f32_e32 v43, v43
	v_cvt_pk_bf16_f32 v40, v40, v41
	v_mul_f32_e32 v41, 0xbfb8aa3b, v46
	v_exp_f32_e32 v41, v41
	v_add_f32_e32 v42, 1.0, v42
	v_add_f32_e32 v43, 1.0, v43
	v_rcp_f32_e32 v42, v42
	v_add_f32_e32 v41, 1.0, v41
	v_rcp_f32_e32 v44, v41
	v_mul_f32_e32 v41, 0xbfb8aa3b, v47
	v_exp_f32_e32 v41, v41
	v_rcp_f32_e32 v43, v43
	v_lshlrev_b32_e32 v46, 16, v93
	v_and_b32_e32 v47, 0xffff0000, v93
	v_add_f32_e32 v41, 1.0, v41
	v_rcp_f32_e32 v45, v41
	s_nop 0
	v_pk_mul_f32 v[44:45], v[44:45], v[46:47]
	s_nop 0
	v_cvt_pk_bf16_f32 v41, v44, v45
	v_lshlrev_b32_e32 v44, 16, v94
	v_and_b32_e32 v45, 0xffff0000, v94
	v_pk_mul_f32 v[42:43], v[42:43], v[44:45]
	v_lshlrev_b32_e32 v46, 16, v95
	v_cvt_pk_bf16_f32 v42, v42, v43
	v_mul_f32_e32 v43, 0xbfb8aa3b, v48
	v_exp_f32_e32 v43, v43
	v_and_b32_e32 v47, 0xffff0000, v95
	v_add_f32_e32 v43, 1.0, v43
	v_rcp_f32_e32 v44, v43
	v_mul_f32_e32 v43, 0xbfb8aa3b, v49
	v_exp_f32_e32 v43, v43
	s_nop 0
	v_add_f32_e32 v43, 1.0, v43
	v_rcp_f32_e32 v45, v43
	s_nop 0
	v_pk_mul_f32 v[44:45], v[44:45], v[46:47]
	s_nop 0
	v_cvt_pk_bf16_f32 v43, v44, v45
	global_store_dwordx4 v[132:133], v[40:43], off offset:1792
	s_nop 1
	v_pk_add_f32 v[40:41], v[34:35], v[70:71]
	v_pk_add_f32 v[34:35], v[32:33], v[68:69]
	v_mul_f32_e32 v32, 0xbfb8aa3b, v36
	v_mul_f32_e32 v33, 0xbfb8aa3b, v37
	v_exp_f32_e32 v32, v32
	v_exp_f32_e32 v33, v33
	v_lshlrev_b32_e32 v36, 16, v88
	v_and_b32_e32 v37, 0xffff0000, v88
	v_add_f32_e32 v32, 1.0, v32
	v_add_f32_e32 v33, 1.0, v33
	v_rcp_f32_e32 v32, v32
	v_rcp_f32_e32 v33, v33
	v_mul_f32_e32 v34, 0xbfb8aa3b, v34
	v_mul_f32_e32 v35, 0xbfb8aa3b, v35
	v_exp_f32_e32 v34, v34
	v_pk_mul_f32 v[32:33], v[32:33], v[36:37]
	v_exp_f32_e32 v35, v35
	v_cvt_pk_bf16_f32 v32, v32, v33
	v_mul_f32_e32 v33, 0xbfb8aa3b, v38
	v_exp_f32_e32 v33, v33
	v_add_f32_e32 v34, 1.0, v34
	v_add_f32_e32 v35, 1.0, v35
	v_rcp_f32_e32 v34, v34
	v_add_f32_e32 v33, 1.0, v33
	v_rcp_f32_e32 v36, v33
	v_mul_f32_e32 v33, 0xbfb8aa3b, v39
	v_exp_f32_e32 v33, v33
	v_rcp_f32_e32 v35, v35
	v_lshlrev_b32_e32 v38, 16, v89
	v_and_b32_e32 v39, 0xffff0000, v89
	v_add_f32_e32 v33, 1.0, v33
	v_rcp_f32_e32 v37, v33
	s_nop 0
	v_pk_mul_f32 v[36:37], v[36:37], v[38:39]
	s_nop 0
	v_cvt_pk_bf16_f32 v33, v36, v37
	v_lshlrev_b32_e32 v36, 16, v90
	v_and_b32_e32 v37, 0xffff0000, v90
	v_pk_mul_f32 v[34:35], v[34:35], v[36:37]
	v_lshlrev_b32_e32 v38, 16, v91
	v_cvt_pk_bf16_f32 v34, v34, v35
	v_mul_f32_e32 v35, 0xbfb8aa3b, v40
	v_exp_f32_e32 v35, v35
	v_and_b32_e32 v39, 0xffff0000, v91
	v_add_f32_e32 v35, 1.0, v35
	v_rcp_f32_e32 v36, v35
	v_mul_f32_e32 v35, 0xbfb8aa3b, v41
	v_exp_f32_e32 v35, v35
	s_nop 0
	v_add_f32_e32 v35, 1.0, v35
	v_rcp_f32_e32 v37, v35
	s_nop 0
	v_pk_mul_f32 v[36:37], v[36:37], v[38:39]
	s_nop 0
	v_cvt_pk_bf16_f32 v35, v36, v37
	global_store_dwordx4 v[120:121], v[32:35], off offset:1792
	s_nop 1
	v_pk_add_f32 v[32:33], v[26:27], v[70:71]
	v_pk_add_f32 v[26:27], v[24:25], v[68:69]
	v_mul_f32_e32 v24, 0xbfb8aa3b, v28
	v_mul_f32_e32 v25, 0xbfb8aa3b, v29
	v_exp_f32_e32 v24, v24
	v_exp_f32_e32 v25, v25
	v_lshlrev_b32_e32 v28, 16, v84
	v_and_b32_e32 v29, 0xffff0000, v84
	v_add_f32_e32 v24, 1.0, v24
	v_add_f32_e32 v25, 1.0, v25
	v_rcp_f32_e32 v24, v24
	v_rcp_f32_e32 v25, v25
	v_mul_f32_e32 v26, 0xbfb8aa3b, v26
	v_mul_f32_e32 v27, 0xbfb8aa3b, v27
	v_exp_f32_e32 v26, v26
	v_pk_mul_f32 v[24:25], v[24:25], v[28:29]
	v_exp_f32_e32 v27, v27
	v_cvt_pk_bf16_f32 v24, v24, v25
	v_mul_f32_e32 v25, 0xbfb8aa3b, v30
	v_exp_f32_e32 v25, v25
	v_add_f32_e32 v26, 1.0, v26
	v_add_f32_e32 v27, 1.0, v27
	v_rcp_f32_e32 v26, v26
	v_add_f32_e32 v25, 1.0, v25
	v_rcp_f32_e32 v28, v25
	v_mul_f32_e32 v25, 0xbfb8aa3b, v31
	v_exp_f32_e32 v25, v25
	v_rcp_f32_e32 v27, v27
	v_lshlrev_b32_e32 v30, 16, v85
	v_and_b32_e32 v31, 0xffff0000, v85
	v_add_f32_e32 v25, 1.0, v25
	v_rcp_f32_e32 v29, v25
	s_nop 0
	v_pk_mul_f32 v[28:29], v[28:29], v[30:31]
	s_nop 0
	v_cvt_pk_bf16_f32 v25, v28, v29
	v_lshlrev_b32_e32 v28, 16, v86
	v_and_b32_e32 v29, 0xffff0000, v86
	v_pk_mul_f32 v[26:27], v[26:27], v[28:29]
	v_lshlrev_b32_e32 v30, 16, v87
	v_cvt_pk_bf16_f32 v26, v26, v27
	v_mul_f32_e32 v27, 0xbfb8aa3b, v32
	v_exp_f32_e32 v27, v27
	v_and_b32_e32 v31, 0xffff0000, v87
	v_add_f32_e32 v27, 1.0, v27
	v_rcp_f32_e32 v28, v27
	v_mul_f32_e32 v27, 0xbfb8aa3b, v33
	v_exp_f32_e32 v27, v27
	s_nop 0
	v_add_f32_e32 v27, 1.0, v27
	v_rcp_f32_e32 v29, v27
	s_nop 0
	v_pk_mul_f32 v[28:29], v[28:29], v[30:31]
	s_nop 0
	v_cvt_pk_bf16_f32 v27, v28, v29
	global_store_dwordx4 v[108:109], v[24:27], off offset:1792
	s_nop 1
	v_pk_add_f32 v[24:25], v[18:19], v[70:71]
	v_pk_add_f32 v[18:19], v[16:17], v[68:69]
	v_mul_f32_e32 v16, 0xbfb8aa3b, v20
	v_mul_f32_e32 v17, 0xbfb8aa3b, v21
	v_exp_f32_e32 v16, v16
	v_exp_f32_e32 v17, v17
	v_lshlrev_b32_e32 v20, 16, v80
	v_and_b32_e32 v21, 0xffff0000, v80
	v_add_f32_e32 v16, 1.0, v16
	v_add_f32_e32 v17, 1.0, v17
	v_rcp_f32_e32 v16, v16
	v_rcp_f32_e32 v17, v17
	v_mul_f32_e32 v18, 0xbfb8aa3b, v18
	v_mul_f32_e32 v19, 0xbfb8aa3b, v19
	v_exp_f32_e32 v18, v18
	v_pk_mul_f32 v[16:17], v[16:17], v[20:21]
	v_exp_f32_e32 v19, v19
	v_cvt_pk_bf16_f32 v16, v16, v17
	v_mul_f32_e32 v17, 0xbfb8aa3b, v22
	v_exp_f32_e32 v17, v17
	v_add_f32_e32 v18, 1.0, v18
	v_add_f32_e32 v19, 1.0, v19
	v_rcp_f32_e32 v18, v18
	v_add_f32_e32 v17, 1.0, v17
	v_rcp_f32_e32 v20, v17
	v_mul_f32_e32 v17, 0xbfb8aa3b, v23
	v_exp_f32_e32 v17, v17
	v_rcp_f32_e32 v19, v19
	v_lshlrev_b32_e32 v22, 16, v81
	v_and_b32_e32 v23, 0xffff0000, v81
	v_add_f32_e32 v17, 1.0, v17
	v_rcp_f32_e32 v21, v17
	s_nop 0
	v_pk_mul_f32 v[20:21], v[20:21], v[22:23]
	s_nop 0
	v_cvt_pk_bf16_f32 v17, v20, v21
	v_lshlrev_b32_e32 v20, 16, v82
	v_and_b32_e32 v21, 0xffff0000, v82
	v_pk_mul_f32 v[18:19], v[18:19], v[20:21]
	v_lshlrev_b32_e32 v22, 16, v83
	v_cvt_pk_bf16_f32 v18, v18, v19
	v_mul_f32_e32 v19, 0xbfb8aa3b, v24
	v_exp_f32_e32 v19, v19
	v_and_b32_e32 v23, 0xffff0000, v83
	v_add_f32_e32 v19, 1.0, v19
	v_rcp_f32_e32 v20, v19
	v_mul_f32_e32 v19, 0xbfb8aa3b, v25
	v_exp_f32_e32 v19, v19
	s_nop 0
	v_add_f32_e32 v19, 1.0, v19
	v_rcp_f32_e32 v21, v19
	s_nop 0
	v_pk_mul_f32 v[20:21], v[20:21], v[22:23]
	s_nop 0
	v_cvt_pk_bf16_f32 v19, v20, v21
	global_store_dwordx4 v[100:101], v[16:19], off offset:1792
	s_nop 1
	v_pk_add_f32 v[16:17], v[10:11], v[70:71]
	v_pk_add_f32 v[10:11], v[8:9], v[68:69]
	v_mul_f32_e32 v8, 0xbfb8aa3b, v12
	v_mul_f32_e32 v9, 0xbfb8aa3b, v13
	v_exp_f32_e32 v8, v8
	v_exp_f32_e32 v9, v9
	v_lshlrev_b32_e32 v12, 16, v76
	v_and_b32_e32 v13, 0xffff0000, v76
	v_add_f32_e32 v8, 1.0, v8
	v_add_f32_e32 v9, 1.0, v9
	v_rcp_f32_e32 v8, v8
	v_rcp_f32_e32 v9, v9
	v_mul_f32_e32 v10, 0xbfb8aa3b, v10
	v_mul_f32_e32 v11, 0xbfb8aa3b, v11
	v_exp_f32_e32 v10, v10
	v_pk_mul_f32 v[8:9], v[8:9], v[12:13]
	v_exp_f32_e32 v11, v11
	v_cvt_pk_bf16_f32 v8, v8, v9
	v_mul_f32_e32 v9, 0xbfb8aa3b, v14
	v_exp_f32_e32 v9, v9
	v_add_f32_e32 v10, 1.0, v10
	v_add_f32_e32 v11, 1.0, v11
	v_rcp_f32_e32 v10, v10
	v_add_f32_e32 v9, 1.0, v9
	v_rcp_f32_e32 v12, v9
	v_mul_f32_e32 v9, 0xbfb8aa3b, v15
	v_exp_f32_e32 v9, v9
	v_rcp_f32_e32 v11, v11
	v_lshlrev_b32_e32 v14, 16, v77
	v_and_b32_e32 v15, 0xffff0000, v77
	v_add_f32_e32 v9, 1.0, v9
	v_rcp_f32_e32 v13, v9
	s_nop 0
	v_pk_mul_f32 v[12:13], v[12:13], v[14:15]
	s_nop 0
	v_cvt_pk_bf16_f32 v9, v12, v13
	v_lshlrev_b32_e32 v12, 16, v78
	v_and_b32_e32 v13, 0xffff0000, v78
	v_pk_mul_f32 v[10:11], v[10:11], v[12:13]
	v_lshlrev_b32_e32 v14, 16, v79
	v_cvt_pk_bf16_f32 v10, v10, v11
	v_mul_f32_e32 v11, 0xbfb8aa3b, v16
	v_exp_f32_e32 v11, v11
	v_and_b32_e32 v15, 0xffff0000, v79
	v_add_f32_e32 v11, 1.0, v11
	v_rcp_f32_e32 v12, v11
	v_mul_f32_e32 v11, 0xbfb8aa3b, v17
	v_exp_f32_e32 v11, v11
	s_nop 0
	v_add_f32_e32 v11, 1.0, v11
	v_rcp_f32_e32 v13, v11
	s_nop 0
	v_pk_mul_f32 v[12:13], v[12:13], v[14:15]
	s_nop 0
	v_cvt_pk_bf16_f32 v11, v12, v13
	global_store_dwordx4 v[102:103], v[8:11], off offset:1792
	s_nop 1
	v_pk_add_f32 v[8:9], v[2:3], v[70:71]
	v_pk_add_f32 v[2:3], v[0:1], v[68:69]
	v_mul_f32_e32 v0, 0xbfb8aa3b, v4
	v_mul_f32_e32 v1, 0xbfb8aa3b, v5
	v_exp_f32_e32 v0, v0
	v_exp_f32_e32 v1, v1
	v_lshlrev_b32_e32 v4, 16, v64
	v_and_b32_e32 v5, 0xffff0000, v64
	v_add_f32_e32 v0, 1.0, v0
	v_add_f32_e32 v1, 1.0, v1
	v_rcp_f32_e32 v0, v0
	v_rcp_f32_e32 v1, v1
	v_mul_f32_e32 v2, 0xbfb8aa3b, v2
	v_mul_f32_e32 v3, 0xbfb8aa3b, v3
	v_exp_f32_e32 v2, v2
	v_pk_mul_f32 v[0:1], v[0:1], v[4:5]
	v_exp_f32_e32 v3, v3
	v_cvt_pk_bf16_f32 v0, v0, v1
	v_mul_f32_e32 v1, 0xbfb8aa3b, v6
	v_exp_f32_e32 v1, v1
	v_add_f32_e32 v2, 1.0, v2
	v_add_f32_e32 v3, 1.0, v3
	v_rcp_f32_e32 v2, v2
	v_add_f32_e32 v1, 1.0, v1
	v_rcp_f32_e32 v4, v1
	v_mul_f32_e32 v1, 0xbfb8aa3b, v7
	v_exp_f32_e32 v1, v1
	v_rcp_f32_e32 v3, v3
	v_lshlrev_b32_e32 v6, 16, v65
	v_and_b32_e32 v7, 0xffff0000, v65
	v_add_f32_e32 v1, 1.0, v1
	v_rcp_f32_e32 v5, v1
	s_nop 0
	v_pk_mul_f32 v[4:5], v[4:5], v[6:7]
	s_nop 0
	v_cvt_pk_bf16_f32 v1, v4, v5
	v_lshlrev_b32_e32 v4, 16, v66
	v_and_b32_e32 v5, 0xffff0000, v66
	v_pk_mul_f32 v[2:3], v[2:3], v[4:5]
	v_lshlrev_b32_e32 v6, 16, v67
	v_cvt_pk_bf16_f32 v2, v2, v3
	v_mul_f32_e32 v3, 0xbfb8aa3b, v8
	v_exp_f32_e32 v3, v3
	v_and_b32_e32 v7, 0xffff0000, v67
	v_add_f32_e32 v3, 1.0, v3
	v_rcp_f32_e32 v4, v3
	v_mul_f32_e32 v3, 0xbfb8aa3b, v9
	v_exp_f32_e32 v3, v3
	s_nop 0
	v_add_f32_e32 v3, 1.0, v3
	v_rcp_f32_e32 v5, v3
	s_nop 0
	v_pk_mul_f32 v[4:5], v[4:5], v[6:7]
	s_nop 0
	v_cvt_pk_bf16_f32 v3, v4, v5
	global_store_dwordx4 v[104:105], v[0:3], off offset:1792
	s_cbranch_vccz .LBB0_637

.LBB0_709:
	s_add_i32 s70, s49, 2
	s_add_u32 s36, s50, 0x80
	s_addc_u32 s37, s51, 0
	s_add_i32 s38, 0, 0x10000
	v_add_u32_e32 v146, s38, v152
	ds_read_b128 v[134:137], v146
	ds_read_b128 v[138:141], v146 offset:1024
	ds_read_b128 v[142:145], v146 offset:2048
	ds_read_b128 v[146:149], v146 offset:3072
	s_cmp_eq_u32 s66, s49
	s_cselect_b32 s53, s43, s37
	s_cselect_b32 s52, s42, s36
	s_cselect_b32 s55, s45, s35
	s_cselect_b32 s54, s44, s34
	v_lshl_add_u64 v[150:151], s[50:51], 0, v[130:131]
	s_add_i32 m0, s29, 0xc000
	ds_read_b128 v[154:157], v153
	ds_read_b128 v[158:161], v153 offset:1024
	ds_read_b128 v[162:165], v153 offset:2048
	ds_read_b128 v[172:175], v153 offset:3072
	ds_read_b128 v[176:179], v153 offset:4096
	ds_read_b128 v[180:183], v153 offset:5120
	ds_read_b128 v[184:187], v153 offset:6144
	ds_read_b128 v[188:191], v153 offset:7168
	global_load_lds_dwordx4 v[150:151], off
	v_lshl_add_u64 v[150:151], s[50:51], 0, v[132:133]
	s_add_i32 m0, s29, 0xe000
	s_nop 0
	global_load_lds_dwordx4 v[150:151], off
	s_waitcnt lgkmcnt(8)
	s_barrier
	s_waitcnt lgkmcnt(0)
	v_mfma_f32_16x16x32_bf16 v[124:127], v[134:137], v[154:157], v[124:127]
	v_mfma_f32_16x16x32_bf16 v[104:107], v[142:145], v[154:157], v[104:107]
	v_mfma_f32_16x16x32_bf16 v[120:123], v[134:137], v[162:165], v[120:123]
	v_mfma_f32_16x16x32_bf16 v[92:95], v[142:145], v[162:165], v[92:95]
	v_mfma_f32_16x16x32_bf16 v[116:119], v[134:137], v[176:179], v[116:119]
	v_mfma_f32_16x16x32_bf16 v[84:87], v[142:145], v[176:179], v[84:87]
	v_mfma_f32_16x16x32_bf16 v[112:115], v[134:137], v[184:187], v[112:115]
	v_mfma_f32_16x16x32_bf16 v[80:83], v[142:145], v[184:187], v[80:83]
	v_mfma_f32_16x16x32_bf16 v[124:127], v[138:141], v[158:161], v[124:127]
	v_mfma_f32_16x16x32_bf16 v[104:107], v[146:149], v[158:161], v[104:107]
	v_mfma_f32_16x16x32_bf16 v[120:123], v[138:141], v[172:175], v[120:123]
	v_mfma_f32_16x16x32_bf16 v[92:95], v[146:149], v[172:175], v[92:95]
	v_mfma_f32_16x16x32_bf16 v[116:119], v[138:141], v[180:183], v[116:119]
	v_mfma_f32_16x16x32_bf16 v[84:87], v[146:149], v[180:183], v[84:87]
	v_mfma_f32_16x16x32_bf16 v[112:115], v[138:141], v[188:191], v[112:115]
	v_mfma_f32_16x16x32_bf16 v[80:83], v[146:149], v[188:191], v[80:83]
	s_barrier
	s_add_i32 s39, 0, 0x14000
	v_add_u32_e32 v150, s39, v152
	s_add_i32 s36, s38, s28
	ds_read_b128 v[192:195], v150
	ds_read_b128 v[196:199], v150 offset:1024
	ds_read_b128 v[200:203], v150 offset:2048
	ds_read_b128 v[204:207], v150 offset:3072
	v_lshl_add_u64 v[150:151], s[54:55], 0, v[168:169]
	s_mov_b32 m0, s36
	v_lshl_add_u64 v[166:167], s[54:55], 0, v[128:129]
	global_load_lds_dwordx4 v[150:151], off
	s_add_i32 m0, s36, 0x2000
	s_nop 0
	global_load_lds_dwordx4 v[166:167], off
	s_barrier
	s_waitcnt lgkmcnt(0)
	v_mfma_f32_16x16x32_bf16 v[60:63], v[192:195], v[154:157], v[60:63]
	v_mfma_f32_16x16x32_bf16 v[48:51], v[200:203], v[154:157], v[48:51]
	v_mfma_f32_16x16x32_bf16 v[56:59], v[192:195], v[162:165], v[56:59]
	v_mfma_f32_16x16x32_bf16 v[40:43], v[200:203], v[162:165], v[40:43]
	v_mfma_f32_16x16x32_bf16 v[52:55], v[192:195], v[176:179], v[52:55]
	v_mfma_f32_16x16x32_bf16 v[36:39], v[200:203], v[176:179], v[36:39]
	v_mfma_f32_16x16x32_bf16 v[44:47], v[192:195], v[184:187], v[44:47]
	v_mfma_f32_16x16x32_bf16 v[28:31], v[200:203], v[184:187], v[28:31]
	v_mfma_f32_16x16x32_bf16 v[60:63], v[196:199], v[158:161], v[60:63]
	v_mfma_f32_16x16x32_bf16 v[48:51], v[204:207], v[158:161], v[48:51]
	v_mfma_f32_16x16x32_bf16 v[56:59], v[196:199], v[172:175], v[56:59]
	v_mfma_f32_16x16x32_bf16 v[40:43], v[204:207], v[172:175], v[40:43]
	v_mfma_f32_16x16x32_bf16 v[52:55], v[196:199], v[180:183], v[52:55]
	v_mfma_f32_16x16x32_bf16 v[36:39], v[204:207], v[180:183], v[36:39]
	v_mfma_f32_16x16x32_bf16 v[44:47], v[196:199], v[188:191], v[44:47]
	v_mfma_f32_16x16x32_bf16 v[28:31], v[204:207], v[188:191], v[28:31]
	s_mov_b32 m0, s29
	v_lshl_add_u64 v[208:209], s[52:53], 0, v[168:169]
	s_barrier
	ds_read_b128 v[154:157], v153 offset:16384
	ds_read_b128 v[158:161], v153 offset:17408
	ds_read_b128 v[162:165], v153 offset:18432
	ds_read_b128 v[172:175], v153 offset:19456
	ds_read_b128 v[176:179], v153 offset:20480
	ds_read_b128 v[180:183], v153 offset:21504
	ds_read_b128 v[184:187], v153 offset:22528
	ds_read_b128 v[188:191], v153 offset:23552
	global_load_lds_dwordx4 v[208:209], off
	v_lshl_add_u64 v[210:211], s[52:53], 0, v[128:129]
	s_mov_b32 m0, s30
	s_nop 0
	global_load_lds_dwordx4 v[210:211], off
	s_barrier
	s_waitcnt lgkmcnt(0)
	v_mfma_f32_16x16x32_bf16 v[108:111], v[134:137], v[154:157], v[108:111]
	v_mfma_f32_16x16x32_bf16 v[76:79], v[142:145], v[154:157], v[76:79]
	v_mfma_f32_16x16x32_bf16 v[100:103], v[134:137], v[162:165], v[100:103]
	v_mfma_f32_16x16x32_bf16 v[72:75], v[142:145], v[162:165], v[72:75]
	v_mfma_f32_16x16x32_bf16 v[96:99], v[134:137], v[176:179], v[96:99]
	v_mfma_f32_16x16x32_bf16 v[68:71], v[142:145], v[176:179], v[68:71]
	v_mfma_f32_16x16x32_bf16 v[88:91], v[134:137], v[184:187], v[88:91]
	v_mfma_f32_16x16x32_bf16 v[64:67], v[142:145], v[184:187], v[64:67]
	v_mfma_f32_16x16x32_bf16 v[108:111], v[138:141], v[158:161], v[108:111]
	v_mfma_f32_16x16x32_bf16 v[76:79], v[146:149], v[158:161], v[76:79]
	v_mfma_f32_16x16x32_bf16 v[100:103], v[138:141], v[172:175], v[100:103]
	v_mfma_f32_16x16x32_bf16 v[72:75], v[146:149], v[172:175], v[72:75]
	v_mfma_f32_16x16x32_bf16 v[96:99], v[138:141], v[180:183], v[96:99]
	v_mfma_f32_16x16x32_bf16 v[68:71], v[146:149], v[180:183], v[68:71]
	v_mfma_f32_16x16x32_bf16 v[88:91], v[138:141], v[188:191], v[88:91]
	v_mfma_f32_16x16x32_bf16 v[64:67], v[146:149], v[188:191], v[64:67]
	s_barrier
	s_add_u32 s36, s54, s10
	s_addc_u32 s37, s55, 0
	s_add_i32 s38, s39, s28
	v_lshl_add_u64 v[212:213], s[36:37], 0, v[168:169]
	s_mov_b32 m0, s38
	v_lshl_add_u64 v[214:215], s[36:37], 0, v[128:129]
	global_load_lds_dwordx4 v[212:213], off
	s_add_i32 m0, s38, 0x2000
	s_nop 0
	global_load_lds_dwordx4 v[214:215], off
	s_waitcnt vmcnt(6)
	s_barrier
	v_mfma_f32_16x16x32_bf16 v[32:35], v[192:195], v[154:157], v[32:35]
	v_mfma_f32_16x16x32_bf16 v[12:15], v[200:203], v[154:157], v[12:15]
	v_mfma_f32_16x16x32_bf16 v[24:27], v[192:195], v[162:165], v[24:27]
	v_mfma_f32_16x16x32_bf16 v[8:11], v[200:203], v[162:165], v[8:11]
	v_mfma_f32_16x16x32_bf16 v[20:23], v[192:195], v[176:179], v[20:23]
	v_mfma_f32_16x16x32_bf16 v[4:7], v[200:203], v[176:179], v[4:7]
	v_mfma_f32_16x16x32_bf16 v[16:19], v[192:195], v[184:187], v[16:19]
	v_mfma_f32_16x16x32_bf16 v[0:3], v[200:203], v[184:187], v[0:3]
	v_mfma_f32_16x16x32_bf16 v[32:35], v[196:199], v[158:161], v[32:35]
	v_mfma_f32_16x16x32_bf16 v[12:15], v[204:207], v[158:161], v[12:15]
	v_mfma_f32_16x16x32_bf16 v[24:27], v[196:199], v[172:175], v[24:27]
	v_mfma_f32_16x16x32_bf16 v[8:11], v[204:207], v[172:175], v[8:11]
	v_mfma_f32_16x16x32_bf16 v[20:23], v[196:199], v[180:183], v[20:23]
	v_mfma_f32_16x16x32_bf16 v[4:7], v[204:207], v[180:183], v[4:7]
	v_mfma_f32_16x16x32_bf16 v[16:19], v[196:199], v[188:191], v[16:19]
	v_mfma_f32_16x16x32_bf16 v[0:3], v[204:207], v[188:191], v[0:3]
	s_add_i32 s38, 0, 0x18000
	v_add_u32_e32 v146, s38, v152
	s_barrier
	ds_read_b128 v[134:137], v146
	ds_read_b128 v[138:141], v146 offset:1024
	ds_read_b128 v[142:145], v146 offset:2048
	ds_read_b128 v[146:149], v146 offset:3072
	s_add_u32 s36, s52, s10
	s_addc_u32 s37, s53, 0
	s_mov_b32 m0, s31
	v_lshl_add_u64 v[192:193], s[36:37], 0, v[168:169]
	ds_read_b128 v[154:157], v153 offset:32768
	ds_read_b128 v[158:161], v153 offset:33792
	ds_read_b128 v[162:165], v153 offset:34816
	ds_read_b128 v[172:175], v153 offset:35840
	ds_read_b128 v[176:179], v153 offset:36864
	ds_read_b128 v[180:183], v153 offset:37888
	ds_read_b128 v[184:187], v153 offset:38912
	ds_read_b128 v[188:191], v153 offset:39936
	global_load_lds_dwordx4 v[192:193], off
	v_lshl_add_u64 v[192:193], s[36:37], 0, v[128:129]
	s_mov_b32 m0, s56
	s_nop 0
	global_load_lds_dwordx4 v[192:193], off
	s_waitcnt lgkmcnt(8)
	s_barrier
	s_waitcnt lgkmcnt(0)
	v_mfma_f32_16x16x32_bf16 v[124:127], v[134:137], v[154:157], v[124:127]
	v_mfma_f32_16x16x32_bf16 v[104:107], v[142:145], v[154:157], v[104:107]
	v_mfma_f32_16x16x32_bf16 v[120:123], v[134:137], v[162:165], v[120:123]
	v_mfma_f32_16x16x32_bf16 v[92:95], v[142:145], v[162:165], v[92:95]
	v_mfma_f32_16x16x32_bf16 v[116:119], v[134:137], v[176:179], v[116:119]
	v_mfma_f32_16x16x32_bf16 v[84:87], v[142:145], v[176:179], v[84:87]
	v_mfma_f32_16x16x32_bf16 v[112:115], v[134:137], v[184:187], v[112:115]
	v_mfma_f32_16x16x32_bf16 v[80:83], v[142:145], v[184:187], v[80:83]
	v_mfma_f32_16x16x32_bf16 v[124:127], v[138:141], v[158:161], v[124:127]
	v_mfma_f32_16x16x32_bf16 v[104:107], v[146:149], v[158:161], v[104:107]
	v_mfma_f32_16x16x32_bf16 v[120:123], v[138:141], v[172:175], v[120:123]
	v_mfma_f32_16x16x32_bf16 v[92:95], v[146:149], v[172:175], v[92:95]
	v_mfma_f32_16x16x32_bf16 v[116:119], v[138:141], v[180:183], v[116:119]
	v_mfma_f32_16x16x32_bf16 v[84:87], v[146:149], v[180:183], v[84:87]
	v_mfma_f32_16x16x32_bf16 v[112:115], v[138:141], v[188:191], v[112:115]
	v_mfma_f32_16x16x32_bf16 v[80:83], v[146:149], v[188:191], v[80:83]
	s_barrier
	s_add_i32 s36, 0, 0x1c000
	s_add_i32 s37, s38, s28
	v_add_u32_e32 v204, s36, v152
	v_lshl_add_u64 v[150:151], v[150:151], 0, s[88:89]
	s_mov_b32 m0, s37
	ds_read_b128 v[192:195], v204
	ds_read_b128 v[196:199], v204 offset:1024
	ds_read_b128 v[200:203], v204 offset:2048
	ds_read_b128 v[204:207], v204 offset:3072
	global_load_lds_dwordx4 v[150:151], off
	v_lshl_add_u64 v[150:151], v[166:167], 0, s[88:89]
	s_add_i32 m0, s37, 0x2000
	s_nop 0
	global_load_lds_dwordx4 v[150:151], off
	s_barrier
	s_waitcnt lgkmcnt(0)
	v_mfma_f32_16x16x32_bf16 v[60:63], v[192:195], v[154:157], v[60:63]
	v_mfma_f32_16x16x32_bf16 v[48:51], v[200:203], v[154:157], v[48:51]
	v_mfma_f32_16x16x32_bf16 v[56:59], v[192:195], v[162:165], v[56:59]
	v_mfma_f32_16x16x32_bf16 v[40:43], v[200:203], v[162:165], v[40:43]
	v_mfma_f32_16x16x32_bf16 v[52:55], v[192:195], v[176:179], v[52:55]
	v_mfma_f32_16x16x32_bf16 v[36:39], v[200:203], v[176:179], v[36:39]
	v_mfma_f32_16x16x32_bf16 v[44:47], v[192:195], v[184:187], v[44:47]
	v_mfma_f32_16x16x32_bf16 v[28:31], v[200:203], v[184:187], v[28:31]
	v_mfma_f32_16x16x32_bf16 v[60:63], v[196:199], v[158:161], v[60:63]
	v_mfma_f32_16x16x32_bf16 v[48:51], v[204:207], v[158:161], v[48:51]
	v_mfma_f32_16x16x32_bf16 v[56:59], v[196:199], v[172:175], v[56:59]
	v_mfma_f32_16x16x32_bf16 v[40:43], v[204:207], v[172:175], v[40:43]
	v_mfma_f32_16x16x32_bf16 v[52:55], v[196:199], v[180:183], v[52:55]
	v_mfma_f32_16x16x32_bf16 v[36:39], v[204:207], v[180:183], v[36:39]
	v_mfma_f32_16x16x32_bf16 v[44:47], v[196:199], v[188:191], v[44:47]
	v_mfma_f32_16x16x32_bf16 v[28:31], v[204:207], v[188:191], v[28:31]
	s_mov_b32 m0, s61
	v_lshl_add_u64 v[150:151], v[208:209], 0, s[88:89]
	s_barrier
	ds_read_b128 v[154:157], v153 offset:49152
	ds_read_b128 v[158:161], v153 offset:50176
	ds_read_b128 v[162:165], v153 offset:51200
	ds_read_b128 v[172:175], v153 offset:52224
	ds_read_b128 v[176:179], v153 offset:53248
	ds_read_b128 v[180:183], v153 offset:54272
	ds_read_b128 v[184:187], v153 offset:55296
	ds_read_b128 v[188:191], v153 offset:56320
	global_load_lds_dwordx4 v[150:151], off
	v_lshl_add_u64 v[150:151], v[210:211], 0, s[88:89]
	s_mov_b32 m0, s62
	s_nop 0
	global_load_lds_dwordx4 v[150:151], off
	s_barrier
	s_waitcnt lgkmcnt(0)
	v_mfma_f32_16x16x32_bf16 v[108:111], v[134:137], v[154:157], v[108:111]
	v_mfma_f32_16x16x32_bf16 v[76:79], v[142:145], v[154:157], v[76:79]
	v_mfma_f32_16x16x32_bf16 v[100:103], v[134:137], v[162:165], v[100:103]
	v_mfma_f32_16x16x32_bf16 v[72:75], v[142:145], v[162:165], v[72:75]
	v_mfma_f32_16x16x32_bf16 v[96:99], v[134:137], v[176:179], v[96:99]
	v_mfma_f32_16x16x32_bf16 v[68:71], v[142:145], v[176:179], v[68:71]
	v_mfma_f32_16x16x32_bf16 v[88:91], v[134:137], v[184:187], v[88:91]
	v_mfma_f32_16x16x32_bf16 v[64:67], v[142:145], v[184:187], v[64:67]
	v_mfma_f32_16x16x32_bf16 v[108:111], v[138:141], v[158:161], v[108:111]
	v_mfma_f32_16x16x32_bf16 v[76:79], v[146:149], v[158:161], v[76:79]
	v_mfma_f32_16x16x32_bf16 v[100:103], v[138:141], v[172:175], v[100:103]
	v_mfma_f32_16x16x32_bf16 v[72:75], v[146:149], v[172:175], v[72:75]
	v_mfma_f32_16x16x32_bf16 v[96:99], v[138:141], v[180:183], v[96:99]
	v_mfma_f32_16x16x32_bf16 v[68:71], v[146:149], v[180:183], v[68:71]
	v_mfma_f32_16x16x32_bf16 v[88:91], v[138:141], v[188:191], v[88:91]
	v_mfma_f32_16x16x32_bf16 v[64:67], v[146:149], v[188:191], v[64:67]
	s_barrier
	s_add_i32 s36, s36, s28
	v_lshl_add_u64 v[134:135], v[212:213], 0, s[88:89]
	s_mov_b32 m0, s36
	s_nop 0
	global_load_lds_dwordx4 v[134:135], off
	v_lshl_add_u64 v[134:135], v[214:215], 0, s[88:89]
	s_add_i32 m0, s36, 0x2000
	s_nop 0
	global_load_lds_dwordx4 v[134:135], off
	s_waitcnt vmcnt(6)
	s_barrier
	v_mfma_f32_16x16x32_bf16 v[32:35], v[192:195], v[154:157], v[32:35]
	v_mfma_f32_16x16x32_bf16 v[12:15], v[200:203], v[154:157], v[12:15]
	v_mfma_f32_16x16x32_bf16 v[24:27], v[192:195], v[162:165], v[24:27]
	v_mfma_f32_16x16x32_bf16 v[8:11], v[200:203], v[162:165], v[8:11]
	v_mfma_f32_16x16x32_bf16 v[20:23], v[192:195], v[176:179], v[20:23]
	v_mfma_f32_16x16x32_bf16 v[4:7], v[200:203], v[176:179], v[4:7]
	v_mfma_f32_16x16x32_bf16 v[16:19], v[192:195], v[184:187], v[16:19]
	v_mfma_f32_16x16x32_bf16 v[0:3], v[200:203], v[184:187], v[0:3]
	v_mfma_f32_16x16x32_bf16 v[32:35], v[196:199], v[158:161], v[32:35]
	v_mfma_f32_16x16x32_bf16 v[12:15], v[204:207], v[158:161], v[12:15]
	v_mfma_f32_16x16x32_bf16 v[24:27], v[196:199], v[172:175], v[24:27]
	v_mfma_f32_16x16x32_bf16 v[8:11], v[204:207], v[172:175], v[8:11]
	v_mfma_f32_16x16x32_bf16 v[20:23], v[196:199], v[180:183], v[20:23]
	v_mfma_f32_16x16x32_bf16 v[4:7], v[204:207], v[180:183], v[4:7]
	v_mfma_f32_16x16x32_bf16 v[16:19], v[196:199], v[188:191], v[16:19]
	v_mfma_f32_16x16x32_bf16 v[0:3], v[204:207], v[188:191], v[0:3]
	s_add_u32 s50, s50, 0x100
	s_addc_u32 s51, s51, 0
	s_add_u32 s34, s34, 0x100
	s_addc_u32 s35, s35, 0
	s_cmp_ge_u32 s70, s63
	s_mov_b32 s49, s70
	s_barrier
	s_cbranch_scc0 .LBB0_709
	v_mov_b32_e32 v134, v171
	s_cmpk_gt_i32 s48, 0x7f
	s_mov_b64 s[52:53], -1
	s_cbranch_scc0 .LBB0_712
	s_add_i32 s84, s48, 0xffffff80
	s_lshl_b64 s[34:35], s[84:85], 20
	s_add_u32 s50, s57, s34
	s_addc_u32 s51, s58, s35
	s_mov_b64 s[52:53], 0

.LBB0_721:
	s_add_i32 s37, 0, 0x10000
	v_add_u32_e32 v216, s37, v6
	ds_read_b128 v[8:11], v216
	ds_read_b128 v[12:15], v216 offset:1024
	ds_read_b128 v[16:19], v216 offset:2048
	ds_read_b128 v[20:23], v216 offset:3072
	s_add_u32 s38, s50, s10
	s_addc_u32 s39, s51, 0
	v_lshl_add_u64 v[2:3], s[38:39], 0, v[168:169]
	s_add_i32 s36, s31, 0xc000
	v_lshl_add_u64 v[4:5], v[2:3], 0, s[88:89]
	s_mov_b32 m0, s36
	ds_read_b128 v[24:27], v7
	ds_read_b128 v[28:31], v7 offset:1024
	ds_read_b128 v[32:35], v7 offset:2048
	ds_read_b128 v[36:39], v7 offset:3072
	ds_read_b128 v[40:43], v7 offset:4096
	ds_read_b128 v[44:47], v7 offset:5120
	ds_read_b128 v[48:51], v7 offset:6144
	ds_read_b128 v[52:55], v7 offset:7168
	global_load_lds_dwordx4 v[4:5], off
	v_lshl_add_u64 v[4:5], s[38:39], 0, v[0:1]
	s_add_i32 s7, s31, 0xe000
	v_lshl_add_u64 v[56:57], v[4:5], 0, s[88:89]
	s_mov_b32 m0, s7
	s_nop 0
	global_load_lds_dwordx4 v[56:57], off
	s_waitcnt lgkmcnt(8)
	s_barrier
	s_waitcnt lgkmcnt(0)
	v_mfma_f32_16x16x32_bf16 v[56:59], v[8:11], v[24:27], 0
	v_mfma_f32_16x16x32_bf16 v[60:63], v[16:19], v[24:27], 0
	v_mfma_f32_16x16x32_bf16 v[64:67], v[8:11], v[32:35], 0
	v_mfma_f32_16x16x32_bf16 v[68:71], v[16:19], v[32:35], 0
	v_mfma_f32_16x16x32_bf16 v[72:75], v[8:11], v[40:43], 0
	v_mfma_f32_16x16x32_bf16 v[76:79], v[16:19], v[40:43], 0
	v_mfma_f32_16x16x32_bf16 v[80:83], v[8:11], v[48:51], 0
	v_mfma_f32_16x16x32_bf16 v[84:87], v[16:19], v[48:51], 0
	v_mfma_f32_16x16x32_bf16 v[56:59], v[12:15], v[28:31], v[56:59]
	v_mfma_f32_16x16x32_bf16 v[60:63], v[20:23], v[28:31], v[60:63]
	v_mfma_f32_16x16x32_bf16 v[64:67], v[12:15], v[36:39], v[64:67]
	v_mfma_f32_16x16x32_bf16 v[68:71], v[20:23], v[36:39], v[68:71]
	v_mfma_f32_16x16x32_bf16 v[72:75], v[12:15], v[44:47], v[72:75]
	v_mfma_f32_16x16x32_bf16 v[76:79], v[20:23], v[44:47], v[76:79]
	v_mfma_f32_16x16x32_bf16 v[80:83], v[12:15], v[52:55], v[80:83]
	v_mfma_f32_16x16x32_bf16 v[84:87], v[20:23], v[52:55], v[84:87]
	s_barrier
	s_add_i32 s47, 0, 0x14000
	v_lshl_add_u64 v[204:205], s[48:49], 0, v[168:169]
	s_add_i32 s37, s37, s30
	v_add_u32_e32 v217, s47, v6
	v_lshl_add_u64 v[104:105], v[204:205], 0, s[90:91]
	s_mov_b32 m0, s37
	v_lshl_add_u64 v[206:207], s[48:49], 0, v[0:1]
	s_add_i32 s13, s37, 0x2000
	ds_read_b128 v[88:91], v217
	ds_read_b128 v[92:95], v217 offset:1024
	ds_read_b128 v[96:99], v217 offset:2048
	ds_read_b128 v[100:103], v217 offset:3072
	global_load_lds_dwordx4 v[104:105], off
	v_lshl_add_u64 v[104:105], v[206:207], 0, s[90:91]
	s_mov_b32 m0, s13
	s_nop 0
	global_load_lds_dwordx4 v[104:105], off
	s_barrier
	s_waitcnt lgkmcnt(0)
	v_mfma_f32_16x16x32_bf16 v[104:107], v[88:91], v[24:27], 0
	v_mfma_f32_16x16x32_bf16 v[24:27], v[96:99], v[24:27], 0
	v_mfma_f32_16x16x32_bf16 v[104:107], v[92:95], v[28:31], v[104:107]
	v_mfma_f32_16x16x32_bf16 v[24:27], v[100:103], v[28:31], v[24:27]
	v_mfma_f32_16x16x32_bf16 v[28:31], v[88:91], v[32:35], 0
	v_mfma_f32_16x16x32_bf16 v[32:35], v[96:99], v[32:35], 0
	v_mfma_f32_16x16x32_bf16 v[28:31], v[92:95], v[36:39], v[28:31]
	v_mfma_f32_16x16x32_bf16 v[32:35], v[100:103], v[36:39], v[32:35]
	v_mfma_f32_16x16x32_bf16 v[36:39], v[88:91], v[40:43], 0
	v_mfma_f32_16x16x32_bf16 v[40:43], v[96:99], v[40:43], 0
	v_mfma_f32_16x16x32_bf16 v[36:39], v[92:95], v[44:47], v[36:39]
	v_mfma_f32_16x16x32_bf16 v[40:43], v[100:103], v[44:47], v[40:43]
	v_mfma_f32_16x16x32_bf16 v[44:47], v[88:91], v[48:51], 0
	v_mfma_f32_16x16x32_bf16 v[48:51], v[96:99], v[48:51], 0
	v_mfma_f32_16x16x32_bf16 v[44:47], v[92:95], v[52:55], v[44:47]
	v_mfma_f32_16x16x32_bf16 v[48:51], v[100:103], v[52:55], v[48:51]
	v_lshl_add_u64 v[208:209], s[50:51], 0, v[168:169]
	s_mov_b32 m0, s31
	v_lshl_add_u64 v[136:137], v[208:209], 0, s[90:91]
	v_lshl_add_u64 v[210:211], s[50:51], 0, v[0:1]
	s_barrier
	ds_read_b128 v[52:55], v7 offset:16384
	ds_read_b128 v[108:111], v7 offset:17408
	ds_read_b128 v[112:115], v7 offset:18432
	ds_read_b128 v[116:119], v7 offset:19456
	ds_read_b128 v[120:123], v7 offset:20480
	ds_read_b128 v[124:127], v7 offset:21504
	ds_read_b128 v[128:131], v7 offset:22528
	ds_read_b128 v[132:135], v7 offset:23552
	global_load_lds_dwordx4 v[136:137], off
	v_lshl_add_u64 v[136:137], v[210:211], 0, s[90:91]
	s_mov_b32 m0, s34
	s_nop 0
	global_load_lds_dwordx4 v[136:137], off
	s_barrier
	s_waitcnt lgkmcnt(0)
	v_mfma_f32_16x16x32_bf16 v[136:139], v[8:11], v[52:55], 0
	v_mfma_f32_16x16x32_bf16 v[144:147], v[8:11], v[112:115], 0
	v_mfma_f32_16x16x32_bf16 v[152:155], v[8:11], v[120:123], 0
	v_mfma_f32_16x16x32_bf16 v[8:11], v[8:11], v[128:131], 0
	v_mfma_f32_16x16x32_bf16 v[136:139], v[12:15], v[108:111], v[136:139]
	v_mfma_f32_16x16x32_bf16 v[140:143], v[16:19], v[52:55], 0
	v_mfma_f32_16x16x32_bf16 v[144:147], v[12:15], v[116:119], v[144:147]
	v_mfma_f32_16x16x32_bf16 v[148:151], v[16:19], v[112:115], 0
	v_mfma_f32_16x16x32_bf16 v[152:155], v[12:15], v[124:127], v[152:155]
	v_mfma_f32_16x16x32_bf16 v[156:159], v[16:19], v[120:123], 0
	v_mfma_f32_16x16x32_bf16 v[8:11], v[12:15], v[132:135], v[8:11]
	v_mfma_f32_16x16x32_bf16 v[12:15], v[16:19], v[128:131], 0
	v_mfma_f32_16x16x32_bf16 v[140:143], v[20:23], v[108:111], v[140:143]
	v_mfma_f32_16x16x32_bf16 v[148:151], v[20:23], v[116:119], v[148:151]
	v_mfma_f32_16x16x32_bf16 v[156:159], v[20:23], v[124:127], v[156:159]
	v_mfma_f32_16x16x32_bf16 v[12:15], v[20:23], v[132:135], v[12:15]
	s_barrier
	s_add_u32 s38, s48, s10
	s_addc_u32 s39, s49, 0
	v_lshl_add_u64 v[212:213], s[38:39], 0, v[168:169]
	s_add_i32 s51, s47, s30
	v_lshl_add_u64 v[16:17], v[212:213], 0, s[90:91]
	s_mov_b32 m0, s51
	v_lshl_add_u64 v[214:215], s[38:39], 0, v[0:1]
	s_add_i32 s47, s51, 0x2000
	global_load_lds_dwordx4 v[16:17], off
	v_lshl_add_u64 v[16:17], v[214:215], 0, s[90:91]
	s_mov_b32 m0, s47
	s_nop 0
	global_load_lds_dwordx4 v[16:17], off
	s_waitcnt vmcnt(6)
	s_barrier
	v_mfma_f32_16x16x32_bf16 v[16:19], v[88:91], v[52:55], 0
	v_mfma_f32_16x16x32_bf16 v[20:23], v[96:99], v[52:55], 0
	v_mfma_f32_16x16x32_bf16 v[16:19], v[92:95], v[108:111], v[16:19]
	v_mfma_f32_16x16x32_bf16 v[20:23], v[100:103], v[108:111], v[20:23]
	v_mfma_f32_16x16x32_bf16 v[52:55], v[88:91], v[112:115], 0
	v_mfma_f32_16x16x32_bf16 v[108:111], v[96:99], v[112:115], 0
	v_mfma_f32_16x16x32_bf16 v[112:115], v[88:91], v[120:123], 0
	v_mfma_f32_16x16x32_bf16 v[88:91], v[88:91], v[128:131], 0
	v_mfma_f32_16x16x32_bf16 v[52:55], v[92:95], v[116:119], v[52:55]
	v_mfma_f32_16x16x32_bf16 v[108:111], v[100:103], v[116:119], v[108:111]
	v_mfma_f32_16x16x32_bf16 v[112:115], v[92:95], v[124:127], v[112:115]
	v_mfma_f32_16x16x32_bf16 v[116:119], v[96:99], v[120:123], 0
	v_mfma_f32_16x16x32_bf16 v[88:91], v[92:95], v[132:135], v[88:91]
	v_mfma_f32_16x16x32_bf16 v[92:95], v[96:99], v[128:131], 0
	v_mfma_f32_16x16x32_bf16 v[116:119], v[100:103], v[124:127], v[116:119]
	v_mfma_f32_16x16x32_bf16 v[92:95], v[100:103], v[132:135], v[92:95]
	s_add_i32 s63, 0, 0x18000
	v_add_u32_e32 v218, s63, v6
	s_barrier
	ds_read_b128 v[96:99], v218
	ds_read_b128 v[100:103], v218 offset:1024
	ds_read_b128 v[120:123], v218 offset:2048
	ds_read_b128 v[124:127], v218 offset:3072
	s_mov_b32 m0, s35
	v_lshl_add_u64 v[188:189], v[2:3], 0, s[90:91]
	ds_read_b128 v[128:131], v7 offset:32768
	ds_read_b128 v[132:135], v7 offset:33792
	ds_read_b128 v[160:163], v7 offset:34816
	ds_read_b128 v[164:167], v7 offset:35840
	ds_read_b128 v[172:175], v7 offset:36864
	ds_read_b128 v[176:179], v7 offset:37888
	ds_read_b128 v[180:183], v7 offset:38912
	ds_read_b128 v[184:187], v7 offset:39936
	global_load_lds_dwordx4 v[188:189], off
	v_lshl_add_u64 v[188:189], v[4:5], 0, s[90:91]
	s_mov_b32 m0, s52
	s_nop 0
	global_load_lds_dwordx4 v[188:189], off
	s_waitcnt lgkmcnt(8)
	s_barrier
	s_waitcnt lgkmcnt(0)
	v_mfma_f32_16x16x32_bf16 v[56:59], v[96:99], v[128:131], v[56:59]
	v_mfma_f32_16x16x32_bf16 v[60:63], v[120:123], v[128:131], v[60:63]
	v_mfma_f32_16x16x32_bf16 v[64:67], v[96:99], v[160:163], v[64:67]
	v_mfma_f32_16x16x32_bf16 v[68:71], v[120:123], v[160:163], v[68:71]
	v_mfma_f32_16x16x32_bf16 v[72:75], v[96:99], v[172:175], v[72:75]
	v_mfma_f32_16x16x32_bf16 v[76:79], v[120:123], v[172:175], v[76:79]
	v_mfma_f32_16x16x32_bf16 v[80:83], v[96:99], v[180:183], v[80:83]
	v_mfma_f32_16x16x32_bf16 v[84:87], v[120:123], v[180:183], v[84:87]
	v_mfma_f32_16x16x32_bf16 v[56:59], v[100:103], v[132:135], v[56:59]
	v_mfma_f32_16x16x32_bf16 v[60:63], v[124:127], v[132:135], v[60:63]
	v_mfma_f32_16x16x32_bf16 v[64:67], v[100:103], v[164:167], v[64:67]
	v_mfma_f32_16x16x32_bf16 v[68:71], v[124:127], v[164:167], v[68:71]
	v_mfma_f32_16x16x32_bf16 v[72:75], v[100:103], v[176:179], v[72:75]
	v_mfma_f32_16x16x32_bf16 v[76:79], v[124:127], v[176:179], v[76:79]
	v_mfma_f32_16x16x32_bf16 v[80:83], v[100:103], v[184:187], v[80:83]
	v_mfma_f32_16x16x32_bf16 v[84:87], v[124:127], v[184:187], v[84:87]
	s_barrier
	s_add_i32 s50, 0, 0x1c000
	s_add_i32 s63, s63, s30
	v_add_u32_e32 v219, s50, v6
	v_lshl_add_u64 v[204:205], v[204:205], 0, s[94:95]
	s_mov_b32 m0, s63
	s_add_i32 s48, s63, 0x2000
	ds_read_b128 v[188:191], v219
	ds_read_b128 v[192:195], v219 offset:1024
	ds_read_b128 v[196:199], v219 offset:2048
	ds_read_b128 v[200:203], v219 offset:3072
	global_load_lds_dwordx4 v[204:205], off
	v_lshl_add_u64 v[204:205], v[206:207], 0, s[94:95]
	s_mov_b32 m0, s48
	s_nop 0
	global_load_lds_dwordx4 v[204:205], off
	s_barrier
	s_waitcnt lgkmcnt(0)
	v_mfma_f32_16x16x32_bf16 v[104:107], v[188:191], v[128:131], v[104:107]
	v_mfma_f32_16x16x32_bf16 v[24:27], v[196:199], v[128:131], v[24:27]
	v_mfma_f32_16x16x32_bf16 v[28:31], v[188:191], v[160:163], v[28:31]
	v_mfma_f32_16x16x32_bf16 v[32:35], v[196:199], v[160:163], v[32:35]
	v_mfma_f32_16x16x32_bf16 v[36:39], v[188:191], v[172:175], v[36:39]
	v_mfma_f32_16x16x32_bf16 v[40:43], v[196:199], v[172:175], v[40:43]
	v_mfma_f32_16x16x32_bf16 v[44:47], v[188:191], v[180:183], v[44:47]
	v_mfma_f32_16x16x32_bf16 v[48:51], v[196:199], v[180:183], v[48:51]
	v_mfma_f32_16x16x32_bf16 v[104:107], v[192:195], v[132:135], v[104:107]
	v_mfma_f32_16x16x32_bf16 v[24:27], v[200:203], v[132:135], v[24:27]
	v_mfma_f32_16x16x32_bf16 v[28:31], v[192:195], v[164:167], v[28:31]
	v_mfma_f32_16x16x32_bf16 v[32:35], v[200:203], v[164:167], v[32:35]
	v_mfma_f32_16x16x32_bf16 v[36:39], v[192:195], v[176:179], v[36:39]
	v_mfma_f32_16x16x32_bf16 v[40:43], v[200:203], v[176:179], v[40:43]
	v_mfma_f32_16x16x32_bf16 v[44:47], v[192:195], v[184:187], v[44:47]
	v_mfma_f32_16x16x32_bf16 v[48:51], v[200:203], v[184:187], v[48:51]
	s_mov_b32 m0, s58
	v_lshl_add_u64 v[204:205], v[208:209], 0, s[94:95]
	s_barrier
	ds_read_b128 v[128:131], v7 offset:49152
	ds_read_b128 v[132:135], v7 offset:50176
	ds_read_b128 v[160:163], v7 offset:51200
	ds_read_b128 v[164:167], v7 offset:52224
	ds_read_b128 v[172:175], v7 offset:53248
	ds_read_b128 v[176:179], v7 offset:54272
	ds_read_b128 v[180:183], v7 offset:55296
	ds_read_b128 v[184:187], v7 offset:56320
	global_load_lds_dwordx4 v[204:205], off
	v_lshl_add_u64 v[204:205], v[210:211], 0, s[94:95]
	s_mov_b32 m0, s59
	s_nop 0
	global_load_lds_dwordx4 v[204:205], off
	s_barrier
	s_waitcnt lgkmcnt(0)
	v_mfma_f32_16x16x32_bf16 v[136:139], v[96:99], v[128:131], v[136:139]
	v_mfma_f32_16x16x32_bf16 v[140:143], v[120:123], v[128:131], v[140:143]
	v_mfma_f32_16x16x32_bf16 v[144:147], v[96:99], v[160:163], v[144:147]
	v_mfma_f32_16x16x32_bf16 v[148:151], v[120:123], v[160:163], v[148:151]
	v_mfma_f32_16x16x32_bf16 v[152:155], v[96:99], v[172:175], v[152:155]
	v_mfma_f32_16x16x32_bf16 v[156:159], v[120:123], v[172:175], v[156:159]
	v_mfma_f32_16x16x32_bf16 v[8:11], v[96:99], v[180:183], v[8:11]
	v_mfma_f32_16x16x32_bf16 v[12:15], v[120:123], v[180:183], v[12:15]
	v_mfma_f32_16x16x32_bf16 v[136:139], v[100:103], v[132:135], v[136:139]
	v_mfma_f32_16x16x32_bf16 v[140:143], v[124:127], v[132:135], v[140:143]
	v_mfma_f32_16x16x32_bf16 v[144:147], v[100:103], v[164:167], v[144:147]
	v_mfma_f32_16x16x32_bf16 v[148:151], v[124:127], v[164:167], v[148:151]
	v_mfma_f32_16x16x32_bf16 v[152:155], v[100:103], v[176:179], v[152:155]
	v_mfma_f32_16x16x32_bf16 v[156:159], v[124:127], v[176:179], v[156:159]
	v_mfma_f32_16x16x32_bf16 v[8:11], v[100:103], v[184:187], v[8:11]
	v_mfma_f32_16x16x32_bf16 v[12:15], v[124:127], v[184:187], v[12:15]
	s_barrier
	s_add_i32 s50, s50, s30
	v_lshl_add_u64 v[96:97], v[212:213], 0, s[94:95]
	s_mov_b32 m0, s50
	s_add_i32 s49, s50, 0x2000
	global_load_lds_dwordx4 v[96:97], off
	v_lshl_add_u64 v[96:97], v[214:215], 0, s[94:95]
	s_mov_b32 m0, s49
	s_nop 0
	global_load_lds_dwordx4 v[96:97], off
	s_waitcnt vmcnt(6)
	s_barrier
	v_mfma_f32_16x16x32_bf16 v[16:19], v[188:191], v[128:131], v[16:19]
	v_mfma_f32_16x16x32_bf16 v[20:23], v[196:199], v[128:131], v[20:23]
	v_mfma_f32_16x16x32_bf16 v[52:55], v[188:191], v[160:163], v[52:55]
	v_mfma_f32_16x16x32_bf16 v[96:99], v[196:199], v[160:163], v[108:111]
	v_mfma_f32_16x16x32_bf16 v[100:103], v[188:191], v[172:175], v[112:115]
	v_mfma_f32_16x16x32_bf16 v[108:111], v[196:199], v[172:175], v[116:119]
	v_mfma_f32_16x16x32_bf16 v[88:91], v[188:191], v[180:183], v[88:91]
	v_mfma_f32_16x16x32_bf16 v[92:95], v[196:199], v[180:183], v[92:95]
	v_mfma_f32_16x16x32_bf16 v[16:19], v[192:195], v[132:135], v[16:19]
	v_mfma_f32_16x16x32_bf16 v[20:23], v[200:203], v[132:135], v[20:23]
	v_mfma_f32_16x16x32_bf16 v[52:55], v[192:195], v[164:167], v[52:55]
	v_mfma_f32_16x16x32_bf16 v[96:99], v[200:203], v[164:167], v[96:99]
	v_mfma_f32_16x16x32_bf16 v[100:103], v[192:195], v[176:179], v[100:103]
	v_mfma_f32_16x16x32_bf16 v[108:111], v[200:203], v[176:179], v[108:111]
	v_mfma_f32_16x16x32_bf16 v[88:91], v[192:195], v[184:187], v[88:91]
	v_mfma_f32_16x16x32_bf16 v[92:95], v[200:203], v[184:187], v[92:95]
	s_barrier
	ds_read_b128 v[112:115], v216
	ds_read_b128 v[116:119], v216 offset:1024
	ds_read_b128 v[120:123], v216 offset:2048
	ds_read_b128 v[124:127], v216 offset:3072
	s_mov_b32 m0, s36
	v_lshl_add_u64 v[2:3], v[2:3], 0, s[94:95]
	ds_read_b128 v[128:131], v7
	ds_read_b128 v[132:135], v7 offset:1024
	ds_read_b128 v[160:163], v7 offset:2048
	ds_read_b128 v[164:167], v7 offset:3072
	ds_read_b128 v[172:175], v7 offset:4096
	ds_read_b128 v[176:179], v7 offset:5120
	ds_read_b128 v[180:183], v7 offset:6144
	ds_read_b128 v[184:187], v7 offset:7168
	global_load_lds_dwordx4 v[2:3], off
	v_lshl_add_u64 v[2:3], v[4:5], 0, s[94:95]
	s_mov_b32 m0, s7
	s_nop 0
	global_load_lds_dwordx4 v[2:3], off
	s_waitcnt lgkmcnt(8)
	s_barrier
	s_waitcnt lgkmcnt(0)
	v_mfma_f32_16x16x32_bf16 v[2:5], v[112:115], v[128:131], v[56:59]
	v_mfma_f32_16x16x32_bf16 v[56:59], v[120:123], v[128:131], v[60:63]
	v_mfma_f32_16x16x32_bf16 v[60:63], v[112:115], v[160:163], v[64:67]
	v_mfma_f32_16x16x32_bf16 v[64:67], v[120:123], v[160:163], v[68:71]
	v_mfma_f32_16x16x32_bf16 v[68:71], v[112:115], v[172:175], v[72:75]
	v_mfma_f32_16x16x32_bf16 v[72:75], v[120:123], v[172:175], v[76:79]
	v_mfma_f32_16x16x32_bf16 v[76:79], v[112:115], v[180:183], v[80:83]
	v_mfma_f32_16x16x32_bf16 v[80:83], v[120:123], v[180:183], v[84:87]
	v_mfma_f32_16x16x32_bf16 v[2:5], v[116:119], v[132:135], v[2:5]
	v_mfma_f32_16x16x32_bf16 v[56:59], v[124:127], v[132:135], v[56:59]
	v_mfma_f32_16x16x32_bf16 v[60:63], v[116:119], v[164:167], v[60:63]
	v_mfma_f32_16x16x32_bf16 v[64:67], v[124:127], v[164:167], v[64:67]
	v_mfma_f32_16x16x32_bf16 v[68:71], v[116:119], v[176:179], v[68:71]
	v_mfma_f32_16x16x32_bf16 v[72:75], v[124:127], v[176:179], v[72:75]
	v_mfma_f32_16x16x32_bf16 v[76:79], v[116:119], v[184:187], v[76:79]
	v_mfma_f32_16x16x32_bf16 v[80:83], v[124:127], v[184:187], v[80:83]
	s_barrier
	s_mov_b32 m0, s37
	v_lshl_add_u64 v[200:201], s[44:45], 0, v[168:169]
	ds_read_b128 v[84:87], v217
	ds_read_b128 v[188:191], v217 offset:1024
	ds_read_b128 v[192:195], v217 offset:2048
	ds_read_b128 v[196:199], v217 offset:3072
	global_load_lds_dwordx4 v[200:201], off
	v_lshl_add_u64 v[202:203], s[44:45], 0, v[0:1]
	s_mov_b32 m0, s13
	s_nop 0
	global_load_lds_dwordx4 v[202:203], off
	s_barrier
	s_waitcnt lgkmcnt(0)
	v_mfma_f32_16x16x32_bf16 v[104:107], v[84:87], v[128:131], v[104:107]
	v_mfma_f32_16x16x32_bf16 v[24:27], v[192:195], v[128:131], v[24:27]
	v_mfma_f32_16x16x32_bf16 v[28:31], v[84:87], v[160:163], v[28:31]
	v_mfma_f32_16x16x32_bf16 v[32:35], v[192:195], v[160:163], v[32:35]
	v_mfma_f32_16x16x32_bf16 v[36:39], v[84:87], v[172:175], v[36:39]
	v_mfma_f32_16x16x32_bf16 v[40:43], v[192:195], v[172:175], v[40:43]
	v_mfma_f32_16x16x32_bf16 v[44:47], v[84:87], v[180:183], v[44:47]
	v_mfma_f32_16x16x32_bf16 v[48:51], v[192:195], v[180:183], v[48:51]
	v_mfma_f32_16x16x32_bf16 v[104:107], v[188:191], v[132:135], v[104:107]
	v_mfma_f32_16x16x32_bf16 v[24:27], v[196:199], v[132:135], v[24:27]
	v_mfma_f32_16x16x32_bf16 v[28:31], v[188:191], v[164:167], v[28:31]
	v_mfma_f32_16x16x32_bf16 v[32:35], v[196:199], v[164:167], v[32:35]
	v_mfma_f32_16x16x32_bf16 v[36:39], v[188:191], v[176:179], v[36:39]
	v_mfma_f32_16x16x32_bf16 v[40:43], v[196:199], v[176:179], v[40:43]
	v_mfma_f32_16x16x32_bf16 v[44:47], v[188:191], v[184:187], v[44:47]
	v_mfma_f32_16x16x32_bf16 v[48:51], v[196:199], v[184:187], v[48:51]
	s_mov_b32 m0, s31
	v_lshl_add_u64 v[204:205], s[42:43], 0, v[168:169]
	s_barrier
	ds_read_b128 v[128:131], v7 offset:16384
	ds_read_b128 v[132:135], v7 offset:17408
	ds_read_b128 v[160:163], v7 offset:18432
	ds_read_b128 v[164:167], v7 offset:19456
	ds_read_b128 v[172:175], v7 offset:20480
	ds_read_b128 v[176:179], v7 offset:21504
	ds_read_b128 v[180:183], v7 offset:22528
	ds_read_b128 v[184:187], v7 offset:23552
	global_load_lds_dwordx4 v[204:205], off
	v_lshl_add_u64 v[206:207], s[42:43], 0, v[0:1]
	s_mov_b32 m0, s34
	s_nop 0
	global_load_lds_dwordx4 v[206:207], off
	s_barrier
	s_waitcnt lgkmcnt(0)
	v_mfma_f32_16x16x32_bf16 v[136:139], v[112:115], v[128:131], v[136:139]
	v_mfma_f32_16x16x32_bf16 v[140:143], v[120:123], v[128:131], v[140:143]
	v_mfma_f32_16x16x32_bf16 v[144:147], v[112:115], v[160:163], v[144:147]
	v_mfma_f32_16x16x32_bf16 v[148:151], v[120:123], v[160:163], v[148:151]
	v_mfma_f32_16x16x32_bf16 v[152:155], v[112:115], v[172:175], v[152:155]
	v_mfma_f32_16x16x32_bf16 v[156:159], v[120:123], v[172:175], v[156:159]
	v_mfma_f32_16x16x32_bf16 v[8:11], v[112:115], v[180:183], v[8:11]
	v_mfma_f32_16x16x32_bf16 v[12:15], v[120:123], v[180:183], v[12:15]
	v_mfma_f32_16x16x32_bf16 v[136:139], v[116:119], v[132:135], v[136:139]
	v_mfma_f32_16x16x32_bf16 v[140:143], v[124:127], v[132:135], v[140:143]
	v_mfma_f32_16x16x32_bf16 v[144:147], v[116:119], v[164:167], v[144:147]
	v_mfma_f32_16x16x32_bf16 v[148:151], v[124:127], v[164:167], v[148:151]
	v_mfma_f32_16x16x32_bf16 v[152:155], v[116:119], v[176:179], v[152:155]
	v_mfma_f32_16x16x32_bf16 v[156:159], v[124:127], v[176:179], v[156:159]
	v_mfma_f32_16x16x32_bf16 v[8:11], v[116:119], v[184:187], v[8:11]
	v_mfma_f32_16x16x32_bf16 v[12:15], v[124:127], v[184:187], v[12:15]
	s_barrier
	s_add_u32 s36, s44, s10
	s_addc_u32 s37, s45, 0
	s_mov_b32 m0, s51
	v_lshl_add_u64 v[208:209], s[36:37], 0, v[168:169]
	global_load_lds_dwordx4 v[208:209], off
	v_lshl_add_u64 v[210:211], s[36:37], 0, v[0:1]
	s_mov_b32 m0, s47
	s_nop 0
	global_load_lds_dwordx4 v[210:211], off
	s_waitcnt vmcnt(6)
	s_barrier
	v_mfma_f32_16x16x32_bf16 v[16:19], v[84:87], v[128:131], v[16:19]
	v_mfma_f32_16x16x32_bf16 v[20:23], v[192:195], v[128:131], v[20:23]
	v_mfma_f32_16x16x32_bf16 v[52:55], v[84:87], v[160:163], v[52:55]
	v_mfma_f32_16x16x32_bf16 v[96:99], v[192:195], v[160:163], v[96:99]
	v_mfma_f32_16x16x32_bf16 v[100:103], v[84:87], v[172:175], v[100:103]
	v_mfma_f32_16x16x32_bf16 v[108:111], v[192:195], v[172:175], v[108:111]
	v_mfma_f32_16x16x32_bf16 v[84:87], v[84:87], v[180:183], v[88:91]
	v_mfma_f32_16x16x32_bf16 v[88:91], v[192:195], v[180:183], v[92:95]
	v_mfma_f32_16x16x32_bf16 v[16:19], v[188:191], v[132:135], v[16:19]
	v_mfma_f32_16x16x32_bf16 v[20:23], v[196:199], v[132:135], v[20:23]
	v_mfma_f32_16x16x32_bf16 v[52:55], v[188:191], v[164:167], v[52:55]
	v_mfma_f32_16x16x32_bf16 v[96:99], v[196:199], v[164:167], v[96:99]
	v_mfma_f32_16x16x32_bf16 v[100:103], v[188:191], v[176:179], v[100:103]
	v_mfma_f32_16x16x32_bf16 v[108:111], v[196:199], v[176:179], v[108:111]
	v_mfma_f32_16x16x32_bf16 v[84:87], v[188:191], v[184:187], v[84:87]
	v_mfma_f32_16x16x32_bf16 v[88:91], v[196:199], v[184:187], v[88:91]
	s_barrier
	ds_read_b128 v[92:95], v218
	ds_read_b128 v[112:115], v218 offset:1024
	ds_read_b128 v[116:119], v218 offset:2048
	ds_read_b128 v[120:123], v218 offset:3072
	s_add_u32 s36, s42, s10
	s_addc_u32 s37, s43, 0
	s_mov_b32 m0, s35
	v_lshl_add_u64 v[184:185], s[36:37], 0, v[168:169]
	ds_read_b128 v[124:127], v7 offset:32768
	ds_read_b128 v[128:131], v7 offset:33792
	ds_read_b128 v[132:135], v7 offset:34816
	ds_read_b128 v[160:163], v7 offset:35840
	ds_read_b128 v[164:167], v7 offset:36864
	ds_read_b128 v[172:175], v7 offset:37888
	ds_read_b128 v[176:179], v7 offset:38912
	ds_read_b128 v[180:183], v7 offset:39936
	global_load_lds_dwordx4 v[184:185], off
	v_lshl_add_u64 v[184:185], s[36:37], 0, v[0:1]
	s_mov_b32 m0, s52
	s_nop 0
	global_load_lds_dwordx4 v[184:185], off
	s_waitcnt lgkmcnt(8)
	s_barrier
	s_waitcnt lgkmcnt(0)
	v_mfma_f32_16x16x32_bf16 v[2:5], v[92:95], v[124:127], v[2:5]
	v_mfma_f32_16x16x32_bf16 v[56:59], v[116:119], v[124:127], v[56:59]
	v_mfma_f32_16x16x32_bf16 v[60:63], v[92:95], v[132:135], v[60:63]
	v_mfma_f32_16x16x32_bf16 v[64:67], v[116:119], v[132:135], v[64:67]
	v_mfma_f32_16x16x32_bf16 v[68:71], v[92:95], v[164:167], v[68:71]
	v_mfma_f32_16x16x32_bf16 v[72:75], v[116:119], v[164:167], v[72:75]
	v_mfma_f32_16x16x32_bf16 v[76:79], v[92:95], v[176:179], v[76:79]
	v_mfma_f32_16x16x32_bf16 v[80:83], v[116:119], v[176:179], v[80:83]
	v_mfma_f32_16x16x32_bf16 v[2:5], v[112:115], v[128:131], v[2:5]
	v_mfma_f32_16x16x32_bf16 v[56:59], v[120:123], v[128:131], v[56:59]
	v_mfma_f32_16x16x32_bf16 v[60:63], v[112:115], v[160:163], v[60:63]
	v_mfma_f32_16x16x32_bf16 v[64:67], v[120:123], v[160:163], v[64:67]
	v_mfma_f32_16x16x32_bf16 v[68:71], v[112:115], v[172:175], v[68:71]
	v_mfma_f32_16x16x32_bf16 v[72:75], v[120:123], v[172:175], v[72:75]
	v_mfma_f32_16x16x32_bf16 v[76:79], v[112:115], v[180:183], v[76:79]
	v_mfma_f32_16x16x32_bf16 v[80:83], v[120:123], v[180:183], v[80:83]
	s_barrier
	s_mov_b32 m0, s63
	v_lshl_add_u64 v[200:201], v[200:201], 0, s[88:89]
	ds_read_b128 v[184:187], v219
	ds_read_b128 v[188:191], v219 offset:1024
	ds_read_b128 v[192:195], v219 offset:2048
	ds_read_b128 v[196:199], v219 offset:3072
	global_load_lds_dwordx4 v[200:201], off
	v_lshl_add_u64 v[200:201], v[202:203], 0, s[88:89]
	s_mov_b32 m0, s48
	s_nop 0
	global_load_lds_dwordx4 v[200:201], off
	s_barrier
	s_waitcnt lgkmcnt(0)
	v_mfma_f32_16x16x32_bf16 v[104:107], v[184:187], v[124:127], v[104:107]
	v_mfma_f32_16x16x32_bf16 v[24:27], v[192:195], v[124:127], v[24:27]
	v_mfma_f32_16x16x32_bf16 v[28:31], v[184:187], v[132:135], v[28:31]
	v_mfma_f32_16x16x32_bf16 v[32:35], v[192:195], v[132:135], v[32:35]
	v_mfma_f32_16x16x32_bf16 v[36:39], v[184:187], v[164:167], v[36:39]
	v_mfma_f32_16x16x32_bf16 v[40:43], v[192:195], v[164:167], v[40:43]
	v_mfma_f32_16x16x32_bf16 v[44:47], v[184:187], v[176:179], v[44:47]
	v_mfma_f32_16x16x32_bf16 v[48:51], v[192:195], v[176:179], v[48:51]
	v_mfma_f32_16x16x32_bf16 v[104:107], v[188:191], v[128:131], v[104:107]
	v_mfma_f32_16x16x32_bf16 v[24:27], v[196:199], v[128:131], v[24:27]
	v_mfma_f32_16x16x32_bf16 v[28:31], v[188:191], v[160:163], v[28:31]
	v_mfma_f32_16x16x32_bf16 v[32:35], v[196:199], v[160:163], v[32:35]
	v_mfma_f32_16x16x32_bf16 v[36:39], v[188:191], v[172:175], v[36:39]
	v_mfma_f32_16x16x32_bf16 v[40:43], v[196:199], v[172:175], v[40:43]
	v_mfma_f32_16x16x32_bf16 v[44:47], v[188:191], v[180:183], v[44:47]
	v_mfma_f32_16x16x32_bf16 v[48:51], v[196:199], v[180:183], v[48:51]
	s_mov_b32 m0, s58
	v_lshl_add_u64 v[200:201], v[204:205], 0, s[88:89]
	s_barrier
	ds_read_b128 v[124:127], v7 offset:49152
	ds_read_b128 v[128:131], v7 offset:50176
	ds_read_b128 v[132:135], v7 offset:51200
	ds_read_b128 v[160:163], v7 offset:52224
	ds_read_b128 v[164:167], v7 offset:53248
	ds_read_b128 v[172:175], v7 offset:54272
	ds_read_b128 v[176:179], v7 offset:55296
	ds_read_b128 v[180:183], v7 offset:56320
	global_load_lds_dwordx4 v[200:201], off
	v_lshl_add_u64 v[200:201], v[206:207], 0, s[88:89]
	s_mov_b32 m0, s59
	s_nop 0
	global_load_lds_dwordx4 v[200:201], off
	s_barrier
	s_waitcnt lgkmcnt(0)
	v_mfma_f32_16x16x32_bf16 v[136:139], v[92:95], v[124:127], v[136:139]
	v_mfma_f32_16x16x32_bf16 v[140:143], v[116:119], v[124:127], v[140:143]
	v_mfma_f32_16x16x32_bf16 v[144:147], v[92:95], v[132:135], v[144:147]
	v_mfma_f32_16x16x32_bf16 v[148:151], v[116:119], v[132:135], v[148:151]
	v_mfma_f32_16x16x32_bf16 v[152:155], v[92:95], v[164:167], v[152:155]
	v_mfma_f32_16x16x32_bf16 v[156:159], v[116:119], v[164:167], v[156:159]
	v_mfma_f32_16x16x32_bf16 v[8:11], v[92:95], v[176:179], v[8:11]
	v_mfma_f32_16x16x32_bf16 v[12:15], v[116:119], v[176:179], v[12:15]
	v_mfma_f32_16x16x32_bf16 v[136:139], v[112:115], v[128:131], v[136:139]
	v_mfma_f32_16x16x32_bf16 v[140:143], v[120:123], v[128:131], v[140:143]
	v_mfma_f32_16x16x32_bf16 v[144:147], v[112:115], v[160:163], v[144:147]
	v_mfma_f32_16x16x32_bf16 v[148:151], v[120:123], v[160:163], v[148:151]
	v_mfma_f32_16x16x32_bf16 v[152:155], v[112:115], v[172:175], v[152:155]
	v_mfma_f32_16x16x32_bf16 v[156:159], v[120:123], v[172:175], v[156:159]
	v_mfma_f32_16x16x32_bf16 v[8:11], v[112:115], v[180:183], v[8:11]
	v_mfma_f32_16x16x32_bf16 v[12:15], v[120:123], v[180:183], v[12:15]
	s_barrier
	s_mov_b32 m0, s50
	v_lshl_add_u64 v[92:93], v[208:209], 0, s[88:89]
	global_load_lds_dwordx4 v[92:93], off
	v_lshl_add_u64 v[92:93], v[210:211], 0, s[88:89]
	s_mov_b32 m0, s49
	s_nop 0
	global_load_lds_dwordx4 v[92:93], off
	s_waitcnt vmcnt(6)
	s_barrier
	v_mfma_f32_16x16x32_bf16 v[16:19], v[184:187], v[124:127], v[16:19]
	v_mfma_f32_16x16x32_bf16 v[20:23], v[192:195], v[124:127], v[20:23]
	v_mfma_f32_16x16x32_bf16 v[52:55], v[184:187], v[132:135], v[52:55]
	v_mfma_f32_16x16x32_bf16 v[92:95], v[192:195], v[132:135], v[96:99]
	v_mfma_f32_16x16x32_bf16 v[96:99], v[184:187], v[164:167], v[100:103]
	v_mfma_f32_16x16x32_bf16 v[100:103], v[192:195], v[164:167], v[108:111]
	v_mfma_f32_16x16x32_bf16 v[84:87], v[184:187], v[176:179], v[84:87]
	v_mfma_f32_16x16x32_bf16 v[88:91], v[192:195], v[176:179], v[88:91]
	v_mfma_f32_16x16x32_bf16 v[16:19], v[188:191], v[128:131], v[16:19]
	v_mfma_f32_16x16x32_bf16 v[20:23], v[196:199], v[128:131], v[20:23]
	v_mfma_f32_16x16x32_bf16 v[52:55], v[188:191], v[160:163], v[52:55]
	v_mfma_f32_16x16x32_bf16 v[92:95], v[196:199], v[160:163], v[92:95]
	v_mfma_f32_16x16x32_bf16 v[96:99], v[188:191], v[172:175], v[96:99]
	v_mfma_f32_16x16x32_bf16 v[100:103], v[196:199], v[172:175], v[100:103]
	v_mfma_f32_16x16x32_bf16 v[84:87], v[188:191], v[180:183], v[84:87]
	v_mfma_f32_16x16x32_bf16 v[88:91], v[196:199], v[180:183], v[88:91]
	s_ashr_i32 s7, s6, 31
	s_ashr_i32 s13, s12, 31
	s_lshl_b64 s[6:7], s[6:7], 22
	s_add_u32 s36, s53, s6
	s_addc_u32 s37, s54, s7
	s_lshl_b64 s[6:7], s[12:13], 20
	v_mov_b32_e32 v109, v171
	s_add_u32 s6, s36, s6
	s_barrier
	s_addc_u32 s7, s37, s7
	s_lshl_b32 s12, s57, 8
	v_lshrrev_b32_e32 v108, 2, v109
	v_and_or_b32 v108, v108, 12, s12
	v_or_b32_e32 v108, s56, v108
	v_and_or_b32 v110, v109, 15, s55
	v_ashrrev_i32_e32 v109, 31, v108
	v_ashrrev_i32_e32 v111, 31, v110
	v_lshl_add_u64 v[108:109], v[108:109], 2, s[6:7]
	v_lshlrev_b64 v[112:113], 12, v[110:111]
	v_lshl_add_u64 v[112:113], v[108:109], 0, v[112:113]
	global_store_dwordx4 v[112:113], v[2:5], off
	global_store_dwordx4 v[112:113], v[56:59], off offset:64
	global_store_dwordx4 v[112:113], v[104:107], off offset:512
	global_store_dwordx4 v[112:113], v[24:27], off offset:576
	v_or_b32_e32 v2, 16, v110
	v_ashrrev_i32_e32 v3, 31, v2
	v_lshlrev_b64 v[2:3], 12, v[2:3]
	v_lshl_add_u64 v[2:3], v[108:109], 0, v[2:3]
	global_store_dwordx4 v[2:3], v[60:63], off
	global_store_dwordx4 v[2:3], v[64:67], off offset:64
	global_store_dwordx4 v[2:3], v[28:31], off offset:512
	global_store_dwordx4 v[2:3], v[32:35], off offset:576
	v_or_b32_e32 v2, 32, v110
	v_ashrrev_i32_e32 v3, 31, v2
	v_lshlrev_b64 v[2:3], 12, v[2:3]
	v_lshl_add_u64 v[2:3], v[108:109], 0, v[2:3]
	global_store_dwordx4 v[2:3], v[68:71], off
	global_store_dwordx4 v[2:3], v[72:75], off offset:64
	global_store_dwordx4 v[2:3], v[36:39], off offset:512
	global_store_dwordx4 v[2:3], v[40:43], off offset:576
	v_or_b32_e32 v2, 48, v110
	v_ashrrev_i32_e32 v3, 31, v2
	v_lshlrev_b64 v[2:3], 12, v[2:3]
	v_lshl_add_u64 v[2:3], v[108:109], 0, v[2:3]
	s_mov_b64 s[6:7], 0x80000
	global_store_dwordx4 v[2:3], v[76:79], off
	global_store_dwordx4 v[2:3], v[80:83], off offset:64
	global_store_dwordx4 v[2:3], v[44:47], off offset:512
	global_store_dwordx4 v[2:3], v[48:51], off offset:576
	v_lshl_add_u64 v[2:3], v[112:113], 0, s[6:7]
	s_mov_b32 s6, 0x80000
	v_add_co_u32_e32 v4, vcc, s6, v112
	s_mov_b64 s[6:7], 0x90000
	s_nop 0
	v_addc_co_u32_e32 v5, vcc, 0, v113, vcc
	global_store_dwordx4 v[4:5], v[136:139], off
	global_store_dwordx4 v[2:3], v[140:143], off offset:64
	global_store_dwordx4 v[2:3], v[16:19], off offset:512
	global_store_dwordx4 v[2:3], v[20:23], off offset:576
	v_lshl_add_u64 v[2:3], v[112:113], 0, s[6:7]
	s_mov_b32 s6, 0x90000
	v_add_co_u32_e32 v4, vcc, s6, v112
	s_mov_b64 s[6:7], 0xa0000
	s_nop 0
	v_addc_co_u32_e32 v5, vcc, 0, v113, vcc
	global_store_dwordx4 v[4:5], v[144:147], off
	global_store_dwordx4 v[2:3], v[148:151], off offset:64
	global_store_dwordx4 v[2:3], v[52:55], off offset:512
	global_store_dwordx4 v[2:3], v[92:95], off offset:576
	v_lshl_add_u64 v[2:3], v[112:113], 0, s[6:7]
	s_mov_b32 s6, 0xa0000
	v_add_co_u32_e32 v4, vcc, s6, v112
	s_mov_b64 s[6:7], 0xb0000
	s_nop 0
	v_addc_co_u32_e32 v5, vcc, 0, v113, vcc
	global_store_dwordx4 v[4:5], v[152:155], off
	global_store_dwordx4 v[2:3], v[156:159], off offset:64
	global_store_dwordx4 v[2:3], v[96:99], off offset:512
	global_store_dwordx4 v[2:3], v[100:103], off offset:576
	v_add_co_u32_e32 v4, vcc, 0xb0000, v112
	v_lshl_add_u64 v[2:3], v[112:113], 0, s[6:7]
	s_nop 0
	v_addc_co_u32_e32 v5, vcc, 0, v113, vcc
	global_store_dwordx4 v[4:5], v[8:11], off
	global_store_dwordx4 v[2:3], v[12:15], off offset:64
	global_store_dwordx4 v[2:3], v[84:87], off offset:512
	global_store_dwordx4 v[2:3], v[88:91], off offset:576
	s_add_i32 s60, s60, s96
	s_andn2_b64 vcc, exec, s[40:41]
	s_mov_b32 s6, s46
	s_mov_b32 s57, s62
	s_mov_b32 s12, s61
	s_mov_b64 s[48:49], s[44:45]
	s_mov_b64 s[50:51], s[42:43]
	s_cbranch_vccz .LBB0_728
